# GEMM K-loop counter and pointer bumps moved ahead of the last compute segment (only the barrier remains between the last MFMA and the back edge)
# baseline (speedup 1.0000x reference)
; #define PG8_STAGE(bufoff, gbase, voff) do { _Pragma("unroll") for (int _i = 0; _i < 2; ++_i) \
;     __builtin_amdgcn_global_load_lds((const unsigned*)((const char*)(gbase) + (voff)[_i]), (PG8_LAS unsigned*)(lds + (bufoff) + ldsw + _i * 8192), 16, 0, 0); } while (0)
; #define PG8_LDA(dst, b, h) do { _Pragma("unroll") for (int m = 0; m < 4; ++m) _Pragma("unroll") for (int k = 0; k < 2; ++k) dst[m][k] = *(const PG8_LAS bf16x8*)(lds + PG8_SA(b, h) + aoff + m * 2048 + k * 1024); } while (0)
; #define PG8_LDB(dst, b, h) do { _Pragma("unroll") for (int n = 0; n < 2; ++n) _Pragma("unroll") for (int k = 0; k < 2; ++k) dst[n][k] = *(const PG8_LAS bf16x8*)(lds + PG8_SB(b, h) + boff + n * 2048 + k * 1024); } while (0)
; #define PG8_MMA(ai, bj, At, Bt) do { __builtin_amdgcn_s_setprio(1); _Pragma("unroll") for (int m = 0; m < 4; ++m) _Pragma("unroll") for (int n = 0; n < 2; ++n) _Pragma("unroll") for (int k = 0; k < 2; ++k) \
;     acc[ai][bj][m][n] = __builtin_amdgcn_mfma_f32_16x16x32_bf16(Bt[n][k], At[m][k], acc[ai][bj][m][n], 0, 0, 0); __builtin_amdgcn_s_setprio(0); } while (0)
; #define PG8_WAIT_L(n) asm volatile("s_waitcnt lgkmcnt(" #n ")" ::: "memory")
; #define PG8_BAR __builtin_amdgcn_s_barrier()
; #define PG8_SCHED __builtin_amdgcn_sched_barrier(0)
; template <class Epi, class Sched>
; __device__ __forceinline__ void gemm_phase(PG8_LAS unsigned char* lds, const int lda, const int ldb, const Sched& S, const Epi& E) {
;     ...
;       PG8_LDB(B0, 0, 0); PG8_SCHED; PG8_LDA(At, 0, 0); PG8_STAGE(PG8_SA(1, 1), a1 + hstepA, voffA);
;       PG8_WAIT_L(8); PG8_BAR; PG8_WAIT_L(0); PG8_MMA(0, 0, At, B0); PG8_BAR; PG8_SCHED;
;       PG8_LDB(B1, 0, 1); PG8_STAGE(PG8_SB(0, 0), b2, voffB);
;       PG8_BAR; PG8_WAIT_L(0); PG8_MMA(0, 1, At, B1); PG8_BAR;
;       PG8_LDA(At, 0, 1); PG8_STAGE(PG8_SA(0, 0), a2, voffA);
;       PG8_BAR; PG8_WAIT_L(0); PG8_MMA(1, 0, At, B0); PG8_BAR; PG8_SCHED;
.LBB0_335:
	s_add_u32 s10, s8, 0xfffc0080
	s_addc_u32 s11, s9, -1
	s_add_i32 s31, 0, 0x10000
	v_add_u32_e32 v156, s31, v131
	ds_read_b128 v[144:147], v156
	ds_read_b128 v[148:151], v156 offset:1024
	ds_read_b128 v[152:155], v156 offset:2048
	ds_read_b128 v[200:203], v156 offset:3072
	s_cmp_eq_u32 s30, 12
	s_cselect_b32 s25, s17, s11
	s_cselect_b32 s24, s26, s10
	s_cselect_b32 s11, s15, s29
	s_cselect_b32 s10, s27, s28
	v_lshl_add_u64 v[156:157], s[8:9], 0, v[140:141]
	s_add_i32 m0, s40, 0xc000
	ds_read_b128 v[204:207], v172
	ds_read_b128 v[208:211], v172 offset:1024
	ds_read_b128 v[212:215], v172 offset:2048
	ds_read_b128 v[216:219], v172 offset:3072
	ds_read_b128 v[220:223], v172 offset:4096
	ds_read_b128 v[224:227], v172 offset:5120
	ds_read_b128 v[228:231], v172 offset:6144
	ds_read_b128 v[232:235], v172 offset:7168
	global_load_lds_dwordx4 v[156:157], off
	v_lshl_add_u64 v[156:157], s[8:9], 0, v[142:143]
	s_add_i32 m0, s40, 0xe000
	s_nop 0
	global_load_lds_dwordx4 v[156:157], off
	s_waitcnt lgkmcnt(8)
	s_barrier
	s_waitcnt lgkmcnt(0)
	v_mfma_f32_16x16x32_bf16 v[126:129], v[144:147], v[204:207], v[126:129]
	v_mfma_f32_16x16x32_bf16 v[122:125], v[152:155], v[204:207], v[122:125]
	v_mfma_f32_16x16x32_bf16 v[110:113], v[144:147], v[212:215], v[110:113]
	v_mfma_f32_16x16x32_bf16 v[106:109], v[152:155], v[212:215], v[106:109]
	v_mfma_f32_16x16x32_bf16 v[94:97], v[144:147], v[220:223], v[94:97]
	v_mfma_f32_16x16x32_bf16 v[90:93], v[152:155], v[220:223], v[90:93]
	v_mfma_f32_16x16x32_bf16 v[78:81], v[144:147], v[228:231], v[78:81]
	v_mfma_f32_16x16x32_bf16 v[74:77], v[152:155], v[228:231], v[74:77]
	v_mfma_f32_16x16x32_bf16 v[126:129], v[148:151], v[208:211], v[126:129]
	v_mfma_f32_16x16x32_bf16 v[122:125], v[200:203], v[208:211], v[122:125]
	v_mfma_f32_16x16x32_bf16 v[110:113], v[148:151], v[216:219], v[110:113]
	v_mfma_f32_16x16x32_bf16 v[106:109], v[200:203], v[216:219], v[106:109]
	v_mfma_f32_16x16x32_bf16 v[94:97], v[148:151], v[224:227], v[94:97]
	v_mfma_f32_16x16x32_bf16 v[90:93], v[200:203], v[224:227], v[90:93]
	v_mfma_f32_16x16x32_bf16 v[78:81], v[148:151], v[232:235], v[78:81]
	v_mfma_f32_16x16x32_bf16 v[74:77], v[200:203], v[232:235], v[74:77]
	s_barrier
	s_add_i32 s33, 0, 0x14000
	v_add_u32_e32 v156, s33, v131
	s_add_i32 s31, s31, s39
	ds_read_b128 v[236:239], v156
	ds_read_b128 v[240:243], v156 offset:1024
	ds_read_b128 v[244:247], v156 offset:2048
	ds_read_b128 v[248:251], v156 offset:3072
	v_lshl_add_u64 v[156:157], s[10:11], 0, v[134:135]
	s_mov_b32 m0, s31
	v_lshl_add_u64 v[174:175], s[10:11], 0, v[132:133]
	global_load_lds_dwordx4 v[156:157], off
	s_add_i32 m0, s31, 0x2000
	s_nop 0
	global_load_lds_dwordx4 v[174:175], off
	s_barrier
	s_waitcnt lgkmcnt(0)
	v_mfma_f32_16x16x32_bf16 v[118:121], v[236:239], v[204:207], v[118:121]
	v_mfma_f32_16x16x32_bf16 v[114:117], v[244:247], v[204:207], v[114:117]
	v_mfma_f32_16x16x32_bf16 v[102:105], v[236:239], v[212:215], v[102:105]
	v_mfma_f32_16x16x32_bf16 v[98:101], v[244:247], v[212:215], v[98:101]
	v_mfma_f32_16x16x32_bf16 v[86:89], v[236:239], v[220:223], v[86:89]
	v_mfma_f32_16x16x32_bf16 v[82:85], v[244:247], v[220:223], v[82:85]
	v_mfma_f32_16x16x32_bf16 v[70:73], v[236:239], v[228:231], v[70:73]
	v_mfma_f32_16x16x32_bf16 v[66:69], v[244:247], v[228:231], v[66:69]
	v_mfma_f32_16x16x32_bf16 v[118:121], v[240:243], v[208:211], v[118:121]
	v_mfma_f32_16x16x32_bf16 v[114:117], v[248:251], v[208:211], v[114:117]
	v_mfma_f32_16x16x32_bf16 v[102:105], v[240:243], v[216:219], v[102:105]
	v_mfma_f32_16x16x32_bf16 v[98:101], v[248:251], v[216:219], v[98:101]
	v_mfma_f32_16x16x32_bf16 v[86:89], v[240:243], v[224:227], v[86:89]
	v_mfma_f32_16x16x32_bf16 v[82:85], v[248:251], v[224:227], v[82:85]
	v_mfma_f32_16x16x32_bf16 v[70:73], v[240:243], v[232:235], v[70:73]
	v_mfma_f32_16x16x32_bf16 v[66:69], v[248:251], v[232:235], v[66:69]
	s_barrier
	s_mov_b32 m0, s40
	v_lshl_add_u64 v[182:183], s[24:25], 0, v[134:135]
	ds_read_b128 v[204:207], v172 offset:16384
	ds_read_b128 v[208:211], v172 offset:17408
	ds_read_b128 v[212:215], v172 offset:18432
	ds_read_b128 v[216:219], v172 offset:19456
	ds_read_b128 v[220:223], v172 offset:20480
	ds_read_b128 v[224:227], v172 offset:21504
	ds_read_b128 v[228:231], v172 offset:22528
	ds_read_b128 v[232:235], v172 offset:23552
	global_load_lds_dwordx4 v[182:183], off
	v_lshl_add_u64 v[184:185], s[24:25], 0, v[132:133]
	s_mov_b32 m0, s41
	s_nop 0
	global_load_lds_dwordx4 v[184:185], off
	s_barrier
	s_waitcnt lgkmcnt(0)
	v_mfma_f32_16x16x32_bf16 v[62:65], v[144:147], v[204:207], v[62:65]
	v_mfma_f32_16x16x32_bf16 v[58:61], v[152:155], v[204:207], v[58:61]
	v_mfma_f32_16x16x32_bf16 v[46:49], v[144:147], v[212:215], v[46:49]
	v_mfma_f32_16x16x32_bf16 v[42:45], v[152:155], v[212:215], v[42:45]
	v_mfma_f32_16x16x32_bf16 v[30:33], v[144:147], v[220:223], v[30:33]
	v_mfma_f32_16x16x32_bf16 v[26:29], v[152:155], v[220:223], v[26:29]
	v_mfma_f32_16x16x32_bf16 v[14:17], v[144:147], v[228:231], v[14:17]
	v_mfma_f32_16x16x32_bf16 v[10:13], v[152:155], v[228:231], v[10:13]
	v_mfma_f32_16x16x32_bf16 v[62:65], v[148:151], v[208:211], v[62:65]
	v_mfma_f32_16x16x32_bf16 v[58:61], v[200:203], v[208:211], v[58:61]
	v_mfma_f32_16x16x32_bf16 v[46:49], v[148:151], v[216:219], v[46:49]
	v_mfma_f32_16x16x32_bf16 v[42:45], v[200:203], v[216:219], v[42:45]
	v_mfma_f32_16x16x32_bf16 v[30:33], v[148:151], v[224:227], v[30:33]
	v_mfma_f32_16x16x32_bf16 v[26:29], v[200:203], v[224:227], v[26:29]
	v_mfma_f32_16x16x32_bf16 v[14:17], v[148:151], v[232:235], v[14:17]
	v_mfma_f32_16x16x32_bf16 v[10:13], v[200:203], v[232:235], v[10:13]
	s_barrier
; #define PG8_STAGE(bufoff, gbase, voff) do { _Pragma("unroll") for (int _i = 0; _i < 2; ++_i) \
;     __builtin_amdgcn_global_load_lds((const unsigned*)((const char*)(gbase) + (voff)[_i]), (PG8_LAS unsigned*)(lds + (bufoff) + ldsw + _i * 8192), 16, 0, 0); } while (0)
; #define PG8_LDA(dst, b, h) do { _Pragma("unroll") for (int m = 0; m < 4; ++m) _Pragma("unroll") for (int k = 0; k < 2; ++k) dst[m][k] = *(const PG8_LAS bf16x8*)(lds + PG8_SA(b, h) + aoff + m * 2048 + k * 1024); } while (0)
; #define PG8_LDB(dst, b, h) do { _Pragma("unroll") for (int n = 0; n < 2; ++n) _Pragma("unroll") for (int k = 0; k < 2; ++k) dst[n][k] = *(const PG8_LAS bf16x8*)(lds + PG8_SB(b, h) + boff + n * 2048 + k * 1024); } while (0)
; #define PG8_MMA(ai, bj, At, Bt) do { __builtin_amdgcn_s_setprio(1); _Pragma("unroll") for (int m = 0; m < 4; ++m) _Pragma("unroll") for (int n = 0; n < 2; ++n) _Pragma("unroll") for (int k = 0; k < 2; ++k) \
;     acc[ai][bj][m][n] = __builtin_amdgcn_mfma_f32_16x16x32_bf16(Bt[n][k], At[m][k], acc[ai][bj][m][n], 0, 0, 0); __builtin_amdgcn_s_setprio(0); } while (0)
; #define PG8_WAIT_V(n) asm volatile("s_waitcnt vmcnt(" #n ")" ::: "memory")
; #define PG8_WAIT_L(n) asm volatile("s_waitcnt lgkmcnt(" #n ")" ::: "memory")
; #define PG8_BAR __builtin_amdgcn_s_barrier()
; #define PG8_SCHED __builtin_amdgcn_sched_barrier(0)
; template <class Epi, class Sched>
; __device__ __forceinline__ void gemm_phase(PG8_LAS unsigned char* lds, const int lda, const int ldb, const Sched& S, const Epi& E) {
;     ...
;       PG8_STAGE(PG8_SB(0, 1), b2 + hstepB, voffB);
;       PG8_WAIT_V(6); PG8_BAR; PG8_MMA(1, 1, At, B1); PG8_BAR;
;       PG8_LDB(B0, 1, 0); PG8_SCHED; PG8_LDA(At, 1, 0); PG8_STAGE(PG8_SA(0, 1), a2 + hstepA, voffA);
;       PG8_WAIT_L(8); PG8_BAR; PG8_WAIT_L(0); PG8_MMA(0, 0, At, B0); PG8_BAR; PG8_SCHED;
;       PG8_LDB(B1, 1, 1); PG8_STAGE(PG8_SB(1, 0), b3, voffB);
;       PG8_BAR; PG8_WAIT_L(0); PG8_MMA(0, 1, At, B1); PG8_BAR;
;       PG8_LDA(At, 1, 1); PG8_STAGE(PG8_SA(1, 0), a3, voffA);
	s_add_u32 s34, s10, 0x40000
	s_addc_u32 s35, s11, 0
	s_add_i32 s31, s33, s39
	v_lshl_add_u64 v[144:145], s[34:35], 0, v[134:135]
	s_mov_b32 m0, s31
	s_nop 0
	global_load_lds_dwordx4 v[144:145], off
	v_lshl_add_u64 v[144:145], s[34:35], 0, v[132:133]
	s_add_i32 m0, s31, 0x2000
	s_nop 0
	global_load_lds_dwordx4 v[144:145], off
	s_waitcnt vmcnt(6)
	s_barrier
	v_mfma_f32_16x16x32_bf16 v[54:57], v[236:239], v[204:207], v[54:57]
	v_mfma_f32_16x16x32_bf16 v[50:53], v[244:247], v[204:207], v[50:53]
	v_mfma_f32_16x16x32_bf16 v[38:41], v[236:239], v[212:215], v[38:41]
	v_mfma_f32_16x16x32_bf16 v[34:37], v[244:247], v[212:215], v[34:37]
	v_mfma_f32_16x16x32_bf16 v[22:25], v[236:239], v[220:223], v[22:25]
	v_mfma_f32_16x16x32_bf16 v[18:21], v[244:247], v[220:223], v[18:21]
	v_mfma_f32_16x16x32_bf16 v[6:9], v[236:239], v[228:231], v[6:9]
	v_mfma_f32_16x16x32_bf16 v[2:5], v[244:247], v[228:231], v[2:5]
	v_mfma_f32_16x16x32_bf16 v[54:57], v[240:243], v[208:211], v[54:57]
	v_mfma_f32_16x16x32_bf16 v[50:53], v[248:251], v[208:211], v[50:53]
	v_mfma_f32_16x16x32_bf16 v[38:41], v[240:243], v[216:219], v[38:41]
	v_mfma_f32_16x16x32_bf16 v[34:37], v[248:251], v[216:219], v[34:37]
	v_mfma_f32_16x16x32_bf16 v[22:25], v[240:243], v[224:227], v[22:25]
	v_mfma_f32_16x16x32_bf16 v[18:21], v[248:251], v[224:227], v[18:21]
	v_mfma_f32_16x16x32_bf16 v[6:9], v[240:243], v[232:235], v[6:9]
	v_mfma_f32_16x16x32_bf16 v[2:5], v[248:251], v[232:235], v[2:5]
	s_barrier
	s_add_i32 s31, 0, 0x18000
	v_add_u32_e32 v173, s31, v131
	ds_read_b128 v[144:147], v173
	ds_read_b128 v[148:151], v173 offset:1024
	ds_read_b128 v[152:155], v173 offset:2048
	ds_read_b128 v[200:203], v173 offset:3072
	s_add_u32 s24, s24, 0x40000
	s_addc_u32 s25, s25, 0
	s_mov_b32 m0, s42
	v_lshl_add_u64 v[236:237], s[24:25], 0, v[134:135]
	ds_read_b128 v[204:207], v172 offset:32768
	ds_read_b128 v[208:211], v172 offset:33792
	ds_read_b128 v[212:215], v172 offset:34816
	ds_read_b128 v[216:219], v172 offset:35840
	ds_read_b128 v[220:223], v172 offset:36864
	ds_read_b128 v[224:227], v172 offset:37888
	ds_read_b128 v[228:231], v172 offset:38912
	ds_read_b128 v[232:235], v172 offset:39936
	global_load_lds_dwordx4 v[236:237], off
	v_lshl_add_u64 v[236:237], s[24:25], 0, v[132:133]
	s_mov_b32 m0, s43
	s_nop 0
	global_load_lds_dwordx4 v[236:237], off
	s_waitcnt lgkmcnt(8)
	s_barrier
	s_waitcnt lgkmcnt(0)
	v_mfma_f32_16x16x32_bf16 v[126:129], v[144:147], v[204:207], v[126:129]
	v_mfma_f32_16x16x32_bf16 v[122:125], v[152:155], v[204:207], v[122:125]
	v_mfma_f32_16x16x32_bf16 v[110:113], v[144:147], v[212:215], v[110:113]
	v_mfma_f32_16x16x32_bf16 v[106:109], v[152:155], v[212:215], v[106:109]
	v_mfma_f32_16x16x32_bf16 v[94:97], v[144:147], v[220:223], v[94:97]
	v_mfma_f32_16x16x32_bf16 v[90:93], v[152:155], v[220:223], v[90:93]
	v_mfma_f32_16x16x32_bf16 v[78:81], v[144:147], v[228:231], v[78:81]
	v_mfma_f32_16x16x32_bf16 v[74:77], v[152:155], v[228:231], v[74:77]
	v_mfma_f32_16x16x32_bf16 v[126:129], v[148:151], v[208:211], v[126:129]
	v_mfma_f32_16x16x32_bf16 v[122:125], v[200:203], v[208:211], v[122:125]
	v_mfma_f32_16x16x32_bf16 v[110:113], v[148:151], v[216:219], v[110:113]
	v_mfma_f32_16x16x32_bf16 v[106:109], v[200:203], v[216:219], v[106:109]
	v_mfma_f32_16x16x32_bf16 v[94:97], v[148:151], v[224:227], v[94:97]
	v_mfma_f32_16x16x32_bf16 v[90:93], v[200:203], v[224:227], v[90:93]
	v_mfma_f32_16x16x32_bf16 v[78:81], v[148:151], v[232:235], v[78:81]
	v_mfma_f32_16x16x32_bf16 v[74:77], v[200:203], v[232:235], v[74:77]
	s_barrier
	s_add_i32 s24, 0, 0x1c000
	s_add_i32 s25, s31, s39
	v_add_u32_e32 v173, s24, v131
	v_lshl_add_u64 v[156:157], v[156:157], 0, s[86:87]
	s_mov_b32 m0, s25
	ds_read_b128 v[236:239], v173
	ds_read_b128 v[240:243], v173 offset:1024
	ds_read_b128 v[244:247], v173 offset:2048
	ds_read_b128 v[248:251], v173 offset:3072
	global_load_lds_dwordx4 v[156:157], off
	v_lshl_add_u64 v[156:157], v[174:175], 0, s[86:87]
	s_add_i32 m0, s25, 0x2000
	s_nop 0
	global_load_lds_dwordx4 v[156:157], off
	s_barrier
	s_waitcnt lgkmcnt(0)
	v_mfma_f32_16x16x32_bf16 v[118:121], v[236:239], v[204:207], v[118:121]
	v_mfma_f32_16x16x32_bf16 v[114:117], v[244:247], v[204:207], v[114:117]
	v_mfma_f32_16x16x32_bf16 v[102:105], v[236:239], v[212:215], v[102:105]
	v_mfma_f32_16x16x32_bf16 v[98:101], v[244:247], v[212:215], v[98:101]
	v_mfma_f32_16x16x32_bf16 v[86:89], v[236:239], v[220:223], v[86:89]
	v_mfma_f32_16x16x32_bf16 v[82:85], v[244:247], v[220:223], v[82:85]
	v_mfma_f32_16x16x32_bf16 v[70:73], v[236:239], v[228:231], v[70:73]
	v_mfma_f32_16x16x32_bf16 v[66:69], v[244:247], v[228:231], v[66:69]
	v_mfma_f32_16x16x32_bf16 v[118:121], v[240:243], v[208:211], v[118:121]
	v_mfma_f32_16x16x32_bf16 v[114:117], v[248:251], v[208:211], v[114:117]
	v_mfma_f32_16x16x32_bf16 v[102:105], v[240:243], v[216:219], v[102:105]
	v_mfma_f32_16x16x32_bf16 v[98:101], v[248:251], v[216:219], v[98:101]
	v_mfma_f32_16x16x32_bf16 v[86:89], v[240:243], v[224:227], v[86:89]
	v_mfma_f32_16x16x32_bf16 v[82:85], v[248:251], v[224:227], v[82:85]
	v_mfma_f32_16x16x32_bf16 v[70:73], v[240:243], v[232:235], v[70:73]
	v_mfma_f32_16x16x32_bf16 v[66:69], v[248:251], v[232:235], v[66:69]
	s_barrier
	s_mov_b32 m0, s45
	v_lshl_add_u64 v[156:157], v[182:183], 0, s[86:87]
	ds_read_b128 v[204:207], v172 offset:49152
	ds_read_b128 v[208:211], v172 offset:50176
	ds_read_b128 v[212:215], v172 offset:51200
	ds_read_b128 v[216:219], v172 offset:52224
	ds_read_b128 v[220:223], v172 offset:53248
	ds_read_b128 v[224:227], v172 offset:54272
	ds_read_b128 v[228:231], v172 offset:55296
	ds_read_b128 v[232:235], v172 offset:56320
	global_load_lds_dwordx4 v[156:157], off
	v_lshl_add_u64 v[156:157], v[184:185], 0, s[86:87]
	s_mov_b32 m0, s46
	s_nop 0
	global_load_lds_dwordx4 v[156:157], off
	s_barrier
; #define PG8_STAGE(bufoff, gbase, voff) do { _Pragma("unroll") for (int _i = 0; _i < 2; ++_i) \
;     __builtin_amdgcn_global_load_lds((const unsigned*)((const char*)(gbase) + (voff)[_i]), (PG8_LAS unsigned*)(lds + (bufoff) + ldsw + _i * 8192), 16, 0, 0); } while (0)
; #define PG8_MMA(ai, bj, At, Bt) do { __builtin_amdgcn_s_setprio(1); _Pragma("unroll") for (int m = 0; m < 4; ++m) _Pragma("unroll") for (int n = 0; n < 2; ++n) _Pragma("unroll") for (int k = 0; k < 2; ++k) \
;     acc[ai][bj][m][n] = __builtin_amdgcn_mfma_f32_16x16x32_bf16(Bt[n][k], At[m][k], acc[ai][bj][m][n], 0, 0, 0); __builtin_amdgcn_s_setprio(0); } while (0)
; #define PG8_WAIT_V(n) asm volatile("s_waitcnt vmcnt(" #n ")" ::: "memory")
; #define PG8_WAIT_L(n) asm volatile("s_waitcnt lgkmcnt(" #n ")" ::: "memory")
; #define PG8_BAR __builtin_amdgcn_s_barrier()
; #define PG8_SCHED __builtin_amdgcn_sched_barrier(0)
; template <class Epi, class Sched>
; __device__ __forceinline__ void gemm_phase(PG8_LAS unsigned char* lds, const int lda, const int ldb, const Sched& S, const Epi& E) {
;     ...
;       PG8_BAR; PG8_WAIT_L(0); PG8_MMA(1, 0, At, B0); PG8_BAR; PG8_SCHED;
;       PG8_STAGE(PG8_SB(1, 1), b3 + hstepB, voffB);
;       PG8_WAIT_V(6); PG8_BAR; PG8_MMA(1, 1, At, B1); PG8_BAR;
;   __device__ __forceinline__ void operator()(const f32x4 (&acc)[2][2][4][2], const Unit& u, int wr, int wc, int fr, int fq) const {
;     ...
;               const int nn = c - 1792, part = nn >> 8, ch = nn & 255;
;               if (u.pn == 7 && bj == 0 && wc == 1 && n == 1) {
;                 *reinterpret_cast<float4*>(AB + (size_t)r * 16 + 4 * fq) = make_float4(v[0], v[1], v[2], v[3]);
;               } else {
;                 u16* d; int cstride;
;                 if (r < ML) { const int b = r >> 11, tt = r & 2047; d = FT + ((size_t)(b * 256)) * 4096 + part * 2048 + tt; cstride = 4096; }
;                 else { const int rc = r - ML, b = rc >> 8, tt = rc & 255; d = FTC + ((size_t)(b * 256)) * 512 + part * 256 + tt; cstride = 512; }
; #pragma unroll
;                 for (int e = 0; e < 4; ++e) d[(size_t)(ch + e) * cstride] = f2bf(v[e]);
;                 if (u.pn == 7 && bj == 0 && wc == 0) {
; #pragma unroll
;                   for (int e = 0; e < 4; ++e) {
;                     const int kc = n * 16 + 4 * fq + e;
;                     if (kc >= 1 && kc <= 16) d[(size_t)(64 - kc) * cstride] = f2bf(v[e]);
	s_waitcnt lgkmcnt(0)
	v_mfma_f32_16x16x32_bf16 v[62:65], v[144:147], v[204:207], v[62:65]
	v_mfma_f32_16x16x32_bf16 v[58:61], v[152:155], v[204:207], v[58:61]
	v_mfma_f32_16x16x32_bf16 v[46:49], v[144:147], v[212:215], v[46:49]
	v_mfma_f32_16x16x32_bf16 v[42:45], v[152:155], v[212:215], v[42:45]
	v_mfma_f32_16x16x32_bf16 v[30:33], v[144:147], v[220:223], v[30:33]
	v_mfma_f32_16x16x32_bf16 v[26:29], v[152:155], v[220:223], v[26:29]
	v_mfma_f32_16x16x32_bf16 v[14:17], v[144:147], v[228:231], v[14:17]
	v_mfma_f32_16x16x32_bf16 v[10:13], v[152:155], v[228:231], v[10:13]
	v_mfma_f32_16x16x32_bf16 v[62:65], v[148:151], v[208:211], v[62:65]
	v_mfma_f32_16x16x32_bf16 v[58:61], v[200:203], v[208:211], v[58:61]
	v_mfma_f32_16x16x32_bf16 v[46:49], v[148:151], v[216:219], v[46:49]
	v_mfma_f32_16x16x32_bf16 v[42:45], v[200:203], v[216:219], v[42:45]
	v_mfma_f32_16x16x32_bf16 v[30:33], v[148:151], v[224:227], v[30:33]
	v_mfma_f32_16x16x32_bf16 v[26:29], v[200:203], v[224:227], v[26:29]
	v_mfma_f32_16x16x32_bf16 v[14:17], v[148:151], v[232:235], v[14:17]
	v_mfma_f32_16x16x32_bf16 v[10:13], v[200:203], v[232:235], v[10:13]
	s_barrier
	s_add_u32 s10, s10, 0x40080
	s_addc_u32 s11, s11, 0
	s_add_i32 s24, s24, s39
	v_lshl_add_u64 v[144:145], s[10:11], 0, v[134:135]
	s_mov_b32 m0, s24
	s_nop 0
	global_load_lds_dwordx4 v[144:145], off
	v_lshl_add_u64 v[144:145], s[10:11], 0, v[132:133]
	s_add_i32 m0, s24, 0x2000
	s_nop 0
	global_load_lds_dwordx4 v[144:145], off
	s_add_i32 s30, s30, 2
	s_add_u32 s8, s8, 0x100
	s_addc_u32 s9, s9, 0
	s_add_u32 s28, s28, 0x100
	s_addc_u32 s29, s29, 0
	s_cmp_gt_u32 s30, 13
	s_waitcnt vmcnt(6)
	s_barrier
	v_mfma_f32_16x16x32_bf16 v[54:57], v[236:239], v[204:207], v[54:57]
	v_mfma_f32_16x16x32_bf16 v[50:53], v[244:247], v[204:207], v[50:53]
	v_mfma_f32_16x16x32_bf16 v[38:41], v[236:239], v[212:215], v[38:41]
	v_mfma_f32_16x16x32_bf16 v[34:37], v[244:247], v[212:215], v[34:37]
	v_mfma_f32_16x16x32_bf16 v[22:25], v[236:239], v[220:223], v[22:25]
	v_mfma_f32_16x16x32_bf16 v[18:21], v[244:247], v[220:223], v[18:21]
	v_mfma_f32_16x16x32_bf16 v[6:9], v[236:239], v[228:231], v[6:9]
	v_mfma_f32_16x16x32_bf16 v[2:5], v[244:247], v[228:231], v[2:5]
	v_mfma_f32_16x16x32_bf16 v[54:57], v[240:243], v[208:211], v[54:57]
	v_mfma_f32_16x16x32_bf16 v[50:53], v[248:251], v[208:211], v[50:53]
	v_mfma_f32_16x16x32_bf16 v[38:41], v[240:243], v[216:219], v[38:41]
	v_mfma_f32_16x16x32_bf16 v[34:37], v[248:251], v[216:219], v[34:37]
	v_mfma_f32_16x16x32_bf16 v[22:25], v[240:243], v[224:227], v[22:25]
	v_mfma_f32_16x16x32_bf16 v[18:21], v[248:251], v[224:227], v[18:21]
	v_mfma_f32_16x16x32_bf16 v[6:9], v[240:243], v[232:235], v[6:9]
	v_mfma_f32_16x16x32_bf16 v[2:5], v[248:251], v[232:235], v[2:5]
	s_barrier
	s_cbranch_scc0 .LBB0_335
	s_lshl_b32 s15, s2, 8
	s_add_i32 s15, s15, s44
	v_or_b32_e32 v152, s15, v1
	s_mov_b32 s2, 0xffff
	v_cmp_lt_i32_e64 s[10:11], s2, v152
	s_and_b32 s2, s15, 0xffffff00
	s_add_i32 s2, s2, 0xffff0000
	s_lshl_b64 s[28:29], s[2:3], 10
	s_ashr_i32 s2, s15, 3
	s_and_b32 s8, s2, 0xffffff00
	s_ashr_i32 s9, s8, 31
	s_lshl_b64 s[26:27], s[8:9], 13
	s_lshl_b32 s24, s48, 8
	s_cmp_gt_i32 s48, 6
	s_cselect_b64 s[30:31], -1, 0
	v_bitop3_b32 v146, s15, v186, v1 bitop3:0xc8
	v_bitop3_b32 v148, s15, v187, v1 bitop3:0xc8
	s_mov_b64 s[8:9], -1
	s_and_b64 vcc, exec, s[30:31]
	s_cbranch_vccz .LBB0_346
	s_and_saveexec_b64 s[8:9], s[10:11]
	s_xor_b64 s[8:9], exec, s[8:9]
	s_add_u32 s34, s54, s28
	s_addc_u32 s35, s55, s29
	s_or_saveexec_b64 s[8:9], s[8:9]
	s_add_i32 s2, s24, 0xfffff900
	v_mov_b64_e32 v[144:145], 0x200
	v_mov_b32_e32 v150, s2
	v_mov_b64_e32 v[154:155], s[34:35]
	v_mov_b64_e32 v[156:157], v[146:147]
	s_xor_b64 exec, exec, s[8:9]
	s_add_u32 s34, s69, s26
	s_addc_u32 s35, s52, s27
	s_lshl_b32 s2, s2, 3
	v_mov_b64_e32 v[144:145], 0x1000
	v_mov_b32_e32 v150, s2
	v_mov_b64_e32 v[154:155], s[34:35]
	v_mov_b64_e32 v[156:157], v[148:149]
	s_or_b64 exec, exec, s[8:9]
	v_ashrrev_i32_e32 v151, 31, v150
	v_lshl_add_u64 v[150:151], v[150:151], 1, v[154:155]
	v_lshlrev_b32_e32 v154, 1, v156
	v_mov_b32_e32 v155, v0
	v_mul_u32_u24_e32 v145, v144, v136
	v_lshl_add_u64 v[150:151], v[150:151], 0, v[154:155]
	v_lshlrev_b32_e32 v154, 1, v145
	v_cvt_pk_bf16_f32 v149, v126, s0
	v_lshl_add_u64 v[154:155], v[150:151], 0, v[154:155]
	v_mul_u32_u24_e32 v147, v144, v166
	global_store_short v[154:155], v149, off
	v_lshlrev_b32_e32 v154, 1, v147
	v_mov_b32_e32 v155, v0
	v_cvt_pk_bf16_f32 v145, v127, s0
	v_lshl_add_u64 v[154:155], v[150:151], 0, v[154:155]
	v_mul_u32_u24_e32 v153, v144, v167
	global_store_short v[154:155], v145, off
	v_lshlrev_b32_e32 v154, 1, v153
	v_mov_b32_e32 v155, v0
	s_cmp_lg_u32 s48, 7
	v_cvt_pk_bf16_f32 v147, v128, s0
	v_lshl_add_u64 v[154:155], v[150:151], 0, v[154:155]
	s_cselect_b64 s[8:9], -1, 0
	global_store_short v[154:155], v147, off
	v_mul_u32_u24_e32 v154, v144, v168
	s_xor_b64 s[34:35], s[12:13], -1
	v_lshlrev_b32_e32 v154, 1, v154
	v_mov_b32_e32 v155, v0
	s_or_b64 s[8:9], s[34:35], s[8:9]
	v_cvt_pk_bf16_f32 v153, v129, s0
	v_lshl_add_u64 v[154:155], v[150:151], 0, v[154:155]
	s_and_b64 vcc, exec, s[8:9]
	global_store_short v[154:155], v153, off
	s_cbranch_vccnz .LBB0_345
	s_and_saveexec_b64 s[8:9], s[4:5]
	s_cbranch_execz .LBB0_344
	v_mul_u32_u24_e32 v154, v144, v158
	v_lshlrev_b32_e32 v154, 1, v154
	v_mov_b32_e32 v155, v0
	v_lshl_add_u64 v[154:155], v[150:151], 0, v[154:155]
	global_store_short v[154:155], v149, off

; #define PG8_STAGE(bufoff, gbase, voff) do { _Pragma("unroll") for (int _i = 0; _i < 2; ++_i) \
;     __builtin_amdgcn_global_load_lds((const unsigned*)((const char*)(gbase) + (voff)[_i]), (PG8_LAS unsigned*)(lds + (bufoff) + ldsw + _i * 8192), 16, 0, 0); } while (0)
; #define PG8_LDA(dst, b, h) do { _Pragma("unroll") for (int m = 0; m < 4; ++m) _Pragma("unroll") for (int k = 0; k < 2; ++k) dst[m][k] = *(const PG8_LAS bf16x8*)(lds + PG8_SA(b, h) + aoff + m * 2048 + k * 1024); } while (0)
; #define PG8_LDB(dst, b, h) do { _Pragma("unroll") for (int n = 0; n < 2; ++n) _Pragma("unroll") for (int k = 0; k < 2; ++k) dst[n][k] = *(const PG8_LAS bf16x8*)(lds + PG8_SB(b, h) + boff + n * 2048 + k * 1024); } while (0)
; #define PG8_MMA(ai, bj, At, Bt) do { __builtin_amdgcn_s_setprio(1); _Pragma("unroll") for (int m = 0; m < 4; ++m) _Pragma("unroll") for (int n = 0; n < 2; ++n) _Pragma("unroll") for (int k = 0; k < 2; ++k) \
;     acc[ai][bj][m][n] = __builtin_amdgcn_mfma_f32_16x16x32_bf16(Bt[n][k], At[m][k], acc[ai][bj][m][n], 0, 0, 0); __builtin_amdgcn_s_setprio(0); } while (0)
; #define PG8_WAIT_L(n) asm volatile("s_waitcnt lgkmcnt(" #n ")" ::: "memory")
; #define PG8_BAR __builtin_amdgcn_s_barrier()
; #define PG8_SCHED __builtin_amdgcn_sched_barrier(0)
; template <class Epi, class Sched>
; __device__ __forceinline__ void gemm_phase(PG8_LAS unsigned char* lds, const int lda, const int ldb, const Sched& S, const Epi& E) {
;     ...
;       PG8_LDB(B0, 0, 0); PG8_SCHED; PG8_LDA(At, 0, 0); PG8_STAGE(PG8_SA(1, 1), a1 + hstepA, voffA);
;       PG8_WAIT_L(8); PG8_BAR; PG8_WAIT_L(0); PG8_MMA(0, 0, At, B0); PG8_BAR; PG8_SCHED;
;       PG8_LDB(B1, 0, 1); PG8_STAGE(PG8_SB(0, 0), b2, voffB);
;       PG8_BAR; PG8_WAIT_L(0); PG8_MMA(0, 1, At, B1); PG8_BAR;
;       PG8_LDA(At, 0, 1); PG8_STAGE(PG8_SA(0, 0), a2, voffA);
;       PG8_BAR; PG8_WAIT_L(0); PG8_MMA(1, 0, At, B0); PG8_BAR; PG8_SCHED;
.LBB0_685:
	s_add_u32 s12, s10, 0xfffc0080
	s_addc_u32 s13, s11, -1
	s_add_i32 s31, 0, 0x10000
	v_add_u32_e32 v156, s31, v131
	ds_read_b128 v[144:147], v156
	ds_read_b128 v[148:151], v156 offset:1024
	ds_read_b128 v[152:155], v156 offset:2048
	ds_read_b128 v[200:203], v156 offset:3072
	s_cmp_eq_u32 s30, 12
	s_cselect_b32 s25, s19, s13
	s_cselect_b32 s24, s26, s12
	s_cselect_b32 s13, s17, s29
	s_cselect_b32 s12, s27, s28
	v_lshl_add_u64 v[156:157], s[10:11], 0, v[140:141]
	s_add_i32 m0, s40, 0xc000
	ds_read_b128 v[204:207], v172
	ds_read_b128 v[208:211], v172 offset:1024
	ds_read_b128 v[212:215], v172 offset:2048
	ds_read_b128 v[216:219], v172 offset:3072
	ds_read_b128 v[220:223], v172 offset:4096
	ds_read_b128 v[224:227], v172 offset:5120
	ds_read_b128 v[228:231], v172 offset:6144
	ds_read_b128 v[232:235], v172 offset:7168
	global_load_lds_dwordx4 v[156:157], off
	v_lshl_add_u64 v[156:157], s[10:11], 0, v[142:143]
	s_add_i32 m0, s40, 0xe000
	s_nop 0
	global_load_lds_dwordx4 v[156:157], off
	s_waitcnt lgkmcnt(8)
	s_barrier
	s_waitcnt lgkmcnt(0)
	v_mfma_f32_16x16x32_bf16 v[126:129], v[144:147], v[204:207], v[126:129]
	v_mfma_f32_16x16x32_bf16 v[122:125], v[152:155], v[204:207], v[122:125]
	v_mfma_f32_16x16x32_bf16 v[110:113], v[144:147], v[212:215], v[110:113]
	v_mfma_f32_16x16x32_bf16 v[106:109], v[152:155], v[212:215], v[106:109]
	v_mfma_f32_16x16x32_bf16 v[94:97], v[144:147], v[220:223], v[94:97]
	v_mfma_f32_16x16x32_bf16 v[90:93], v[152:155], v[220:223], v[90:93]
	v_mfma_f32_16x16x32_bf16 v[78:81], v[144:147], v[228:231], v[78:81]
	v_mfma_f32_16x16x32_bf16 v[74:77], v[152:155], v[228:231], v[74:77]
	v_mfma_f32_16x16x32_bf16 v[126:129], v[148:151], v[208:211], v[126:129]
	v_mfma_f32_16x16x32_bf16 v[122:125], v[200:203], v[208:211], v[122:125]
	v_mfma_f32_16x16x32_bf16 v[110:113], v[148:151], v[216:219], v[110:113]
	v_mfma_f32_16x16x32_bf16 v[106:109], v[200:203], v[216:219], v[106:109]
	v_mfma_f32_16x16x32_bf16 v[94:97], v[148:151], v[224:227], v[94:97]
	v_mfma_f32_16x16x32_bf16 v[90:93], v[200:203], v[224:227], v[90:93]
	v_mfma_f32_16x16x32_bf16 v[78:81], v[148:151], v[232:235], v[78:81]
	v_mfma_f32_16x16x32_bf16 v[74:77], v[200:203], v[232:235], v[74:77]
	s_barrier
	s_add_i32 s33, 0, 0x14000
	v_add_u32_e32 v156, s33, v131
	s_add_i32 s31, s31, s39
	ds_read_b128 v[236:239], v156
	ds_read_b128 v[240:243], v156 offset:1024
	ds_read_b128 v[244:247], v156 offset:2048
	ds_read_b128 v[248:251], v156 offset:3072
	v_lshl_add_u64 v[156:157], s[12:13], 0, v[134:135]
	s_mov_b32 m0, s31
	v_lshl_add_u64 v[174:175], s[12:13], 0, v[132:133]
	global_load_lds_dwordx4 v[156:157], off
	s_add_i32 m0, s31, 0x2000
	s_nop 0
	global_load_lds_dwordx4 v[174:175], off
	s_barrier
	s_waitcnt lgkmcnt(0)
	v_mfma_f32_16x16x32_bf16 v[118:121], v[236:239], v[204:207], v[118:121]
	v_mfma_f32_16x16x32_bf16 v[114:117], v[244:247], v[204:207], v[114:117]
	v_mfma_f32_16x16x32_bf16 v[102:105], v[236:239], v[212:215], v[102:105]
	v_mfma_f32_16x16x32_bf16 v[98:101], v[244:247], v[212:215], v[98:101]
	v_mfma_f32_16x16x32_bf16 v[86:89], v[236:239], v[220:223], v[86:89]
	v_mfma_f32_16x16x32_bf16 v[82:85], v[244:247], v[220:223], v[82:85]
	v_mfma_f32_16x16x32_bf16 v[70:73], v[236:239], v[228:231], v[70:73]
	v_mfma_f32_16x16x32_bf16 v[66:69], v[244:247], v[228:231], v[66:69]
	v_mfma_f32_16x16x32_bf16 v[118:121], v[240:243], v[208:211], v[118:121]
	v_mfma_f32_16x16x32_bf16 v[114:117], v[248:251], v[208:211], v[114:117]
	v_mfma_f32_16x16x32_bf16 v[102:105], v[240:243], v[216:219], v[102:105]
	v_mfma_f32_16x16x32_bf16 v[98:101], v[248:251], v[216:219], v[98:101]
	v_mfma_f32_16x16x32_bf16 v[86:89], v[240:243], v[224:227], v[86:89]
	v_mfma_f32_16x16x32_bf16 v[82:85], v[248:251], v[224:227], v[82:85]
	v_mfma_f32_16x16x32_bf16 v[70:73], v[240:243], v[232:235], v[70:73]
	v_mfma_f32_16x16x32_bf16 v[66:69], v[248:251], v[232:235], v[66:69]
	s_barrier
	s_mov_b32 m0, s40
	v_lshl_add_u64 v[182:183], s[24:25], 0, v[134:135]
	ds_read_b128 v[204:207], v172 offset:16384
	ds_read_b128 v[208:211], v172 offset:17408
	ds_read_b128 v[212:215], v172 offset:18432
	ds_read_b128 v[216:219], v172 offset:19456
	ds_read_b128 v[220:223], v172 offset:20480
	ds_read_b128 v[224:227], v172 offset:21504
	ds_read_b128 v[228:231], v172 offset:22528
	ds_read_b128 v[232:235], v172 offset:23552
	global_load_lds_dwordx4 v[182:183], off
	v_lshl_add_u64 v[184:185], s[24:25], 0, v[132:133]
	s_mov_b32 m0, s41
	s_nop 0
	global_load_lds_dwordx4 v[184:185], off
	s_barrier
	s_waitcnt lgkmcnt(0)
	v_mfma_f32_16x16x32_bf16 v[62:65], v[144:147], v[204:207], v[62:65]
	v_mfma_f32_16x16x32_bf16 v[58:61], v[152:155], v[204:207], v[58:61]
	v_mfma_f32_16x16x32_bf16 v[46:49], v[144:147], v[212:215], v[46:49]
	v_mfma_f32_16x16x32_bf16 v[42:45], v[152:155], v[212:215], v[42:45]
	v_mfma_f32_16x16x32_bf16 v[30:33], v[144:147], v[220:223], v[30:33]
	v_mfma_f32_16x16x32_bf16 v[26:29], v[152:155], v[220:223], v[26:29]
	v_mfma_f32_16x16x32_bf16 v[14:17], v[144:147], v[228:231], v[14:17]
	v_mfma_f32_16x16x32_bf16 v[10:13], v[152:155], v[228:231], v[10:13]
	v_mfma_f32_16x16x32_bf16 v[62:65], v[148:151], v[208:211], v[62:65]
	v_mfma_f32_16x16x32_bf16 v[58:61], v[200:203], v[208:211], v[58:61]
	v_mfma_f32_16x16x32_bf16 v[46:49], v[148:151], v[216:219], v[46:49]
	v_mfma_f32_16x16x32_bf16 v[42:45], v[200:203], v[216:219], v[42:45]
	v_mfma_f32_16x16x32_bf16 v[30:33], v[148:151], v[224:227], v[30:33]
	v_mfma_f32_16x16x32_bf16 v[26:29], v[200:203], v[224:227], v[26:29]
	v_mfma_f32_16x16x32_bf16 v[14:17], v[148:151], v[232:235], v[14:17]
	v_mfma_f32_16x16x32_bf16 v[10:13], v[200:203], v[232:235], v[10:13]
	s_barrier
; #define PG8_STAGE(bufoff, gbase, voff) do { _Pragma("unroll") for (int _i = 0; _i < 2; ++_i) \
;     __builtin_amdgcn_global_load_lds((const unsigned*)((const char*)(gbase) + (voff)[_i]), (PG8_LAS unsigned*)(lds + (bufoff) + ldsw + _i * 8192), 16, 0, 0); } while (0)
; #define PG8_LDA(dst, b, h) do { _Pragma("unroll") for (int m = 0; m < 4; ++m) _Pragma("unroll") for (int k = 0; k < 2; ++k) dst[m][k] = *(const PG8_LAS bf16x8*)(lds + PG8_SA(b, h) + aoff + m * 2048 + k * 1024); } while (0)
; #define PG8_LDB(dst, b, h) do { _Pragma("unroll") for (int n = 0; n < 2; ++n) _Pragma("unroll") for (int k = 0; k < 2; ++k) dst[n][k] = *(const PG8_LAS bf16x8*)(lds + PG8_SB(b, h) + boff + n * 2048 + k * 1024); } while (0)
; #define PG8_MMA(ai, bj, At, Bt) do { __builtin_amdgcn_s_setprio(1); _Pragma("unroll") for (int m = 0; m < 4; ++m) _Pragma("unroll") for (int n = 0; n < 2; ++n) _Pragma("unroll") for (int k = 0; k < 2; ++k) \
;     acc[ai][bj][m][n] = __builtin_amdgcn_mfma_f32_16x16x32_bf16(Bt[n][k], At[m][k], acc[ai][bj][m][n], 0, 0, 0); __builtin_amdgcn_s_setprio(0); } while (0)
; #define PG8_WAIT_V(n) asm volatile("s_waitcnt vmcnt(" #n ")" ::: "memory")
; #define PG8_WAIT_L(n) asm volatile("s_waitcnt lgkmcnt(" #n ")" ::: "memory")
; #define PG8_BAR __builtin_amdgcn_s_barrier()
; #define PG8_SCHED __builtin_amdgcn_sched_barrier(0)
; template <class Epi, class Sched>
; __device__ __forceinline__ void gemm_phase(PG8_LAS unsigned char* lds, const int lda, const int ldb, const Sched& S, const Epi& E) {
;     ...
;       PG8_STAGE(PG8_SB(0, 1), b2 + hstepB, voffB);
;       PG8_WAIT_V(6); PG8_BAR; PG8_MMA(1, 1, At, B1); PG8_BAR;
;       PG8_LDB(B0, 1, 0); PG8_SCHED; PG8_LDA(At, 1, 0); PG8_STAGE(PG8_SA(0, 1), a2 + hstepA, voffA);
;       PG8_WAIT_L(8); PG8_BAR; PG8_WAIT_L(0); PG8_MMA(0, 0, At, B0); PG8_BAR; PG8_SCHED;
;       PG8_LDB(B1, 1, 1); PG8_STAGE(PG8_SB(1, 0), b3, voffB);
;       PG8_BAR; PG8_WAIT_L(0); PG8_MMA(0, 1, At, B1); PG8_BAR;
;       PG8_LDA(At, 1, 1); PG8_STAGE(PG8_SA(1, 0), a3, voffA);
;       PG8_BAR; PG8_WAIT_L(0); PG8_MMA(1, 0, At, B0); PG8_BAR; PG8_SCHED;
	s_add_u32 s34, s12, 0x40000
	s_addc_u32 s35, s13, 0
	s_add_i32 s31, s33, s39
	v_lshl_add_u64 v[144:145], s[34:35], 0, v[134:135]
	s_mov_b32 m0, s31
	s_nop 0
	global_load_lds_dwordx4 v[144:145], off
	v_lshl_add_u64 v[144:145], s[34:35], 0, v[132:133]
	s_add_i32 m0, s31, 0x2000
	s_nop 0
	global_load_lds_dwordx4 v[144:145], off
	s_waitcnt vmcnt(6)
	s_barrier
	v_mfma_f32_16x16x32_bf16 v[54:57], v[236:239], v[204:207], v[54:57]
	v_mfma_f32_16x16x32_bf16 v[50:53], v[244:247], v[204:207], v[50:53]
	v_mfma_f32_16x16x32_bf16 v[38:41], v[236:239], v[212:215], v[38:41]
	v_mfma_f32_16x16x32_bf16 v[34:37], v[244:247], v[212:215], v[34:37]
	v_mfma_f32_16x16x32_bf16 v[22:25], v[236:239], v[220:223], v[22:25]
	v_mfma_f32_16x16x32_bf16 v[18:21], v[244:247], v[220:223], v[18:21]
	v_mfma_f32_16x16x32_bf16 v[6:9], v[236:239], v[228:231], v[6:9]
	v_mfma_f32_16x16x32_bf16 v[2:5], v[244:247], v[228:231], v[2:5]
	v_mfma_f32_16x16x32_bf16 v[54:57], v[240:243], v[208:211], v[54:57]
	v_mfma_f32_16x16x32_bf16 v[50:53], v[248:251], v[208:211], v[50:53]
	v_mfma_f32_16x16x32_bf16 v[38:41], v[240:243], v[216:219], v[38:41]
	v_mfma_f32_16x16x32_bf16 v[34:37], v[248:251], v[216:219], v[34:37]
	v_mfma_f32_16x16x32_bf16 v[22:25], v[240:243], v[224:227], v[22:25]
	v_mfma_f32_16x16x32_bf16 v[18:21], v[248:251], v[224:227], v[18:21]
	v_mfma_f32_16x16x32_bf16 v[6:9], v[240:243], v[232:235], v[6:9]
	v_mfma_f32_16x16x32_bf16 v[2:5], v[248:251], v[232:235], v[2:5]
	s_barrier
	s_add_i32 s31, 0, 0x18000
	v_add_u32_e32 v173, s31, v131
	ds_read_b128 v[144:147], v173
	ds_read_b128 v[148:151], v173 offset:1024
	ds_read_b128 v[152:155], v173 offset:2048
	ds_read_b128 v[200:203], v173 offset:3072
	s_add_u32 s24, s24, 0x40000
	s_addc_u32 s25, s25, 0
	s_mov_b32 m0, s42
	v_lshl_add_u64 v[236:237], s[24:25], 0, v[134:135]
	ds_read_b128 v[204:207], v172 offset:32768
	ds_read_b128 v[208:211], v172 offset:33792
	ds_read_b128 v[212:215], v172 offset:34816
	ds_read_b128 v[216:219], v172 offset:35840
	ds_read_b128 v[220:223], v172 offset:36864
	ds_read_b128 v[224:227], v172 offset:37888
	ds_read_b128 v[228:231], v172 offset:38912
	ds_read_b128 v[232:235], v172 offset:39936
	global_load_lds_dwordx4 v[236:237], off
	v_lshl_add_u64 v[236:237], s[24:25], 0, v[132:133]
	s_mov_b32 m0, s43
	s_nop 0
	global_load_lds_dwordx4 v[236:237], off
	s_waitcnt lgkmcnt(8)
	s_barrier
	s_waitcnt lgkmcnt(0)
	v_mfma_f32_16x16x32_bf16 v[126:129], v[144:147], v[204:207], v[126:129]
	v_mfma_f32_16x16x32_bf16 v[122:125], v[152:155], v[204:207], v[122:125]
	v_mfma_f32_16x16x32_bf16 v[110:113], v[144:147], v[212:215], v[110:113]
	v_mfma_f32_16x16x32_bf16 v[106:109], v[152:155], v[212:215], v[106:109]
	v_mfma_f32_16x16x32_bf16 v[94:97], v[144:147], v[220:223], v[94:97]
	v_mfma_f32_16x16x32_bf16 v[90:93], v[152:155], v[220:223], v[90:93]
	v_mfma_f32_16x16x32_bf16 v[78:81], v[144:147], v[228:231], v[78:81]
	v_mfma_f32_16x16x32_bf16 v[74:77], v[152:155], v[228:231], v[74:77]
	v_mfma_f32_16x16x32_bf16 v[126:129], v[148:151], v[208:211], v[126:129]
	v_mfma_f32_16x16x32_bf16 v[122:125], v[200:203], v[208:211], v[122:125]
	v_mfma_f32_16x16x32_bf16 v[110:113], v[148:151], v[216:219], v[110:113]
	v_mfma_f32_16x16x32_bf16 v[106:109], v[200:203], v[216:219], v[106:109]
	v_mfma_f32_16x16x32_bf16 v[94:97], v[148:151], v[224:227], v[94:97]
	v_mfma_f32_16x16x32_bf16 v[90:93], v[200:203], v[224:227], v[90:93]
	v_mfma_f32_16x16x32_bf16 v[78:81], v[148:151], v[232:235], v[78:81]
	v_mfma_f32_16x16x32_bf16 v[74:77], v[200:203], v[232:235], v[74:77]
	s_barrier
	s_add_i32 s24, 0, 0x1c000
	s_add_i32 s25, s31, s39
	v_add_u32_e32 v173, s24, v131
	v_lshl_add_u64 v[156:157], v[156:157], 0, s[86:87]
	s_mov_b32 m0, s25
	ds_read_b128 v[236:239], v173
	ds_read_b128 v[240:243], v173 offset:1024
	ds_read_b128 v[244:247], v173 offset:2048
	ds_read_b128 v[248:251], v173 offset:3072
	global_load_lds_dwordx4 v[156:157], off
	v_lshl_add_u64 v[156:157], v[174:175], 0, s[86:87]
	s_add_i32 m0, s25, 0x2000
	s_nop 0
	global_load_lds_dwordx4 v[156:157], off
	s_barrier
	s_waitcnt lgkmcnt(0)
	v_mfma_f32_16x16x32_bf16 v[118:121], v[236:239], v[204:207], v[118:121]
	v_mfma_f32_16x16x32_bf16 v[114:117], v[244:247], v[204:207], v[114:117]
	v_mfma_f32_16x16x32_bf16 v[102:105], v[236:239], v[212:215], v[102:105]
	v_mfma_f32_16x16x32_bf16 v[98:101], v[244:247], v[212:215], v[98:101]
	v_mfma_f32_16x16x32_bf16 v[86:89], v[236:239], v[220:223], v[86:89]
	v_mfma_f32_16x16x32_bf16 v[82:85], v[244:247], v[220:223], v[82:85]
	v_mfma_f32_16x16x32_bf16 v[70:73], v[236:239], v[228:231], v[70:73]
	v_mfma_f32_16x16x32_bf16 v[66:69], v[244:247], v[228:231], v[66:69]
	v_mfma_f32_16x16x32_bf16 v[118:121], v[240:243], v[208:211], v[118:121]
	v_mfma_f32_16x16x32_bf16 v[114:117], v[248:251], v[208:211], v[114:117]
	v_mfma_f32_16x16x32_bf16 v[102:105], v[240:243], v[216:219], v[102:105]
	v_mfma_f32_16x16x32_bf16 v[98:101], v[248:251], v[216:219], v[98:101]
	v_mfma_f32_16x16x32_bf16 v[86:89], v[240:243], v[224:227], v[86:89]
	v_mfma_f32_16x16x32_bf16 v[82:85], v[248:251], v[224:227], v[82:85]
	v_mfma_f32_16x16x32_bf16 v[70:73], v[240:243], v[232:235], v[70:73]
	v_mfma_f32_16x16x32_bf16 v[66:69], v[248:251], v[232:235], v[66:69]
	s_barrier
	s_mov_b32 m0, s45
	v_lshl_add_u64 v[156:157], v[182:183], 0, s[86:87]
	ds_read_b128 v[204:207], v172 offset:49152
	ds_read_b128 v[208:211], v172 offset:50176
	ds_read_b128 v[212:215], v172 offset:51200
	ds_read_b128 v[216:219], v172 offset:52224
	ds_read_b128 v[220:223], v172 offset:53248
	ds_read_b128 v[224:227], v172 offset:54272
	ds_read_b128 v[228:231], v172 offset:55296
	ds_read_b128 v[232:235], v172 offset:56320
	global_load_lds_dwordx4 v[156:157], off
	v_lshl_add_u64 v[156:157], v[184:185], 0, s[86:87]
	s_mov_b32 m0, s46
	s_nop 0
	global_load_lds_dwordx4 v[156:157], off
	s_barrier
; #define PG8_STAGE(bufoff, gbase, voff) do { _Pragma("unroll") for (int _i = 0; _i < 2; ++_i) \
;     __builtin_amdgcn_global_load_lds((const unsigned*)((const char*)(gbase) + (voff)[_i]), (PG8_LAS unsigned*)(lds + (bufoff) + ldsw + _i * 8192), 16, 0, 0); } while (0)
; #define PG8_WAIT_V(n) asm volatile("s_waitcnt vmcnt(" #n ")" ::: "memory")
; #define PG8_BAR __builtin_amdgcn_s_barrier()
; template <class Epi, class Sched>
; __device__ __forceinline__ void gemm_phase(PG8_LAS unsigned char* lds, const int lda, const int ldb, const Sched& S, const Epi& E) {
;     ...
;       PG8_BAR; PG8_WAIT_L(0); PG8_MMA(1, 0, At, B0); PG8_BAR; PG8_SCHED;
;       PG8_STAGE(PG8_SB(1, 1), b3 + hstepB, voffB);
;       PG8_WAIT_V(6); PG8_BAR; PG8_MMA(1, 1, At, B1); PG8_BAR;
;   __device__ __forceinline__ void operator()(const f32x4 (&acc)[2][2][4][2], const Unit& u, int wr, int wc, int fr, int fq) const {
;     ...
;         const int r = u.pm * 256 + ai * 128 + wr * 64 + m * 16 + fr;
; #pragma unroll
;         for (int bj = 0; bj < 2; ++bj)
; #pragma unroll
;           for (int n = 0; n < 2; ++n) {
;             const f32x4 v = acc[ai][bj][m][n];
;             const int c = u.pn * 256 + bj * 128 + wc * 32 + n * 16 + 4 * fq;
;             if (u.pn < 7) {
;               uint2 w; w.x = pack2(v[0], v[1]); w.y = pack2(v[2], v[3]);
;               *reinterpret_cast<uint2*>(PB + (size_t)r * PBW + c) = w;
;             } else {
;               const int nn = c - 1792, part = nn >> 8, ch = nn & 255;
;               if (u.pn == 7 && bj == 0 && wc == 1 && n == 1) {
;                 *reinterpret_cast<float4*>(AB + (size_t)r * 16 + 4 * fq) = make_float4(v[0], v[1], v[2], v[3]);
;               } else {
;                 u16* d; int cstride;
;                 if (r < ML) { const int b = r >> 11, tt = r & 2047; d = FT + ((size_t)(b * 256)) * 4096 + part * 2048 + tt; cstride = 4096; }
;                 else { const int rc = r - ML, b = rc >> 8, tt = rc & 255; d = FTC + ((size_t)(b * 256)) * 512 + part * 256 + tt; cstride = 512; }
; #pragma unroll
;                 for (int e = 0; e < 4; ++e) d[(size_t)(ch + e) * cstride] = f2bf(v[e]);
;                 if (u.pn == 7 && bj == 0 && wc == 0) {
; #pragma unroll
;                   for (int e = 0; e < 4; ++e) {
;                     const int kc = n * 16 + 4 * fq + e;
;                     if (kc >= 1 && kc <= 16) d[(size_t)(64 - kc) * cstride] = f2bf(v[e]);
	s_waitcnt lgkmcnt(0)
	v_mfma_f32_16x16x32_bf16 v[62:65], v[144:147], v[204:207], v[62:65]
	v_mfma_f32_16x16x32_bf16 v[58:61], v[152:155], v[204:207], v[58:61]
	v_mfma_f32_16x16x32_bf16 v[46:49], v[144:147], v[212:215], v[46:49]
	v_mfma_f32_16x16x32_bf16 v[42:45], v[152:155], v[212:215], v[42:45]
	v_mfma_f32_16x16x32_bf16 v[30:33], v[144:147], v[220:223], v[30:33]
	v_mfma_f32_16x16x32_bf16 v[26:29], v[152:155], v[220:223], v[26:29]
	v_mfma_f32_16x16x32_bf16 v[14:17], v[144:147], v[228:231], v[14:17]
	v_mfma_f32_16x16x32_bf16 v[10:13], v[152:155], v[228:231], v[10:13]
	v_mfma_f32_16x16x32_bf16 v[62:65], v[148:151], v[208:211], v[62:65]
	v_mfma_f32_16x16x32_bf16 v[58:61], v[200:203], v[208:211], v[58:61]
	v_mfma_f32_16x16x32_bf16 v[46:49], v[148:151], v[216:219], v[46:49]
	v_mfma_f32_16x16x32_bf16 v[42:45], v[200:203], v[216:219], v[42:45]
	v_mfma_f32_16x16x32_bf16 v[30:33], v[148:151], v[224:227], v[30:33]
	v_mfma_f32_16x16x32_bf16 v[26:29], v[200:203], v[224:227], v[26:29]
	v_mfma_f32_16x16x32_bf16 v[14:17], v[148:151], v[232:235], v[14:17]
	v_mfma_f32_16x16x32_bf16 v[10:13], v[200:203], v[232:235], v[10:13]
	s_barrier
	s_add_u32 s12, s12, 0x40080
	s_addc_u32 s13, s13, 0
	s_add_i32 s24, s24, s39
	v_lshl_add_u64 v[144:145], s[12:13], 0, v[134:135]
	s_mov_b32 m0, s24
	s_nop 0
	global_load_lds_dwordx4 v[144:145], off
	v_lshl_add_u64 v[144:145], s[12:13], 0, v[132:133]
	s_add_i32 m0, s24, 0x2000
	s_nop 0
	global_load_lds_dwordx4 v[144:145], off
	s_add_i32 s30, s30, 2
	s_add_u32 s10, s10, 0x100
	s_addc_u32 s11, s11, 0
	s_add_u32 s28, s28, 0x100
	s_addc_u32 s29, s29, 0
	s_cmp_gt_u32 s30, 13
	s_waitcnt vmcnt(6)
	s_barrier
	v_mfma_f32_16x16x32_bf16 v[54:57], v[236:239], v[204:207], v[54:57]
	v_mfma_f32_16x16x32_bf16 v[50:53], v[244:247], v[204:207], v[50:53]
	v_mfma_f32_16x16x32_bf16 v[38:41], v[236:239], v[212:215], v[38:41]
	v_mfma_f32_16x16x32_bf16 v[34:37], v[244:247], v[212:215], v[34:37]
	v_mfma_f32_16x16x32_bf16 v[22:25], v[236:239], v[220:223], v[22:25]
	v_mfma_f32_16x16x32_bf16 v[18:21], v[244:247], v[220:223], v[18:21]
	v_mfma_f32_16x16x32_bf16 v[6:9], v[236:239], v[228:231], v[6:9]
	v_mfma_f32_16x16x32_bf16 v[2:5], v[244:247], v[228:231], v[2:5]
	v_mfma_f32_16x16x32_bf16 v[54:57], v[240:243], v[208:211], v[54:57]
	v_mfma_f32_16x16x32_bf16 v[50:53], v[248:251], v[208:211], v[50:53]
	v_mfma_f32_16x16x32_bf16 v[38:41], v[240:243], v[216:219], v[38:41]
	v_mfma_f32_16x16x32_bf16 v[34:37], v[248:251], v[216:219], v[34:37]
	v_mfma_f32_16x16x32_bf16 v[22:25], v[240:243], v[224:227], v[22:25]
	v_mfma_f32_16x16x32_bf16 v[18:21], v[248:251], v[224:227], v[18:21]
	v_mfma_f32_16x16x32_bf16 v[6:9], v[240:243], v[232:235], v[6:9]
	v_mfma_f32_16x16x32_bf16 v[2:5], v[248:251], v[232:235], v[2:5]
	s_barrier
	s_cbranch_scc0 .LBB0_685
	s_lshl_b32 s17, s2, 8
	s_add_i32 s17, s17, s44
	v_or_b32_e32 v152, s17, v1
	s_mov_b32 s2, 0xffff
	v_cmp_lt_i32_e64 s[12:13], s2, v152
	s_and_b32 s2, s17, 0xffffff00
	s_add_i32 s2, s2, 0xffff0000
	s_lshl_b64 s[28:29], s[2:3], 10
	s_ashr_i32 s2, s17, 3
	s_and_b32 s10, s2, 0xffffff00
	s_ashr_i32 s11, s10, 31
	s_lshl_b64 s[26:27], s[10:11], 13
	s_lshl_b32 s24, s48, 8
	s_cmp_gt_i32 s48, 6
	s_cselect_b64 s[30:31], -1, 0
	v_bitop3_b32 v146, s17, v186, v1 bitop3:0xc8
	v_bitop3_b32 v148, s17, v187, v1 bitop3:0xc8
	s_mov_b64 s[10:11], -1
	s_and_b64 vcc, exec, s[30:31]
	s_cbranch_vccz .LBB0_696
	s_and_saveexec_b64 s[10:11], s[12:13]
	s_xor_b64 s[10:11], exec, s[10:11]
	s_add_u32 s34, s54, s28
	s_addc_u32 s35, s55, s29
	s_or_saveexec_b64 s[10:11], s[10:11]
	s_add_i32 s2, s24, 0xfffff900
	v_mov_b64_e32 v[144:145], 0x200
	v_mov_b32_e32 v150, s2
	v_mov_b64_e32 v[154:155], s[34:35]
	v_mov_b64_e32 v[156:157], v[146:147]
	s_xor_b64 exec, exec, s[10:11]
	s_add_u32 s34, s69, s26
	s_addc_u32 s35, s52, s27
	s_lshl_b32 s2, s2, 3
	v_mov_b64_e32 v[144:145], 0x1000
	v_mov_b32_e32 v150, s2
	v_mov_b64_e32 v[154:155], s[34:35]
	v_mov_b64_e32 v[156:157], v[148:149]
	s_or_b64 exec, exec, s[10:11]
	v_ashrrev_i32_e32 v151, 31, v150
	v_lshl_add_u64 v[150:151], v[150:151], 1, v[154:155]
	v_lshlrev_b32_e32 v154, 1, v156
	v_mov_b32_e32 v155, v0
	v_mul_u32_u24_e32 v145, v144, v136
	v_lshl_add_u64 v[150:151], v[150:151], 0, v[154:155]
	v_lshlrev_b32_e32 v154, 1, v145
	v_cvt_pk_bf16_f32 v149, v126, s0
	v_lshl_add_u64 v[154:155], v[150:151], 0, v[154:155]
	v_mul_u32_u24_e32 v147, v144, v166
	global_store_short v[154:155], v149, off
	v_lshlrev_b32_e32 v154, 1, v147
	v_mov_b32_e32 v155, v0
	v_cvt_pk_bf16_f32 v145, v127, s0
	v_lshl_add_u64 v[154:155], v[150:151], 0, v[154:155]
	v_mul_u32_u24_e32 v153, v144, v167
	global_store_short v[154:155], v145, off
	v_lshlrev_b32_e32 v154, 1, v153
	v_mov_b32_e32 v155, v0
	s_cmp_lg_u32 s48, 7
	v_cvt_pk_bf16_f32 v147, v128, s0
	v_lshl_add_u64 v[154:155], v[150:151], 0, v[154:155]
	s_cselect_b64 s[10:11], -1, 0
	global_store_short v[154:155], v147, off
	v_mul_u32_u24_e32 v154, v144, v168
	s_xor_b64 s[34:35], s[14:15], -1
	v_lshlrev_b32_e32 v154, 1, v154
	v_mov_b32_e32 v155, v0
	s_or_b64 s[10:11], s[34:35], s[10:11]
	v_cvt_pk_bf16_f32 v153, v129, s0
	v_lshl_add_u64 v[154:155], v[150:151], 0, v[154:155]
	s_and_b64 vcc, exec, s[10:11]
	global_store_short v[154:155], v153, off
	s_cbranch_vccnz .LBB0_695
	s_and_saveexec_b64 s[10:11], s[4:5]
	s_cbranch_execz .LBB0_694
	v_mul_u32_u24_e32 v154, v144, v158
	v_lshlrev_b32_e32 v154, 1, v154
	v_mov_b32_e32 v155, v0
	v_lshl_add_u64 v[154:155], v[150:151], 0, v[154:155]
	global_store_short v[154:155], v149, off

; #define PG8_STAGE(bufoff, gbase, voff) do { _Pragma("unroll") for (int _i = 0; _i < 2; ++_i) \
;     __builtin_amdgcn_global_load_lds((const unsigned*)((const char*)(gbase) + (voff)[_i]), (PG8_LAS unsigned*)(lds + (bufoff) + ldsw + _i * 8192), 16, 0, 0); } while (0)
; #define PG8_LDA(dst, b, h) do { _Pragma("unroll") for (int m = 0; m < 4; ++m) _Pragma("unroll") for (int k = 0; k < 2; ++k) dst[m][k] = *(const PG8_LAS bf16x8*)(lds + PG8_SA(b, h) + aoff + m * 2048 + k * 1024); } while (0)
; #define PG8_LDB(dst, b, h) do { _Pragma("unroll") for (int n = 0; n < 2; ++n) _Pragma("unroll") for (int k = 0; k < 2; ++k) dst[n][k] = *(const PG8_LAS bf16x8*)(lds + PG8_SB(b, h) + boff + n * 2048 + k * 1024); } while (0)
; #define PG8_MMA(ai, bj, At, Bt) do { __builtin_amdgcn_s_setprio(1); _Pragma("unroll") for (int m = 0; m < 4; ++m) _Pragma("unroll") for (int n = 0; n < 2; ++n) _Pragma("unroll") for (int k = 0; k < 2; ++k) \
;     acc[ai][bj][m][n] = __builtin_amdgcn_mfma_f32_16x16x32_bf16(Bt[n][k], At[m][k], acc[ai][bj][m][n], 0, 0, 0); __builtin_amdgcn_s_setprio(0); } while (0)
; #define PG8_WAIT_L(n) asm volatile("s_waitcnt lgkmcnt(" #n ")" ::: "memory")
; #define PG8_BAR __builtin_amdgcn_s_barrier()
; #define PG8_SCHED __builtin_amdgcn_sched_barrier(0)
; template <class Epi, class Sched>
; __device__ __forceinline__ void gemm_phase(PG8_LAS unsigned char* lds, const int lda, const int ldb, const Sched& S, const Epi& E) {
;     ...
;     for (int t = 0; t < nt; t += 2) {
;       const bool last = (t == nt - 2);
;       const char* a1 = cA + (size_t)(t + 1) * kstep;
;       const char* a2 = last ? nA : cA + (size_t)(t + 2) * kstep; const char* b2 = last ? nB : cB + (size_t)(t + 2) * kstep;
;       const char* a3 = a2 + kstep; const char* b3 = b2 + kstep;
;       PG8_LDB(B0, 0, 0); PG8_SCHED; PG8_LDA(At, 0, 0); PG8_STAGE(PG8_SA(1, 1), a1 + hstepA, voffA);
;       PG8_WAIT_L(8); PG8_BAR; PG8_WAIT_L(0); PG8_MMA(0, 0, At, B0); PG8_BAR; PG8_SCHED;
;       PG8_LDB(B1, 0, 1); PG8_STAGE(PG8_SB(0, 0), b2, voffB);
;       PG8_BAR; PG8_WAIT_L(0); PG8_MMA(0, 1, At, B1); PG8_BAR;
;       PG8_LDA(At, 0, 1); PG8_STAGE(PG8_SA(0, 0), a2, voffA);
;       PG8_BAR; PG8_WAIT_L(0); PG8_MMA(1, 0, At, B0); PG8_BAR; PG8_SCHED;
.LBB0_1088:
	s_add_u32 s16, s14, 0xfff00080
	s_addc_u32 s17, s15, -1
	s_add_i32 s33, 0, 0x10000
	v_add_u32_e32 v145, s33, v1
	ds_read_b128 v[152:155], v145
	ds_read_b128 v[156:159], v145 offset:1024
	ds_read_b128 v[160:163], v145 offset:2048
	ds_read_b128 v[164:167], v145 offset:3072
	s_cmp_eq_u32 s34, 60
	s_cselect_b32 s19, s7, s17
	s_cselect_b32 s18, s13, s16
	s_cselect_b32 s17, s1, s31
	s_cselect_b32 s16, s29, s30
	v_lshl_add_u64 v[182:183], s[14:15], 0, v[140:141]
	s_add_i32 m0, s21, 0xc000
	ds_read_b128 v[168:171], v131
	ds_read_b128 v[172:175], v131 offset:1024
	ds_read_b128 v[200:203], v131 offset:2048
	ds_read_b128 v[204:207], v131 offset:3072
	ds_read_b128 v[208:211], v131 offset:4096
	ds_read_b128 v[212:215], v131 offset:5120
	ds_read_b128 v[216:219], v131 offset:6144
	ds_read_b128 v[220:223], v131 offset:7168
	global_load_lds_dwordx4 v[182:183], off
	v_lshl_add_u64 v[182:183], s[14:15], 0, v[142:143]
	s_add_i32 m0, s21, 0xe000
	s_nop 0
	global_load_lds_dwordx4 v[182:183], off
	s_waitcnt lgkmcnt(8)
	s_barrier
	s_waitcnt lgkmcnt(0)
	v_mfma_f32_16x16x32_bf16 v[126:129], v[152:155], v[168:171], v[126:129]
	v_mfma_f32_16x16x32_bf16 v[122:125], v[160:163], v[168:171], v[122:125]
	v_mfma_f32_16x16x32_bf16 v[118:121], v[152:155], v[200:203], v[118:121]
	v_mfma_f32_16x16x32_bf16 v[114:117], v[160:163], v[200:203], v[114:117]
	v_mfma_f32_16x16x32_bf16 v[102:105], v[152:155], v[208:211], v[102:105]
	v_mfma_f32_16x16x32_bf16 v[98:101], v[160:163], v[208:211], v[98:101]
	v_mfma_f32_16x16x32_bf16 v[86:89], v[152:155], v[216:219], v[86:89]
	v_mfma_f32_16x16x32_bf16 v[82:85], v[160:163], v[216:219], v[82:85]
	v_mfma_f32_16x16x32_bf16 v[126:129], v[156:159], v[172:175], v[126:129]
	v_mfma_f32_16x16x32_bf16 v[122:125], v[164:167], v[172:175], v[122:125]
	v_mfma_f32_16x16x32_bf16 v[118:121], v[156:159], v[204:207], v[118:121]
	v_mfma_f32_16x16x32_bf16 v[114:117], v[164:167], v[204:207], v[114:117]
	v_mfma_f32_16x16x32_bf16 v[102:105], v[156:159], v[212:215], v[102:105]
	v_mfma_f32_16x16x32_bf16 v[98:101], v[164:167], v[212:215], v[98:101]
	v_mfma_f32_16x16x32_bf16 v[86:89], v[156:159], v[220:223], v[86:89]
	v_mfma_f32_16x16x32_bf16 v[82:85], v[164:167], v[220:223], v[82:85]
	s_barrier
	s_add_i32 s35, 0, 0x14000
	s_add_i32 s33, s33, s20
	v_add_u32_e32 v145, s35, v1
	v_lshl_add_u64 v[182:183], s[16:17], 0, v[134:135]
	s_mov_b32 m0, s33
	ds_read_b128 v[224:227], v145
	ds_read_b128 v[228:231], v145 offset:1024
	ds_read_b128 v[232:235], v145 offset:2048
	ds_read_b128 v[236:239], v145 offset:3072
	global_load_lds_dwordx4 v[182:183], off
	v_lshl_add_u64 v[184:185], s[16:17], 0, v[132:133]
	s_add_i32 m0, s33, 0x2000
	s_nop 0
	global_load_lds_dwordx4 v[184:185], off
	s_barrier
	s_waitcnt lgkmcnt(0)
	v_mfma_f32_16x16x32_bf16 v[110:113], v[224:227], v[168:171], v[110:113]
	v_mfma_f32_16x16x32_bf16 v[106:109], v[232:235], v[168:171], v[106:109]
	v_mfma_f32_16x16x32_bf16 v[94:97], v[224:227], v[200:203], v[94:97]
	v_mfma_f32_16x16x32_bf16 v[90:93], v[232:235], v[200:203], v[90:93]
	v_mfma_f32_16x16x32_bf16 v[78:81], v[224:227], v[208:211], v[78:81]
	v_mfma_f32_16x16x32_bf16 v[74:77], v[232:235], v[208:211], v[74:77]
	v_mfma_f32_16x16x32_bf16 v[70:73], v[224:227], v[216:219], v[70:73]
	v_mfma_f32_16x16x32_bf16 v[66:69], v[232:235], v[216:219], v[66:69]
	v_mfma_f32_16x16x32_bf16 v[110:113], v[228:231], v[172:175], v[110:113]
	v_mfma_f32_16x16x32_bf16 v[106:109], v[236:239], v[172:175], v[106:109]
	v_mfma_f32_16x16x32_bf16 v[94:97], v[228:231], v[204:207], v[94:97]
	v_mfma_f32_16x16x32_bf16 v[90:93], v[236:239], v[204:207], v[90:93]
	v_mfma_f32_16x16x32_bf16 v[78:81], v[228:231], v[212:215], v[78:81]
	v_mfma_f32_16x16x32_bf16 v[74:77], v[236:239], v[212:215], v[74:77]
	v_mfma_f32_16x16x32_bf16 v[70:73], v[228:231], v[220:223], v[70:73]
	v_mfma_f32_16x16x32_bf16 v[66:69], v[236:239], v[220:223], v[66:69]
	s_barrier
	s_mov_b32 m0, s21
	v_lshl_add_u64 v[240:241], s[18:19], 0, v[134:135]
	ds_read_b128 v[168:171], v131 offset:16384
	ds_read_b128 v[172:175], v131 offset:17408
	ds_read_b128 v[200:203], v131 offset:18432
	ds_read_b128 v[204:207], v131 offset:19456
	ds_read_b128 v[208:211], v131 offset:20480
	ds_read_b128 v[212:215], v131 offset:21504
	ds_read_b128 v[216:219], v131 offset:22528
	ds_read_b128 v[220:223], v131 offset:23552
	global_load_lds_dwordx4 v[240:241], off
	v_lshl_add_u64 v[242:243], s[18:19], 0, v[132:133]
	s_mov_b32 m0, s22
	s_nop 0
	global_load_lds_dwordx4 v[242:243], off
	s_barrier
	s_waitcnt lgkmcnt(0)
	v_mfma_f32_16x16x32_bf16 v[62:65], v[152:155], v[168:171], v[62:65]
	v_mfma_f32_16x16x32_bf16 v[58:61], v[160:163], v[168:171], v[58:61]
	v_mfma_f32_16x16x32_bf16 v[54:57], v[152:155], v[200:203], v[54:57]
	v_mfma_f32_16x16x32_bf16 v[46:49], v[160:163], v[200:203], v[46:49]
	v_mfma_f32_16x16x32_bf16 v[38:41], v[152:155], v[208:211], v[38:41]
	v_mfma_f32_16x16x32_bf16 v[34:37], v[160:163], v[208:211], v[34:37]
	v_mfma_f32_16x16x32_bf16 v[22:25], v[152:155], v[216:219], v[22:25]
	v_mfma_f32_16x16x32_bf16 v[18:21], v[160:163], v[216:219], v[18:21]
	v_mfma_f32_16x16x32_bf16 v[62:65], v[156:159], v[172:175], v[62:65]
	v_mfma_f32_16x16x32_bf16 v[58:61], v[164:167], v[172:175], v[58:61]
	v_mfma_f32_16x16x32_bf16 v[54:57], v[156:159], v[204:207], v[54:57]
	v_mfma_f32_16x16x32_bf16 v[46:49], v[164:167], v[204:207], v[46:49]
	v_mfma_f32_16x16x32_bf16 v[38:41], v[156:159], v[212:215], v[38:41]
	v_mfma_f32_16x16x32_bf16 v[34:37], v[164:167], v[212:215], v[34:37]
	v_mfma_f32_16x16x32_bf16 v[22:25], v[156:159], v[220:223], v[22:25]
	v_mfma_f32_16x16x32_bf16 v[18:21], v[164:167], v[220:223], v[18:21]
	s_barrier
; #define PG8_STAGE(bufoff, gbase, voff) do { _Pragma("unroll") for (int _i = 0; _i < 2; ++_i) \
;     __builtin_amdgcn_global_load_lds((const unsigned*)((const char*)(gbase) + (voff)[_i]), (PG8_LAS unsigned*)(lds + (bufoff) + ldsw + _i * 8192), 16, 0, 0); } while (0)
; #define PG8_LDA(dst, b, h) do { _Pragma("unroll") for (int m = 0; m < 4; ++m) _Pragma("unroll") for (int k = 0; k < 2; ++k) dst[m][k] = *(const PG8_LAS bf16x8*)(lds + PG8_SA(b, h) + aoff + m * 2048 + k * 1024); } while (0)
; #define PG8_LDB(dst, b, h) do { _Pragma("unroll") for (int n = 0; n < 2; ++n) _Pragma("unroll") for (int k = 0; k < 2; ++k) dst[n][k] = *(const PG8_LAS bf16x8*)(lds + PG8_SB(b, h) + boff + n * 2048 + k * 1024); } while (0)
; #define PG8_MMA(ai, bj, At, Bt) do { __builtin_amdgcn_s_setprio(1); _Pragma("unroll") for (int m = 0; m < 4; ++m) _Pragma("unroll") for (int n = 0; n < 2; ++n) _Pragma("unroll") for (int k = 0; k < 2; ++k) \
;     acc[ai][bj][m][n] = __builtin_amdgcn_mfma_f32_16x16x32_bf16(Bt[n][k], At[m][k], acc[ai][bj][m][n], 0, 0, 0); __builtin_amdgcn_s_setprio(0); } while (0)
; #define PG8_WAIT_V(n) asm volatile("s_waitcnt vmcnt(" #n ")" ::: "memory")
; #define PG8_WAIT_L(n) asm volatile("s_waitcnt lgkmcnt(" #n ")" ::: "memory")
; #define PG8_BAR __builtin_amdgcn_s_barrier()
; #define PG8_SCHED __builtin_amdgcn_sched_barrier(0)
; template <class Epi, class Sched>
; __device__ __forceinline__ void gemm_phase(PG8_LAS unsigned char* lds, const int lda, const int ldb, const Sched& S, const Epi& E) {
;     ...
;       PG8_STAGE(PG8_SB(0, 1), b2 + hstepB, voffB);
;       PG8_WAIT_V(6); PG8_BAR; PG8_MMA(1, 1, At, B1); PG8_BAR;
;       PG8_LDB(B0, 1, 0); PG8_SCHED; PG8_LDA(At, 1, 0); PG8_STAGE(PG8_SA(0, 1), a2 + hstepA, voffA);
;       PG8_WAIT_L(8); PG8_BAR; PG8_WAIT_L(0); PG8_MMA(0, 0, At, B0); PG8_BAR; PG8_SCHED;
;       PG8_LDB(B1, 1, 1); PG8_STAGE(PG8_SB(1, 0), b3, voffB);
;       PG8_BAR; PG8_WAIT_L(0); PG8_MMA(0, 1, At, B1); PG8_BAR;
;       PG8_LDA(At, 1, 1); PG8_STAGE(PG8_SA(1, 0), a3, voffA);
;       PG8_BAR; PG8_WAIT_L(0); PG8_MMA(1, 0, At, B0); PG8_BAR; PG8_SCHED;
	s_add_u32 s36, s16, 0x100000
	s_addc_u32 s37, s17, 0
	s_add_i32 s33, s35, s20
	v_lshl_add_u64 v[152:153], s[36:37], 0, v[134:135]
	s_mov_b32 m0, s33
	s_nop 0
	global_load_lds_dwordx4 v[152:153], off
	v_lshl_add_u64 v[152:153], s[36:37], 0, v[132:133]
	s_add_i32 m0, s33, 0x2000
	s_nop 0
	global_load_lds_dwordx4 v[152:153], off
	s_waitcnt vmcnt(6)
	s_barrier
	v_mfma_f32_16x16x32_bf16 v[50:53], v[224:227], v[168:171], v[50:53]
	v_mfma_f32_16x16x32_bf16 v[42:45], v[232:235], v[168:171], v[42:45]
	v_mfma_f32_16x16x32_bf16 v[30:33], v[224:227], v[200:203], v[30:33]
	v_mfma_f32_16x16x32_bf16 v[26:29], v[232:235], v[200:203], v[26:29]
	v_mfma_f32_16x16x32_bf16 v[14:17], v[224:227], v[208:211], v[14:17]
	v_mfma_f32_16x16x32_bf16 v[10:13], v[232:235], v[208:211], v[10:13]
	v_mfma_f32_16x16x32_bf16 v[6:9], v[224:227], v[216:219], v[6:9]
	v_mfma_f32_16x16x32_bf16 v[2:5], v[232:235], v[216:219], v[2:5]
	v_mfma_f32_16x16x32_bf16 v[50:53], v[228:231], v[172:175], v[50:53]
	v_mfma_f32_16x16x32_bf16 v[42:45], v[236:239], v[172:175], v[42:45]
	v_mfma_f32_16x16x32_bf16 v[30:33], v[228:231], v[204:207], v[30:33]
	v_mfma_f32_16x16x32_bf16 v[26:29], v[236:239], v[204:207], v[26:29]
	v_mfma_f32_16x16x32_bf16 v[14:17], v[228:231], v[212:215], v[14:17]
	v_mfma_f32_16x16x32_bf16 v[10:13], v[236:239], v[212:215], v[10:13]
	v_mfma_f32_16x16x32_bf16 v[6:9], v[228:231], v[220:223], v[6:9]
	v_mfma_f32_16x16x32_bf16 v[2:5], v[236:239], v[220:223], v[2:5]
	s_barrier
	s_add_i32 s33, 0, 0x18000
	v_add_u32_e32 v145, s33, v1
	ds_read_b128 v[152:155], v145
	ds_read_b128 v[156:159], v145 offset:1024
	ds_read_b128 v[160:163], v145 offset:2048
	ds_read_b128 v[164:167], v145 offset:3072
	s_add_u32 s18, s18, 0x100000
	s_addc_u32 s19, s19, 0
	s_mov_b32 m0, s23
	v_lshl_add_u64 v[224:225], s[18:19], 0, v[134:135]
	ds_read_b128 v[168:171], v131 offset:32768
	ds_read_b128 v[172:175], v131 offset:33792
	ds_read_b128 v[200:203], v131 offset:34816
	ds_read_b128 v[204:207], v131 offset:35840
	ds_read_b128 v[208:211], v131 offset:36864
	ds_read_b128 v[212:215], v131 offset:37888
	ds_read_b128 v[216:219], v131 offset:38912
	ds_read_b128 v[220:223], v131 offset:39936
	global_load_lds_dwordx4 v[224:225], off
	v_lshl_add_u64 v[224:225], s[18:19], 0, v[132:133]
	s_mov_b32 m0, s24
	s_nop 0
	global_load_lds_dwordx4 v[224:225], off
	s_waitcnt lgkmcnt(8)
	s_barrier
	s_waitcnt lgkmcnt(0)
	v_mfma_f32_16x16x32_bf16 v[126:129], v[152:155], v[168:171], v[126:129]
	v_mfma_f32_16x16x32_bf16 v[122:125], v[160:163], v[168:171], v[122:125]
	v_mfma_f32_16x16x32_bf16 v[118:121], v[152:155], v[200:203], v[118:121]
	v_mfma_f32_16x16x32_bf16 v[114:117], v[160:163], v[200:203], v[114:117]
	v_mfma_f32_16x16x32_bf16 v[102:105], v[152:155], v[208:211], v[102:105]
	v_mfma_f32_16x16x32_bf16 v[98:101], v[160:163], v[208:211], v[98:101]
	v_mfma_f32_16x16x32_bf16 v[86:89], v[152:155], v[216:219], v[86:89]
	v_mfma_f32_16x16x32_bf16 v[82:85], v[160:163], v[216:219], v[82:85]
	v_mfma_f32_16x16x32_bf16 v[126:129], v[156:159], v[172:175], v[126:129]
	v_mfma_f32_16x16x32_bf16 v[122:125], v[164:167], v[172:175], v[122:125]
	v_mfma_f32_16x16x32_bf16 v[118:121], v[156:159], v[204:207], v[118:121]
	v_mfma_f32_16x16x32_bf16 v[114:117], v[164:167], v[204:207], v[114:117]
	v_mfma_f32_16x16x32_bf16 v[102:105], v[156:159], v[212:215], v[102:105]
	v_mfma_f32_16x16x32_bf16 v[98:101], v[164:167], v[212:215], v[98:101]
	v_mfma_f32_16x16x32_bf16 v[86:89], v[156:159], v[220:223], v[86:89]
	v_mfma_f32_16x16x32_bf16 v[82:85], v[164:167], v[220:223], v[82:85]
	s_barrier
	s_add_i32 s18, 0, 0x1c000
	s_add_i32 s19, s33, s20
	v_add_u32_e32 v145, s18, v1
	v_lshl_add_u64 v[182:183], v[182:183], 0, s[86:87]
	s_mov_b32 m0, s19
	ds_read_b128 v[224:227], v145
	ds_read_b128 v[228:231], v145 offset:1024
	ds_read_b128 v[232:235], v145 offset:2048
	ds_read_b128 v[236:239], v145 offset:3072
	global_load_lds_dwordx4 v[182:183], off
	v_lshl_add_u64 v[182:183], v[184:185], 0, s[86:87]
	s_add_i32 m0, s19, 0x2000
	s_nop 0
	global_load_lds_dwordx4 v[182:183], off
	s_barrier
	s_waitcnt lgkmcnt(0)
	v_mfma_f32_16x16x32_bf16 v[110:113], v[224:227], v[168:171], v[110:113]
	v_mfma_f32_16x16x32_bf16 v[106:109], v[232:235], v[168:171], v[106:109]
	v_mfma_f32_16x16x32_bf16 v[94:97], v[224:227], v[200:203], v[94:97]
	v_mfma_f32_16x16x32_bf16 v[90:93], v[232:235], v[200:203], v[90:93]
	v_mfma_f32_16x16x32_bf16 v[78:81], v[224:227], v[208:211], v[78:81]
	v_mfma_f32_16x16x32_bf16 v[74:77], v[232:235], v[208:211], v[74:77]
	v_mfma_f32_16x16x32_bf16 v[70:73], v[224:227], v[216:219], v[70:73]
	v_mfma_f32_16x16x32_bf16 v[66:69], v[232:235], v[216:219], v[66:69]
	v_mfma_f32_16x16x32_bf16 v[110:113], v[228:231], v[172:175], v[110:113]
	v_mfma_f32_16x16x32_bf16 v[106:109], v[236:239], v[172:175], v[106:109]
	v_mfma_f32_16x16x32_bf16 v[94:97], v[228:231], v[204:207], v[94:97]
	v_mfma_f32_16x16x32_bf16 v[90:93], v[236:239], v[204:207], v[90:93]
	v_mfma_f32_16x16x32_bf16 v[78:81], v[228:231], v[212:215], v[78:81]
	v_mfma_f32_16x16x32_bf16 v[74:77], v[236:239], v[212:215], v[74:77]
	v_mfma_f32_16x16x32_bf16 v[70:73], v[228:231], v[220:223], v[70:73]
	v_mfma_f32_16x16x32_bf16 v[66:69], v[236:239], v[220:223], v[66:69]
	s_barrier
	s_mov_b32 m0, s25
	v_lshl_add_u64 v[182:183], v[240:241], 0, s[86:87]
	ds_read_b128 v[168:171], v131 offset:49152
	ds_read_b128 v[172:175], v131 offset:50176
	ds_read_b128 v[200:203], v131 offset:51200
	ds_read_b128 v[204:207], v131 offset:52224
	ds_read_b128 v[208:211], v131 offset:53248
	ds_read_b128 v[212:215], v131 offset:54272
	ds_read_b128 v[216:219], v131 offset:55296
	ds_read_b128 v[220:223], v131 offset:56320
	global_load_lds_dwordx4 v[182:183], off
	v_lshl_add_u64 v[182:183], v[242:243], 0, s[86:87]
	s_mov_b32 m0, s26
	s_nop 0
	global_load_lds_dwordx4 v[182:183], off
	s_barrier
; #define PG8_STAGE(bufoff, gbase, voff) do { _Pragma("unroll") for (int _i = 0; _i < 2; ++_i) \
;     __builtin_amdgcn_global_load_lds((const unsigned*)((const char*)(gbase) + (voff)[_i]), (PG8_LAS unsigned*)(lds + (bufoff) + ldsw + _i * 8192), 16, 0, 0); } while (0)
; #define PG8_MMA(ai, bj, At, Bt) do { __builtin_amdgcn_s_setprio(1); _Pragma("unroll") for (int m = 0; m < 4; ++m) _Pragma("unroll") for (int n = 0; n < 2; ++n) _Pragma("unroll") for (int k = 0; k < 2; ++k) \
;     acc[ai][bj][m][n] = __builtin_amdgcn_mfma_f32_16x16x32_bf16(Bt[n][k], At[m][k], acc[ai][bj][m][n], 0, 0, 0); __builtin_amdgcn_s_setprio(0); } while (0)
; #define PG8_WAIT_V(n) asm volatile("s_waitcnt vmcnt(" #n ")" ::: "memory")
; #define PG8_WAIT_L(n) asm volatile("s_waitcnt lgkmcnt(" #n ")" ::: "memory")
; #define PG8_BAR __builtin_amdgcn_s_barrier()
; #define PG8_SCHED __builtin_amdgcn_sched_barrier(0)
; template <class Epi, class Sched>
; __device__ __forceinline__ void gemm_phase(PG8_LAS unsigned char* lds, const int lda, const int ldb, const Sched& S, const Epi& E) {
;     ...
;       PG8_BAR; PG8_WAIT_L(0); PG8_MMA(1, 0, At, B0); PG8_BAR; PG8_SCHED;
;       PG8_STAGE(PG8_SB(1, 1), b3 + hstepB, voffB);
;       PG8_WAIT_V(6); PG8_BAR; PG8_MMA(1, 1, At, B1); PG8_BAR;
;     }
	s_waitcnt lgkmcnt(0)
	v_mfma_f32_16x16x32_bf16 v[62:65], v[152:155], v[168:171], v[62:65]
	v_mfma_f32_16x16x32_bf16 v[58:61], v[160:163], v[168:171], v[58:61]
	v_mfma_f32_16x16x32_bf16 v[54:57], v[152:155], v[200:203], v[54:57]
	v_mfma_f32_16x16x32_bf16 v[46:49], v[160:163], v[200:203], v[46:49]
	v_mfma_f32_16x16x32_bf16 v[38:41], v[152:155], v[208:211], v[38:41]
	v_mfma_f32_16x16x32_bf16 v[34:37], v[160:163], v[208:211], v[34:37]
	v_mfma_f32_16x16x32_bf16 v[22:25], v[152:155], v[216:219], v[22:25]
	v_mfma_f32_16x16x32_bf16 v[18:21], v[160:163], v[216:219], v[18:21]
	v_mfma_f32_16x16x32_bf16 v[62:65], v[156:159], v[172:175], v[62:65]
	v_mfma_f32_16x16x32_bf16 v[58:61], v[164:167], v[172:175], v[58:61]
	v_mfma_f32_16x16x32_bf16 v[54:57], v[156:159], v[204:207], v[54:57]
	v_mfma_f32_16x16x32_bf16 v[46:49], v[164:167], v[204:207], v[46:49]
	v_mfma_f32_16x16x32_bf16 v[38:41], v[156:159], v[212:215], v[38:41]
	v_mfma_f32_16x16x32_bf16 v[34:37], v[164:167], v[212:215], v[34:37]
	v_mfma_f32_16x16x32_bf16 v[22:25], v[156:159], v[220:223], v[22:25]
	v_mfma_f32_16x16x32_bf16 v[18:21], v[164:167], v[220:223], v[18:21]
	s_barrier
	s_add_u32 s16, s16, 0x100080
	s_addc_u32 s17, s17, 0
	s_add_i32 s18, s18, s20
	v_lshl_add_u64 v[152:153], s[16:17], 0, v[134:135]
	s_mov_b32 m0, s18
	s_nop 0
	global_load_lds_dwordx4 v[152:153], off
	v_lshl_add_u64 v[152:153], s[16:17], 0, v[132:133]
	s_add_i32 m0, s18, 0x2000
	s_nop 0
	global_load_lds_dwordx4 v[152:153], off
	s_add_i32 s34, s34, 2
	s_add_u32 s14, s14, 0x100
	s_addc_u32 s15, s15, 0
	s_add_u32 s30, s30, 0x100
	s_addc_u32 s31, s31, 0
	s_cmp_gt_u32 s34, 61
	s_waitcnt vmcnt(6)
	s_barrier
	v_mfma_f32_16x16x32_bf16 v[50:53], v[224:227], v[168:171], v[50:53]
	v_mfma_f32_16x16x32_bf16 v[42:45], v[232:235], v[168:171], v[42:45]
	v_mfma_f32_16x16x32_bf16 v[30:33], v[224:227], v[200:203], v[30:33]
	v_mfma_f32_16x16x32_bf16 v[26:29], v[232:235], v[200:203], v[26:29]
	v_mfma_f32_16x16x32_bf16 v[14:17], v[224:227], v[208:211], v[14:17]
	v_mfma_f32_16x16x32_bf16 v[10:13], v[232:235], v[208:211], v[10:13]
	v_mfma_f32_16x16x32_bf16 v[6:9], v[224:227], v[216:219], v[6:9]
	v_mfma_f32_16x16x32_bf16 v[2:5], v[232:235], v[216:219], v[2:5]
	v_mfma_f32_16x16x32_bf16 v[50:53], v[228:231], v[172:175], v[50:53]
	v_mfma_f32_16x16x32_bf16 v[42:45], v[236:239], v[172:175], v[42:45]
	v_mfma_f32_16x16x32_bf16 v[30:33], v[228:231], v[204:207], v[30:33]
	v_mfma_f32_16x16x32_bf16 v[26:29], v[236:239], v[204:207], v[26:29]
	v_mfma_f32_16x16x32_bf16 v[14:17], v[228:231], v[212:215], v[14:17]
	v_mfma_f32_16x16x32_bf16 v[10:13], v[236:239], v[212:215], v[10:13]
	v_mfma_f32_16x16x32_bf16 v[6:9], v[228:231], v[220:223], v[6:9]
	v_mfma_f32_16x16x32_bf16 v[2:5], v[236:239], v[220:223], v[2:5]
	s_barrier
	s_cbranch_scc0 .LBB0_1088
;   __device__ __forceinline__ int kt(const Unit& u) const { return ((u.pn & 7) < 4) ? 4 : 16; }
; template <class Epi, class Sched>
; __device__ __forceinline__ void gemm_phase(PG8_LAS unsigned char* lds, const int lda, const int ldb, const Sched& S, const Epi& E) {
;     ...
;     E(acc, cur, wr, wc, fr, fq);
;     if (!has_next) break;
; #pragma unroll
;     for (int a = 0; a < 2; ++a)
; #pragma unroll
;       for (int b = 0; b < 2; ++b)
; #pragma unroll
;         for (int m = 0; m < 4; ++m)
; #pragma unroll
;           for (int n = 0; n < 2; ++n) acc[a][b][m][n] = (f32x4){0.f, 0.f, 0.f, 0.f};
;     cur = nxt; cA = nA; cB = nB; ++ui;
;     nt = S.kt(cur);
;   __device__ __forceinline__ void operator()(const f32x4 (&acc)[2][2][4][2], const Unit& u, int wr, int wc, int fr, int fq) const {
; #pragma unroll
;     for (int ai = 0; ai < 2; ++ai)
; #pragma unroll
;       for (int m = 0; m < 4; ++m) {
;         const size_t r = (size_t)rowbase + (size_t)u.pn * rows_per_b + u.pm * 256 + ai * 128 + wr * 64 + m * 16 + fr;
; #pragma unroll
;         for (int bj = 0; bj < 2; ++bj)
; #pragma unroll
;           for (int n = 0; n < 2; ++n) {
;             const f32x4 v = acc[ai][bj][m][n];
;             const int c = 256 + bj * 128 + wc * 32 + n * 16 + 4 * fq;
;             uint2 w; w.x = pack2(v[0], v[1]); w.y = pack2(v[2], v[3]);
;             *reinterpret_cast<uint2*>(Y + r * 1024 + c) = w;
;           }
;       }
;   }
	s_lshl_b32 s14, s28, 8
	s_ashr_i32 s15, s14, 31
	s_ashr_i32 s13, s12, 31
	v_lshl_add_u64 v[152:153], v[136:137], 0, s[14:15]
	s_lshl_b64 s[12:13], s[12:13], 22
	v_lshlrev_b64 v[152:153], 11, v[152:153]
	v_lshl_add_u64 v[152:153], v[152:153], 0, s[12:13]
	v_readlane_b32 s12, v253, 54
	v_readlane_b32 s13, v253, 55
	v_mov_b32_e32 v145, v0
	v_cvt_pk_bf16_f32 v109, v108, v109
	v_lshl_add_u64 v[154:155], s[12:13], 0, v[152:153]
	v_lshl_add_u64 v[156:157], v[154:155], 0, v[144:145]
	v_cvt_pk_bf16_f32 v108, v106, v107
	v_or_b32_e32 v106, 0x8000, v152
	v_mov_b32_e32 v107, v153
	s_mov_b64 s[12:13], 0x40000
	v_cvt_pk_bf16_f32 v129, v128, v129
	v_cvt_pk_bf16_f32 v128, v126, v127
	v_cvt_pk_bf16_f32 v125, v124, v125
	v_cvt_pk_bf16_f32 v124, v122, v123
	v_cvt_pk_bf16_f32 v113, v112, v113
	v_cvt_pk_bf16_f32 v112, v110, v111
	global_store_dwordx2 v[156:157], v[108:109], off offset:800
	v_lshl_add_u64 v[106:107], v[138:139], 0, v[106:107]
	v_cvt_pk_bf16_f32 v109, v120, v121
	v_cvt_pk_bf16_f32 v108, v118, v119
	v_cvt_pk_bf16_f32 v93, v92, v93
	v_cvt_pk_bf16_f32 v92, v90, v91
	v_or_b32_e32 v90, 0x10000, v152
	v_mov_b32_e32 v91, v153
	v_cvt_pk_bf16_f32 v69, v68, v69
	v_cvt_pk_bf16_f32 v68, v66, v67
	v_lshl_add_u64 v[66:67], v[154:155], 0, s[12:13]
	s_mov_b64 s[12:13], 0x48000
	global_store_dwordx2 v[156:157], v[128:129], off offset:512
	global_store_dwordx2 v[156:157], v[124:125], off offset:544
	global_store_dwordx2 v[156:157], v[112:113], off offset:768
	global_store_dwordx2 v[106:107], v[108:109], off offset:512
	v_cvt_pk_bf16_f32 v109, v116, v117
	v_cvt_pk_bf16_f32 v108, v114, v115
	v_cvt_pk_bf16_f32 v97, v96, v97
	v_cvt_pk_bf16_f32 v96, v94, v95
	global_store_dwordx2 v[106:107], v[92:93], off offset:800
	v_lshl_add_u64 v[90:91], v[138:139], 0, v[90:91]
	v_cvt_pk_bf16_f32 v93, v104, v105
	v_cvt_pk_bf16_f32 v92, v102, v103
	v_cvt_pk_bf16_f32 v77, v76, v77
	v_cvt_pk_bf16_f32 v76, v74, v75
	v_or_b32_e32 v152, 0x18000, v152
	v_cvt_pk_bf16_f32 v45, v44, v45
	v_cvt_pk_bf16_f32 v44, v42, v43
	v_lshl_add_u64 v[42:43], v[154:155], 0, s[12:13]
	s_mov_b64 s[12:13], 0x50000
	global_store_dwordx2 v[106:107], v[108:109], off offset:544
	global_store_dwordx2 v[106:107], v[96:97], off offset:768
	global_store_dwordx2 v[90:91], v[92:93], off offset:512
	v_cvt_pk_bf16_f32 v93, v100, v101
	v_cvt_pk_bf16_f32 v92, v98, v99
	v_cvt_pk_bf16_f32 v81, v80, v81
	v_cvt_pk_bf16_f32 v80, v78, v79
	global_store_dwordx2 v[90:91], v[76:77], off offset:800
	v_lshl_add_u64 v[74:75], v[138:139], 0, v[152:153]
	v_cvt_pk_bf16_f32 v77, v88, v89
	v_cvt_pk_bf16_f32 v76, v86, v87
	v_mov_b32_e32 v151, v0
	v_cvt_pk_bf16_f32 v29, v28, v29
	v_cvt_pk_bf16_f32 v28, v26, v27
	v_lshl_add_u64 v[26:27], v[154:155], 0, s[12:13]
	s_mov_b64 s[12:13], 0x58000
	global_store_dwordx2 v[90:91], v[92:93], off offset:544
	global_store_dwordx2 v[90:91], v[80:81], off offset:768
	global_store_dwordx2 v[74:75], v[76:77], off offset:512
	v_cvt_pk_bf16_f32 v77, v84, v85
	v_cvt_pk_bf16_f32 v76, v82, v83
	v_cvt_pk_bf16_f32 v73, v72, v73
	v_cvt_pk_bf16_f32 v72, v70, v71
	v_cvt_pk_bf16_f32 v53, v52, v53
	v_cvt_pk_bf16_f32 v52, v50, v51
	v_lshl_add_u64 v[50:51], v[66:67], 0, v[150:151]
	v_cvt_pk_bf16_f32 v33, v32, v33
	v_cvt_pk_bf16_f32 v32, v30, v31
	v_lshl_add_u64 v[30:31], v[42:43], 0, v[150:151]
	v_cvt_pk_bf16_f32 v17, v16, v17
	v_cvt_pk_bf16_f32 v16, v14, v15
	v_lshl_add_u64 v[14:15], v[26:27], 0, v[150:151]
	v_cvt_pk_bf16_f32 v13, v12, v13
	v_cvt_pk_bf16_f32 v12, v10, v11
	v_lshl_add_u64 v[10:11], v[154:155], 0, s[12:13]
	global_store_dwordx2 v[74:75], v[76:77], off offset:544
	global_store_dwordx2 v[74:75], v[72:73], off offset:768
	global_store_dwordx2 v[74:75], v[68:69], off offset:800
	v_mov_b32_e32 v147, v0
	global_store_dwordx2 v[50:51], v[44:45], off offset:512
	v_lshl_add_u64 v[44:45], v[42:43], 0, v[144:145]
	v_cvt_pk_bf16_f32 v51, v56, v57
	v_cvt_pk_bf16_f32 v50, v54, v55
	global_store_dwordx2 v[30:31], v[28:29], off offset:512
	v_lshl_add_u64 v[28:29], v[26:27], 0, v[144:145]
	v_cvt_pk_bf16_f32 v31, v40, v41
	v_cvt_pk_bf16_f32 v30, v38, v39
	global_store_dwordx2 v[14:15], v[12:13], off offset:512
	v_lshl_add_u64 v[12:13], v[10:11], 0, v[144:145]
	v_cvt_pk_bf16_f32 v15, v24, v25
	v_cvt_pk_bf16_f32 v14, v22, v23
	v_mov_b32_e32 v149, v0
	global_store_dwordx2 v[44:45], v[50:51], off offset:512
	v_lshl_add_u64 v[44:45], v[42:43], 0, v[146:147]
	v_cvt_pk_bf16_f32 v49, v48, v49
	v_cvt_pk_bf16_f32 v48, v46, v47
	global_store_dwordx2 v[28:29], v[30:31], off offset:512
	v_lshl_add_u64 v[28:29], v[26:27], 0, v[146:147]
	v_cvt_pk_bf16_f32 v31, v36, v37
	v_cvt_pk_bf16_f32 v30, v34, v35
	global_store_dwordx2 v[12:13], v[14:15], off offset:512
	v_lshl_add_u64 v[12:13], v[10:11], 0, v[146:147]
	v_cvt_pk_bf16_f32 v15, v20, v21
	v_cvt_pk_bf16_f32 v14, v18, v19
	v_lshl_add_u64 v[68:69], v[66:67], 0, v[144:145]
	v_cvt_pk_bf16_f32 v65, v64, v65
	v_cvt_pk_bf16_f32 v64, v62, v63
	v_lshl_add_u64 v[62:63], v[66:67], 0, v[146:147]
	v_cvt_pk_bf16_f32 v61, v60, v61
	v_cvt_pk_bf16_f32 v60, v58, v59
	v_lshl_add_u64 v[58:59], v[66:67], 0, v[148:149]
	global_store_dwordx2 v[44:45], v[48:49], off offset:512
	v_lshl_add_u64 v[44:45], v[42:43], 0, v[148:149]
	global_store_dwordx2 v[28:29], v[30:31], off offset:512
	v_lshl_add_u64 v[28:29], v[26:27], 0, v[148:149]
	global_store_dwordx2 v[12:13], v[14:15], off offset:512
	v_lshl_add_u64 v[12:13], v[10:11], 0, v[148:149]
	v_cvt_pk_bf16_f32 v9, v8, v9
	v_cvt_pk_bf16_f32 v8, v6, v7
	v_lshl_add_u64 v[6:7], v[10:11], 0, v[150:151]
	v_cvt_pk_bf16_f32 v5, v4, v5
	v_cvt_pk_bf16_f32 v4, v2, v3
	s_and_b64 vcc, exec, s[4:5]
	s_mov_b32 s12, s0
	s_mov_b32 s28, s6
	s_mov_b64 s[16:17], s[10:11]
	s_mov_b64 s[14:15], s[8:9]
	global_store_dwordx2 v[68:69], v[64:65], off offset:512
	global_store_dwordx2 v[62:63], v[60:61], off offset:512
	global_store_dwordx2 v[58:59], v[52:53], off offset:512
	global_store_dwordx2 v[44:45], v[32:33], off offset:512
	global_store_dwordx2 v[28:29], v[16:17], off offset:512
	global_store_dwordx2 v[12:13], v[8:9], off offset:512
	global_store_dwordx2 v[6:7], v[4:5], off offset:512
	s_cbranch_vccz .LBB0_1081
	s_waitcnt vmcnt(0)
	s_cmpk_gt_u32 s2, 0xff
	s_movk_i32 s21, 0x210
	s_mov_b32 s26, 0x2aaaaaab
	s_movk_i32 s27, 0xff40
	s_cbranch_scc1 .LBB0_1092
	s_barrier

; #define PG8_STAGE(bufoff, gbase, voff) do { _Pragma("unroll") for (int _i = 0; _i < 2; ++_i) \
;     __builtin_amdgcn_global_load_lds((const unsigned*)((const char*)(gbase) + (voff)[_i]), (PG8_LAS unsigned*)(lds + (bufoff) + ldsw + _i * 8192), 16, 0, 0); } while (0)
; #define PG8_LDA(dst, b, h) do { _Pragma("unroll") for (int m = 0; m < 4; ++m) _Pragma("unroll") for (int k = 0; k < 2; ++k) dst[m][k] = *(const PG8_LAS bf16x8*)(lds + PG8_SA(b, h) + aoff + m * 2048 + k * 1024); } while (0)
; #define PG8_LDB(dst, b, h) do { _Pragma("unroll") for (int n = 0; n < 2; ++n) _Pragma("unroll") for (int k = 0; k < 2; ++k) dst[n][k] = *(const PG8_LAS bf16x8*)(lds + PG8_SB(b, h) + boff + n * 2048 + k * 1024); } while (0)
; #define PG8_MMA(ai, bj, At, Bt) do { __builtin_amdgcn_s_setprio(1); _Pragma("unroll") for (int m = 0; m < 4; ++m) _Pragma("unroll") for (int n = 0; n < 2; ++n) _Pragma("unroll") for (int k = 0; k < 2; ++k) \
;     acc[ai][bj][m][n] = __builtin_amdgcn_mfma_f32_16x16x32_bf16(Bt[n][k], At[m][k], acc[ai][bj][m][n], 0, 0, 0); __builtin_amdgcn_s_setprio(0); } while (0)
; #define PG8_WAIT_L(n) asm volatile("s_waitcnt lgkmcnt(" #n ")" ::: "memory")
; #define PG8_BAR __builtin_amdgcn_s_barrier()
; #define PG8_SCHED __builtin_amdgcn_sched_barrier(0)
; template <class Epi, class Sched>
; __device__ __forceinline__ void gemm_phase(PG8_LAS unsigned char* lds, const int lda, const int ldb, const Sched& S, const Epi& E) {
;     ...
;     for (int t = 0; t < nt; t += 2) {
;       const bool last = (t == nt - 2);
;       const char* a1 = cA + (size_t)(t + 1) * kstep;
;       const char* a2 = last ? nA : cA + (size_t)(t + 2) * kstep; const char* b2 = last ? nB : cB + (size_t)(t + 2) * kstep;
;       const char* a3 = a2 + kstep; const char* b3 = b2 + kstep;
;       PG8_LDB(B0, 0, 0); PG8_SCHED; PG8_LDA(At, 0, 0); PG8_STAGE(PG8_SA(1, 1), a1 + hstepA, voffA);
;       PG8_WAIT_L(8); PG8_BAR; PG8_WAIT_L(0); PG8_MMA(0, 0, At, B0); PG8_BAR; PG8_SCHED;
;       PG8_LDB(B1, 0, 1); PG8_STAGE(PG8_SB(0, 0), b2, voffB);
;       PG8_BAR; PG8_WAIT_L(0); PG8_MMA(0, 1, At, B1); PG8_BAR;
;       PG8_LDA(At, 0, 1); PG8_STAGE(PG8_SA(0, 0), a2, voffA);
;       PG8_BAR; PG8_WAIT_L(0); PG8_MMA(1, 0, At, B0); PG8_BAR; PG8_SCHED;
.LBB0_1482:
	s_add_u32 s20, s18, 0x100
	s_addc_u32 s21, s19, 0
	s_add_i32 s33, 0, 0x10000
	v_add_u32_e32 v154, s33, v131
	ds_read_b128 v[140:143], v154
	ds_read_b128 v[146:149], v154 offset:1024
	ds_read_b128 v[150:153], v154 offset:2048
	ds_read_b128 v[154:157], v154 offset:3072
	s_cmp_eq_u32 s54, 12
	s_cselect_b32 s25, s11, s21
	s_cselect_b32 s24, s50, s20
	s_cselect_b32 s23, s1, s53
	s_cselect_b32 s22, s51, s52
	v_lshl_add_u64 v[174:175], s[18:19], 0, v[136:137]
	s_add_i32 m0, s17, 0xc000
	ds_read_b128 v[158:161], v145
	ds_read_b128 v[162:165], v145 offset:1024
	ds_read_b128 v[166:169], v145 offset:2048
	ds_read_b128 v[170:173], v145 offset:3072
	ds_read_b128 v[200:203], v145 offset:4096
	ds_read_b128 v[204:207], v145 offset:5120
	ds_read_b128 v[208:211], v145 offset:6144
	ds_read_b128 v[212:215], v145 offset:7168
	global_load_lds_dwordx4 v[174:175], off
	v_lshl_add_u64 v[174:175], s[18:19], 0, v[138:139]
	s_add_i32 m0, s17, 0xe000
	s_nop 0
	global_load_lds_dwordx4 v[174:175], off
	s_waitcnt lgkmcnt(8)
	s_barrier
	s_waitcnt lgkmcnt(0)
	v_mfma_f32_16x16x32_bf16 v[126:129], v[140:143], v[158:161], v[126:129]
	v_mfma_f32_16x16x32_bf16 v[122:125], v[150:153], v[158:161], v[122:125]
	v_mfma_f32_16x16x32_bf16 v[110:113], v[140:143], v[166:169], v[110:113]
	v_mfma_f32_16x16x32_bf16 v[106:109], v[150:153], v[166:169], v[106:109]
	v_mfma_f32_16x16x32_bf16 v[94:97], v[140:143], v[200:203], v[94:97]
	v_mfma_f32_16x16x32_bf16 v[90:93], v[150:153], v[200:203], v[90:93]
	v_mfma_f32_16x16x32_bf16 v[78:81], v[140:143], v[208:211], v[78:81]
	v_mfma_f32_16x16x32_bf16 v[74:77], v[150:153], v[208:211], v[74:77]
	v_mfma_f32_16x16x32_bf16 v[126:129], v[146:149], v[162:165], v[126:129]
	v_mfma_f32_16x16x32_bf16 v[122:125], v[154:157], v[162:165], v[122:125]
	v_mfma_f32_16x16x32_bf16 v[110:113], v[146:149], v[170:173], v[110:113]
	v_mfma_f32_16x16x32_bf16 v[106:109], v[154:157], v[170:173], v[106:109]
	v_mfma_f32_16x16x32_bf16 v[94:97], v[146:149], v[204:207], v[94:97]
	v_mfma_f32_16x16x32_bf16 v[90:93], v[154:157], v[204:207], v[90:93]
	v_mfma_f32_16x16x32_bf16 v[78:81], v[146:149], v[212:215], v[78:81]
	v_mfma_f32_16x16x32_bf16 v[74:77], v[154:157], v[212:215], v[74:77]
	s_barrier
	s_add_i32 s55, 0, 0x14000
	v_add_u32_e32 v174, s55, v131
	s_add_i32 s18, s33, s34
	ds_read_b128 v[216:219], v174
	ds_read_b128 v[220:223], v174 offset:1024
	ds_read_b128 v[224:227], v174 offset:2048
	ds_read_b128 v[228:231], v174 offset:3072
	v_lshl_add_u64 v[174:175], s[22:23], 0, v[134:135]
	s_mov_b32 m0, s18
	v_lshl_add_u64 v[182:183], s[22:23], 0, v[132:133]
	global_load_lds_dwordx4 v[174:175], off
	s_add_i32 m0, s18, 0x2000
	s_nop 0
	global_load_lds_dwordx4 v[182:183], off
	s_barrier
	s_waitcnt lgkmcnt(0)
	v_mfma_f32_16x16x32_bf16 v[118:121], v[216:219], v[158:161], v[118:121]
	v_mfma_f32_16x16x32_bf16 v[114:117], v[224:227], v[158:161], v[114:117]
	v_mfma_f32_16x16x32_bf16 v[102:105], v[216:219], v[166:169], v[102:105]
	v_mfma_f32_16x16x32_bf16 v[98:101], v[224:227], v[166:169], v[98:101]
	v_mfma_f32_16x16x32_bf16 v[86:89], v[216:219], v[200:203], v[86:89]
	v_mfma_f32_16x16x32_bf16 v[82:85], v[224:227], v[200:203], v[82:85]
	v_mfma_f32_16x16x32_bf16 v[70:73], v[216:219], v[208:211], v[70:73]
	v_mfma_f32_16x16x32_bf16 v[66:69], v[224:227], v[208:211], v[66:69]
	v_mfma_f32_16x16x32_bf16 v[118:121], v[220:223], v[162:165], v[118:121]
	v_mfma_f32_16x16x32_bf16 v[114:117], v[228:231], v[162:165], v[114:117]
	v_mfma_f32_16x16x32_bf16 v[102:105], v[220:223], v[170:173], v[102:105]
	v_mfma_f32_16x16x32_bf16 v[98:101], v[228:231], v[170:173], v[98:101]
	v_mfma_f32_16x16x32_bf16 v[86:89], v[220:223], v[204:207], v[86:89]
	v_mfma_f32_16x16x32_bf16 v[82:85], v[228:231], v[204:207], v[82:85]
	v_mfma_f32_16x16x32_bf16 v[70:73], v[220:223], v[212:215], v[70:73]
	v_mfma_f32_16x16x32_bf16 v[66:69], v[228:231], v[212:215], v[66:69]
	s_barrier
	s_mov_b32 m0, s17
	v_lshl_add_u64 v[184:185], s[24:25], 0, v[134:135]
	ds_read_b128 v[158:161], v145 offset:16384
	ds_read_b128 v[162:165], v145 offset:17408
	ds_read_b128 v[166:169], v145 offset:18432
	ds_read_b128 v[170:173], v145 offset:19456
	ds_read_b128 v[200:203], v145 offset:20480
	ds_read_b128 v[204:207], v145 offset:21504
	ds_read_b128 v[208:211], v145 offset:22528
	ds_read_b128 v[212:215], v145 offset:23552
	global_load_lds_dwordx4 v[184:185], off
	v_lshl_add_u64 v[232:233], s[24:25], 0, v[132:133]
	s_mov_b32 m0, s37
	s_nop 0
	global_load_lds_dwordx4 v[232:233], off
	s_barrier
	s_waitcnt lgkmcnt(0)
	v_mfma_f32_16x16x32_bf16 v[62:65], v[140:143], v[158:161], v[62:65]
	v_mfma_f32_16x16x32_bf16 v[58:61], v[150:153], v[158:161], v[58:61]
	v_mfma_f32_16x16x32_bf16 v[46:49], v[140:143], v[166:169], v[46:49]
	v_mfma_f32_16x16x32_bf16 v[42:45], v[150:153], v[166:169], v[42:45]
	v_mfma_f32_16x16x32_bf16 v[30:33], v[140:143], v[200:203], v[30:33]
	v_mfma_f32_16x16x32_bf16 v[26:29], v[150:153], v[200:203], v[26:29]
	v_mfma_f32_16x16x32_bf16 v[14:17], v[140:143], v[208:211], v[14:17]
	v_mfma_f32_16x16x32_bf16 v[10:13], v[150:153], v[208:211], v[10:13]
	v_mfma_f32_16x16x32_bf16 v[62:65], v[146:149], v[162:165], v[62:65]
	v_mfma_f32_16x16x32_bf16 v[58:61], v[154:157], v[162:165], v[58:61]
	v_mfma_f32_16x16x32_bf16 v[46:49], v[146:149], v[170:173], v[46:49]
	v_mfma_f32_16x16x32_bf16 v[42:45], v[154:157], v[170:173], v[42:45]
	v_mfma_f32_16x16x32_bf16 v[30:33], v[146:149], v[204:207], v[30:33]
	v_mfma_f32_16x16x32_bf16 v[26:29], v[154:157], v[204:207], v[26:29]
	v_mfma_f32_16x16x32_bf16 v[14:17], v[146:149], v[212:215], v[14:17]
	v_mfma_f32_16x16x32_bf16 v[10:13], v[154:157], v[212:215], v[10:13]
	s_barrier
; #define PG8_STAGE(bufoff, gbase, voff) do { _Pragma("unroll") for (int _i = 0; _i < 2; ++_i) \
;     __builtin_amdgcn_global_load_lds((const unsigned*)((const char*)(gbase) + (voff)[_i]), (PG8_LAS unsigned*)(lds + (bufoff) + ldsw + _i * 8192), 16, 0, 0); } while (0)
; #define PG8_LDA(dst, b, h) do { _Pragma("unroll") for (int m = 0; m < 4; ++m) _Pragma("unroll") for (int k = 0; k < 2; ++k) dst[m][k] = *(const PG8_LAS bf16x8*)(lds + PG8_SA(b, h) + aoff + m * 2048 + k * 1024); } while (0)
; #define PG8_LDB(dst, b, h) do { _Pragma("unroll") for (int n = 0; n < 2; ++n) _Pragma("unroll") for (int k = 0; k < 2; ++k) dst[n][k] = *(const PG8_LAS bf16x8*)(lds + PG8_SB(b, h) + boff + n * 2048 + k * 1024); } while (0)
; #define PG8_MMA(ai, bj, At, Bt) do { __builtin_amdgcn_s_setprio(1); _Pragma("unroll") for (int m = 0; m < 4; ++m) _Pragma("unroll") for (int n = 0; n < 2; ++n) _Pragma("unroll") for (int k = 0; k < 2; ++k) \
;     acc[ai][bj][m][n] = __builtin_amdgcn_mfma_f32_16x16x32_bf16(Bt[n][k], At[m][k], acc[ai][bj][m][n], 0, 0, 0); __builtin_amdgcn_s_setprio(0); } while (0)
; #define PG8_WAIT_V(n) asm volatile("s_waitcnt vmcnt(" #n ")" ::: "memory")
; #define PG8_WAIT_L(n) asm volatile("s_waitcnt lgkmcnt(" #n ")" ::: "memory")
; #define PG8_BAR __builtin_amdgcn_s_barrier()
; #define PG8_SCHED __builtin_amdgcn_sched_barrier(0)
; template <class Epi, class Sched>
; __device__ __forceinline__ void gemm_phase(PG8_LAS unsigned char* lds, const int lda, const int ldb, const Sched& S, const Epi& E) {
;     ...
;       PG8_STAGE(PG8_SB(0, 1), b2 + hstepB, voffB);
;       PG8_WAIT_V(6); PG8_BAR; PG8_MMA(1, 1, At, B1); PG8_BAR;
;       PG8_LDB(B0, 1, 0); PG8_SCHED; PG8_LDA(At, 1, 0); PG8_STAGE(PG8_SA(0, 1), a2 + hstepA, voffA);
;       PG8_WAIT_L(8); PG8_BAR; PG8_WAIT_L(0); PG8_MMA(0, 0, At, B0); PG8_BAR; PG8_SCHED;
;       PG8_LDB(B1, 1, 1); PG8_STAGE(PG8_SB(1, 0), b3, voffB);
;       PG8_BAR; PG8_WAIT_L(0); PG8_MMA(0, 1, At, B1); PG8_BAR;
;       PG8_LDA(At, 1, 1); PG8_STAGE(PG8_SA(1, 0), a3, voffA);
	s_add_u32 s18, s22, 0x40000
	s_addc_u32 s19, s23, 0
	s_add_i32 s33, s55, s34
	v_lshl_add_u64 v[140:141], s[18:19], 0, v[134:135]
	s_mov_b32 m0, s33
	s_nop 0
	global_load_lds_dwordx4 v[140:141], off
	v_lshl_add_u64 v[140:141], s[18:19], 0, v[132:133]
	s_add_i32 m0, s33, 0x2000
	s_nop 0
	global_load_lds_dwordx4 v[140:141], off
	s_waitcnt vmcnt(6)
	s_barrier
	v_mfma_f32_16x16x32_bf16 v[54:57], v[216:219], v[158:161], v[54:57]
	v_mfma_f32_16x16x32_bf16 v[50:53], v[224:227], v[158:161], v[50:53]
	v_mfma_f32_16x16x32_bf16 v[38:41], v[216:219], v[166:169], v[38:41]
	v_mfma_f32_16x16x32_bf16 v[34:37], v[224:227], v[166:169], v[34:37]
	v_mfma_f32_16x16x32_bf16 v[22:25], v[216:219], v[200:203], v[22:25]
	v_mfma_f32_16x16x32_bf16 v[18:21], v[224:227], v[200:203], v[18:21]
	v_mfma_f32_16x16x32_bf16 v[6:9], v[216:219], v[208:211], v[6:9]
	v_mfma_f32_16x16x32_bf16 v[2:5], v[224:227], v[208:211], v[2:5]
	v_mfma_f32_16x16x32_bf16 v[54:57], v[220:223], v[162:165], v[54:57]
	v_mfma_f32_16x16x32_bf16 v[50:53], v[228:231], v[162:165], v[50:53]
	v_mfma_f32_16x16x32_bf16 v[38:41], v[220:223], v[170:173], v[38:41]
	v_mfma_f32_16x16x32_bf16 v[34:37], v[228:231], v[170:173], v[34:37]
	v_mfma_f32_16x16x32_bf16 v[22:25], v[220:223], v[204:207], v[22:25]
	v_mfma_f32_16x16x32_bf16 v[18:21], v[228:231], v[204:207], v[18:21]
	v_mfma_f32_16x16x32_bf16 v[6:9], v[220:223], v[212:215], v[6:9]
	v_mfma_f32_16x16x32_bf16 v[2:5], v[228:231], v[212:215], v[2:5]
	s_barrier
	s_add_i32 s33, 0, 0x18000
	v_add_u32_e32 v154, s33, v131
	ds_read_b128 v[140:143], v154
	ds_read_b128 v[146:149], v154 offset:1024
	ds_read_b128 v[150:153], v154 offset:2048
	ds_read_b128 v[154:157], v154 offset:3072
	s_add_u32 s18, s24, 0x40000
	s_addc_u32 s19, s25, 0
	s_mov_b32 m0, s38
	v_lshl_add_u64 v[216:217], s[18:19], 0, v[134:135]
	ds_read_b128 v[158:161], v145 offset:32768
	ds_read_b128 v[162:165], v145 offset:33792
	ds_read_b128 v[166:169], v145 offset:34816
	ds_read_b128 v[170:173], v145 offset:35840
	ds_read_b128 v[200:203], v145 offset:36864
	ds_read_b128 v[204:207], v145 offset:37888
	ds_read_b128 v[208:211], v145 offset:38912
	ds_read_b128 v[212:215], v145 offset:39936
	global_load_lds_dwordx4 v[216:217], off
	v_lshl_add_u64 v[216:217], s[18:19], 0, v[132:133]
	s_mov_b32 m0, s39
	s_nop 0
	global_load_lds_dwordx4 v[216:217], off
	s_waitcnt lgkmcnt(8)
	s_barrier
	s_waitcnt lgkmcnt(0)
	v_mfma_f32_16x16x32_bf16 v[126:129], v[140:143], v[158:161], v[126:129]
	v_mfma_f32_16x16x32_bf16 v[122:125], v[150:153], v[158:161], v[122:125]
	v_mfma_f32_16x16x32_bf16 v[110:113], v[140:143], v[166:169], v[110:113]
	v_mfma_f32_16x16x32_bf16 v[106:109], v[150:153], v[166:169], v[106:109]
	v_mfma_f32_16x16x32_bf16 v[94:97], v[140:143], v[200:203], v[94:97]
	v_mfma_f32_16x16x32_bf16 v[90:93], v[150:153], v[200:203], v[90:93]
	v_mfma_f32_16x16x32_bf16 v[78:81], v[140:143], v[208:211], v[78:81]
	v_mfma_f32_16x16x32_bf16 v[74:77], v[150:153], v[208:211], v[74:77]
	v_mfma_f32_16x16x32_bf16 v[126:129], v[146:149], v[162:165], v[126:129]
	v_mfma_f32_16x16x32_bf16 v[122:125], v[154:157], v[162:165], v[122:125]
	v_mfma_f32_16x16x32_bf16 v[110:113], v[146:149], v[170:173], v[110:113]
	v_mfma_f32_16x16x32_bf16 v[106:109], v[154:157], v[170:173], v[106:109]
	v_mfma_f32_16x16x32_bf16 v[94:97], v[146:149], v[204:207], v[94:97]
	v_mfma_f32_16x16x32_bf16 v[90:93], v[154:157], v[204:207], v[90:93]
	v_mfma_f32_16x16x32_bf16 v[78:81], v[146:149], v[212:215], v[78:81]
	v_mfma_f32_16x16x32_bf16 v[74:77], v[154:157], v[212:215], v[74:77]
	s_barrier
	s_add_i32 s24, 0, 0x1c000
	s_add_i32 s18, s33, s34
	v_add_u32_e32 v228, s24, v131
	v_lshl_add_u64 v[174:175], v[174:175], 0, s[86:87]
	s_mov_b32 m0, s18
	ds_read_b128 v[216:219], v228
	ds_read_b128 v[220:223], v228 offset:1024
	ds_read_b128 v[224:227], v228 offset:2048
	ds_read_b128 v[228:231], v228 offset:3072
	global_load_lds_dwordx4 v[174:175], off
	v_lshl_add_u64 v[174:175], v[182:183], 0, s[86:87]
	s_add_i32 m0, s18, 0x2000
	s_nop 0
	global_load_lds_dwordx4 v[174:175], off
	s_barrier
; #define PG8_STAGE(bufoff, gbase, voff) do { _Pragma("unroll") for (int _i = 0; _i < 2; ++_i) \
;     __builtin_amdgcn_global_load_lds((const unsigned*)((const char*)(gbase) + (voff)[_i]), (PG8_LAS unsigned*)(lds + (bufoff) + ldsw + _i * 8192), 16, 0, 0); } while (0)
; #define PG8_MMA(ai, bj, At, Bt) do { __builtin_amdgcn_s_setprio(1); _Pragma("unroll") for (int m = 0; m < 4; ++m) _Pragma("unroll") for (int n = 0; n < 2; ++n) _Pragma("unroll") for (int k = 0; k < 2; ++k) \
;     acc[ai][bj][m][n] = __builtin_amdgcn_mfma_f32_16x16x32_bf16(Bt[n][k], At[m][k], acc[ai][bj][m][n], 0, 0, 0); __builtin_amdgcn_s_setprio(0); } while (0)
; #define PG8_WAIT_V(n) asm volatile("s_waitcnt vmcnt(" #n ")" ::: "memory")
; #define PG8_WAIT_L(n) asm volatile("s_waitcnt lgkmcnt(" #n ")" ::: "memory")
; #define PG8_BAR __builtin_amdgcn_s_barrier()
; #define PG8_SCHED __builtin_amdgcn_sched_barrier(0)
; template <class Epi, class Sched>
; __device__ __forceinline__ void gemm_phase(PG8_LAS unsigned char* lds, const int lda, const int ldb, const Sched& S, const Epi& E) {
;     ...
;       PG8_BAR; PG8_WAIT_L(0); PG8_MMA(1, 0, At, B0); PG8_BAR; PG8_SCHED;
;       PG8_STAGE(PG8_SB(1, 1), b3 + hstepB, voffB);
;       PG8_WAIT_V(6); PG8_BAR; PG8_MMA(1, 1, At, B1); PG8_BAR;
;     }
;   __device__ __forceinline__ void operator()(const f32x4 (&acc)[2][2][4][2], const Unit& u, int wr, int wc, int fr, int fq) const {
;     const int mr = (u.pm * 256 < ML) ? ((u.pm * 256) >> 11) : 32;
;     const float* gp = mod + (size_t)mr * 6144 + gate_off;
	s_waitcnt lgkmcnt(0)
	v_mfma_f32_16x16x32_bf16 v[118:121], v[216:219], v[158:161], v[118:121]
	v_mfma_f32_16x16x32_bf16 v[114:117], v[224:227], v[158:161], v[114:117]
	v_mfma_f32_16x16x32_bf16 v[102:105], v[216:219], v[166:169], v[102:105]
	v_mfma_f32_16x16x32_bf16 v[98:101], v[224:227], v[166:169], v[98:101]
	v_mfma_f32_16x16x32_bf16 v[86:89], v[216:219], v[200:203], v[86:89]
	v_mfma_f32_16x16x32_bf16 v[82:85], v[224:227], v[200:203], v[82:85]
	v_mfma_f32_16x16x32_bf16 v[70:73], v[216:219], v[208:211], v[70:73]
	v_mfma_f32_16x16x32_bf16 v[66:69], v[224:227], v[208:211], v[66:69]
	v_mfma_f32_16x16x32_bf16 v[118:121], v[220:223], v[162:165], v[118:121]
	v_mfma_f32_16x16x32_bf16 v[114:117], v[228:231], v[162:165], v[114:117]
	v_mfma_f32_16x16x32_bf16 v[102:105], v[220:223], v[170:173], v[102:105]
	v_mfma_f32_16x16x32_bf16 v[98:101], v[228:231], v[170:173], v[98:101]
	v_mfma_f32_16x16x32_bf16 v[86:89], v[220:223], v[204:207], v[86:89]
	v_mfma_f32_16x16x32_bf16 v[82:85], v[228:231], v[204:207], v[82:85]
	v_mfma_f32_16x16x32_bf16 v[70:73], v[220:223], v[212:215], v[70:73]
	v_mfma_f32_16x16x32_bf16 v[66:69], v[228:231], v[212:215], v[66:69]
	s_barrier
	s_mov_b32 m0, s44
	v_lshl_add_u64 v[174:175], v[184:185], 0, s[86:87]
	ds_read_b128 v[158:161], v145 offset:49152
	ds_read_b128 v[162:165], v145 offset:50176
	ds_read_b128 v[166:169], v145 offset:51200
	ds_read_b128 v[170:173], v145 offset:52224
	ds_read_b128 v[200:203], v145 offset:53248
	ds_read_b128 v[204:207], v145 offset:54272
	ds_read_b128 v[208:211], v145 offset:55296
	ds_read_b128 v[212:215], v145 offset:56320
	global_load_lds_dwordx4 v[174:175], off
	v_lshl_add_u64 v[174:175], v[232:233], 0, s[86:87]
	s_mov_b32 m0, s45
	s_nop 0
	global_load_lds_dwordx4 v[174:175], off
	s_barrier
	s_waitcnt lgkmcnt(0)
	v_mfma_f32_16x16x32_bf16 v[62:65], v[140:143], v[158:161], v[62:65]
	v_mfma_f32_16x16x32_bf16 v[58:61], v[150:153], v[158:161], v[58:61]
	v_mfma_f32_16x16x32_bf16 v[46:49], v[140:143], v[166:169], v[46:49]
	v_mfma_f32_16x16x32_bf16 v[42:45], v[150:153], v[166:169], v[42:45]
	v_mfma_f32_16x16x32_bf16 v[30:33], v[140:143], v[200:203], v[30:33]
	v_mfma_f32_16x16x32_bf16 v[26:29], v[150:153], v[200:203], v[26:29]
	v_mfma_f32_16x16x32_bf16 v[14:17], v[140:143], v[208:211], v[14:17]
	v_mfma_f32_16x16x32_bf16 v[10:13], v[150:153], v[208:211], v[10:13]
	v_mfma_f32_16x16x32_bf16 v[62:65], v[146:149], v[162:165], v[62:65]
	v_mfma_f32_16x16x32_bf16 v[58:61], v[154:157], v[162:165], v[58:61]
	v_mfma_f32_16x16x32_bf16 v[46:49], v[146:149], v[170:173], v[46:49]
	v_mfma_f32_16x16x32_bf16 v[42:45], v[154:157], v[170:173], v[42:45]
	v_mfma_f32_16x16x32_bf16 v[30:33], v[146:149], v[204:207], v[30:33]
	v_mfma_f32_16x16x32_bf16 v[26:29], v[154:157], v[204:207], v[26:29]
	v_mfma_f32_16x16x32_bf16 v[14:17], v[146:149], v[212:215], v[14:17]
	v_mfma_f32_16x16x32_bf16 v[10:13], v[154:157], v[212:215], v[10:13]
	s_barrier
	s_add_u32 s18, s22, 0x40080
	s_addc_u32 s19, s23, 0
	s_add_i32 s22, s24, s34
	v_lshl_add_u64 v[140:141], s[18:19], 0, v[134:135]
	s_mov_b32 m0, s22
	s_nop 0
	global_load_lds_dwordx4 v[140:141], off
	v_lshl_add_u64 v[140:141], s[18:19], 0, v[132:133]
	s_add_i32 m0, s22, 0x2000
	s_nop 0
	global_load_lds_dwordx4 v[140:141], off
	s_add_i32 s54, s54, 2
	s_add_u32 s52, s52, 0x100
	s_addc_u32 s53, s53, 0
	s_cmp_gt_u32 s54, 13
	s_mov_b64 s[18:19], s[20:21]
	s_waitcnt vmcnt(6)
	s_barrier
	v_mfma_f32_16x16x32_bf16 v[54:57], v[216:219], v[158:161], v[54:57]
	v_mfma_f32_16x16x32_bf16 v[50:53], v[224:227], v[158:161], v[50:53]
	v_mfma_f32_16x16x32_bf16 v[38:41], v[216:219], v[166:169], v[38:41]
	v_mfma_f32_16x16x32_bf16 v[34:37], v[224:227], v[166:169], v[34:37]
	v_mfma_f32_16x16x32_bf16 v[22:25], v[216:219], v[200:203], v[22:25]
	v_mfma_f32_16x16x32_bf16 v[18:21], v[224:227], v[200:203], v[18:21]
	v_mfma_f32_16x16x32_bf16 v[6:9], v[216:219], v[208:211], v[6:9]
	v_mfma_f32_16x16x32_bf16 v[2:5], v[224:227], v[208:211], v[2:5]
	v_mfma_f32_16x16x32_bf16 v[54:57], v[220:223], v[162:165], v[54:57]
	v_mfma_f32_16x16x32_bf16 v[50:53], v[228:231], v[162:165], v[50:53]
	v_mfma_f32_16x16x32_bf16 v[38:41], v[220:223], v[170:173], v[38:41]
	v_mfma_f32_16x16x32_bf16 v[34:37], v[228:231], v[170:173], v[34:37]
	v_mfma_f32_16x16x32_bf16 v[22:25], v[220:223], v[204:207], v[22:25]
	v_mfma_f32_16x16x32_bf16 v[18:21], v[228:231], v[204:207], v[18:21]
	v_mfma_f32_16x16x32_bf16 v[6:9], v[220:223], v[212:215], v[6:9]
	v_mfma_f32_16x16x32_bf16 v[2:5], v[228:231], v[212:215], v[2:5]
	s_barrier
	s_cbranch_scc0 .LBB0_1482
	s_cmpk_gt_i32 s16, 0xff
	s_mov_b64 s[18:19], 0x30000
	s_cbranch_scc1 .LBB0_1478
	s_ashr_i32 s1, s16, 3
	s_mul_hi_i32 s19, s1, 0x1800
	s_mul_i32 s18, s1, 0x1800
	s_branch .LBB0_1478

; #define PG8_STAGE(bufoff, gbase, voff) do { _Pragma("unroll") for (int _i = 0; _i < 2; ++_i) \
;     __builtin_amdgcn_global_load_lds((const unsigned*)((const char*)(gbase) + (voff)[_i]), (PG8_LAS unsigned*)(lds + (bufoff) + ldsw + _i * 8192), 16, 0, 0); } while (0)
; #define PG8_LDA(dst, b, h) do { _Pragma("unroll") for (int m = 0; m < 4; ++m) _Pragma("unroll") for (int k = 0; k < 2; ++k) dst[m][k] = *(const PG8_LAS bf16x8*)(lds + PG8_SA(b, h) + aoff + m * 2048 + k * 1024); } while (0)
; #define PG8_LDB(dst, b, h) do { _Pragma("unroll") for (int n = 0; n < 2; ++n) _Pragma("unroll") for (int k = 0; k < 2; ++k) dst[n][k] = *(const PG8_LAS bf16x8*)(lds + PG8_SB(b, h) + boff + n * 2048 + k * 1024); } while (0)
; #define PG8_MMA(ai, bj, At, Bt) do { __builtin_amdgcn_s_setprio(1); _Pragma("unroll") for (int m = 0; m < 4; ++m) _Pragma("unroll") for (int n = 0; n < 2; ++n) _Pragma("unroll") for (int k = 0; k < 2; ++k) \
;     acc[ai][bj][m][n] = __builtin_amdgcn_mfma_f32_16x16x32_bf16(Bt[n][k], At[m][k], acc[ai][bj][m][n], 0, 0, 0); __builtin_amdgcn_s_setprio(0); } while (0)
; #define PG8_WAIT_L(n) asm volatile("s_waitcnt lgkmcnt(" #n ")" ::: "memory")
; #define PG8_BAR __builtin_amdgcn_s_barrier()
; #define PG8_SCHED __builtin_amdgcn_sched_barrier(0)
; template <class Epi, class Sched>
; __device__ __forceinline__ void gemm_phase(PG8_LAS unsigned char* lds, const int lda, const int ldb, const Sched& S, const Epi& E) {
;     ...
;     for (int t = 0; t < nt; t += 2) {
;       const bool last = (t == nt - 2);
;       const char* a1 = cA + (size_t)(t + 1) * kstep;
;       const char* a2 = last ? nA : cA + (size_t)(t + 2) * kstep; const char* b2 = last ? nB : cB + (size_t)(t + 2) * kstep;
;       const char* a3 = a2 + kstep; const char* b3 = b2 + kstep;
;       PG8_LDB(B0, 0, 0); PG8_SCHED; PG8_LDA(At, 0, 0); PG8_STAGE(PG8_SA(1, 1), a1 + hstepA, voffA);
;       PG8_WAIT_L(8); PG8_BAR; PG8_WAIT_L(0); PG8_MMA(0, 0, At, B0); PG8_BAR; PG8_SCHED;
;       PG8_LDB(B1, 0, 1); PG8_STAGE(PG8_SB(0, 0), b2, voffB);
;       PG8_BAR; PG8_WAIT_L(0); PG8_MMA(0, 1, At, B1); PG8_BAR;
;       PG8_LDA(At, 0, 1); PG8_STAGE(PG8_SA(0, 0), a2, voffA);
;       PG8_BAR; PG8_WAIT_L(0); PG8_MMA(1, 0, At, B0); PG8_BAR; PG8_SCHED;
.LBB0_1604:
	s_add_u32 s20, s18, 0xfffc0080
	s_addc_u32 s21, s19, -1
	s_add_i32 s33, 0, 0x10000
	v_add_u32_e32 v154, s33, v131
	ds_read_b128 v[142:145], v154
	ds_read_b128 v[146:149], v154 offset:1024
	ds_read_b128 v[150:153], v154 offset:2048
	ds_read_b128 v[154:157], v154 offset:3072
	s_cmp_eq_u32 s46, 12
	s_cselect_b32 s23, s11, s21
	s_cselect_b32 s22, s42, s20
	s_cselect_b32 s21, s1, s45
	s_cselect_b32 s20, s43, s44
	v_lshl_add_u64 v[174:175], s[18:19], 0, v[136:137]
	s_add_i32 m0, s17, 0xc000
	ds_read_b128 v[158:161], v141
	ds_read_b128 v[162:165], v141 offset:1024
	ds_read_b128 v[166:169], v141 offset:2048
	ds_read_b128 v[170:173], v141 offset:3072
	ds_read_b128 v[200:203], v141 offset:4096
	ds_read_b128 v[204:207], v141 offset:5120
	ds_read_b128 v[208:211], v141 offset:6144
	ds_read_b128 v[212:215], v141 offset:7168
	global_load_lds_dwordx4 v[174:175], off
	v_lshl_add_u64 v[174:175], s[18:19], 0, v[138:139]
	s_add_i32 m0, s17, 0xe000
	s_nop 0
	global_load_lds_dwordx4 v[174:175], off
	s_waitcnt lgkmcnt(8)
	s_barrier
	s_waitcnt lgkmcnt(0)
	v_mfma_f32_16x16x32_bf16 v[126:129], v[142:145], v[158:161], v[126:129]
	v_mfma_f32_16x16x32_bf16 v[118:121], v[150:153], v[158:161], v[118:121]
	v_mfma_f32_16x16x32_bf16 v[110:113], v[142:145], v[166:169], v[110:113]
	v_mfma_f32_16x16x32_bf16 v[102:105], v[150:153], v[166:169], v[102:105]
	v_mfma_f32_16x16x32_bf16 v[94:97], v[142:145], v[200:203], v[94:97]
	v_mfma_f32_16x16x32_bf16 v[86:89], v[150:153], v[200:203], v[86:89]
	v_mfma_f32_16x16x32_bf16 v[78:81], v[142:145], v[208:211], v[78:81]
	v_mfma_f32_16x16x32_bf16 v[70:73], v[150:153], v[208:211], v[70:73]
	v_mfma_f32_16x16x32_bf16 v[126:129], v[146:149], v[162:165], v[126:129]
	v_mfma_f32_16x16x32_bf16 v[118:121], v[154:157], v[162:165], v[118:121]
	v_mfma_f32_16x16x32_bf16 v[110:113], v[146:149], v[170:173], v[110:113]
	v_mfma_f32_16x16x32_bf16 v[102:105], v[154:157], v[170:173], v[102:105]
	v_mfma_f32_16x16x32_bf16 v[94:97], v[146:149], v[204:207], v[94:97]
	v_mfma_f32_16x16x32_bf16 v[86:89], v[154:157], v[204:207], v[86:89]
	v_mfma_f32_16x16x32_bf16 v[78:81], v[146:149], v[212:215], v[78:81]
	v_mfma_f32_16x16x32_bf16 v[70:73], v[154:157], v[212:215], v[70:73]
	s_barrier
	s_add_i32 s47, 0, 0x14000
	v_add_u32_e32 v174, s47, v131
	s_add_i32 s33, s33, s30
	ds_read_b128 v[216:219], v174
	ds_read_b128 v[220:223], v174 offset:1024
	ds_read_b128 v[224:227], v174 offset:2048
	ds_read_b128 v[228:231], v174 offset:3072
	v_lshl_add_u64 v[174:175], s[20:21], 0, v[134:135]
	s_mov_b32 m0, s33
	v_lshl_add_u64 v[182:183], s[20:21], 0, v[132:133]
	global_load_lds_dwordx4 v[174:175], off
	s_add_i32 m0, s33, 0x2000
	s_nop 0
	global_load_lds_dwordx4 v[182:183], off
	s_barrier
	s_waitcnt lgkmcnt(0)
	v_mfma_f32_16x16x32_bf16 v[122:125], v[216:219], v[158:161], v[122:125]
	v_mfma_f32_16x16x32_bf16 v[114:117], v[224:227], v[158:161], v[114:117]
	v_mfma_f32_16x16x32_bf16 v[106:109], v[216:219], v[166:169], v[106:109]
	v_mfma_f32_16x16x32_bf16 v[98:101], v[224:227], v[166:169], v[98:101]
	v_mfma_f32_16x16x32_bf16 v[90:93], v[216:219], v[200:203], v[90:93]
	v_mfma_f32_16x16x32_bf16 v[82:85], v[224:227], v[200:203], v[82:85]
	v_mfma_f32_16x16x32_bf16 v[74:77], v[216:219], v[208:211], v[74:77]
	v_mfma_f32_16x16x32_bf16 v[66:69], v[224:227], v[208:211], v[66:69]
	v_mfma_f32_16x16x32_bf16 v[122:125], v[220:223], v[162:165], v[122:125]
	v_mfma_f32_16x16x32_bf16 v[114:117], v[228:231], v[162:165], v[114:117]
	v_mfma_f32_16x16x32_bf16 v[106:109], v[220:223], v[170:173], v[106:109]
	v_mfma_f32_16x16x32_bf16 v[98:101], v[228:231], v[170:173], v[98:101]
	v_mfma_f32_16x16x32_bf16 v[90:93], v[220:223], v[204:207], v[90:93]
	v_mfma_f32_16x16x32_bf16 v[82:85], v[228:231], v[204:207], v[82:85]
	v_mfma_f32_16x16x32_bf16 v[74:77], v[220:223], v[212:215], v[74:77]
	v_mfma_f32_16x16x32_bf16 v[66:69], v[228:231], v[212:215], v[66:69]
	s_barrier
	s_mov_b32 m0, s17
	v_lshl_add_u64 v[184:185], s[22:23], 0, v[134:135]
	ds_read_b128 v[158:161], v141 offset:16384
	ds_read_b128 v[162:165], v141 offset:17408
	ds_read_b128 v[166:169], v141 offset:18432
	ds_read_b128 v[170:173], v141 offset:19456
	ds_read_b128 v[200:203], v141 offset:20480
	ds_read_b128 v[204:207], v141 offset:21504
	ds_read_b128 v[208:211], v141 offset:22528
	ds_read_b128 v[212:215], v141 offset:23552
	global_load_lds_dwordx4 v[184:185], off
	v_lshl_add_u64 v[232:233], s[22:23], 0, v[132:133]
	s_mov_b32 m0, s35
	s_nop 0
	global_load_lds_dwordx4 v[232:233], off
	s_barrier
	s_waitcnt lgkmcnt(0)
	v_mfma_f32_16x16x32_bf16 v[62:65], v[142:145], v[158:161], v[62:65]
	v_mfma_f32_16x16x32_bf16 v[54:57], v[150:153], v[158:161], v[54:57]
	v_mfma_f32_16x16x32_bf16 v[46:49], v[142:145], v[166:169], v[46:49]
	v_mfma_f32_16x16x32_bf16 v[38:41], v[150:153], v[166:169], v[38:41]
	v_mfma_f32_16x16x32_bf16 v[30:33], v[142:145], v[200:203], v[30:33]
	v_mfma_f32_16x16x32_bf16 v[22:25], v[150:153], v[200:203], v[22:25]
	v_mfma_f32_16x16x32_bf16 v[14:17], v[142:145], v[208:211], v[14:17]
	v_mfma_f32_16x16x32_bf16 v[6:9], v[150:153], v[208:211], v[6:9]
	v_mfma_f32_16x16x32_bf16 v[62:65], v[146:149], v[162:165], v[62:65]
	v_mfma_f32_16x16x32_bf16 v[54:57], v[154:157], v[162:165], v[54:57]
	v_mfma_f32_16x16x32_bf16 v[46:49], v[146:149], v[170:173], v[46:49]
	v_mfma_f32_16x16x32_bf16 v[38:41], v[154:157], v[170:173], v[38:41]
	v_mfma_f32_16x16x32_bf16 v[30:33], v[146:149], v[204:207], v[30:33]
	v_mfma_f32_16x16x32_bf16 v[22:25], v[154:157], v[204:207], v[22:25]
	v_mfma_f32_16x16x32_bf16 v[14:17], v[146:149], v[212:215], v[14:17]
	v_mfma_f32_16x16x32_bf16 v[6:9], v[154:157], v[212:215], v[6:9]
	s_barrier
; #define PG8_STAGE(bufoff, gbase, voff) do { _Pragma("unroll") for (int _i = 0; _i < 2; ++_i) \
;     __builtin_amdgcn_global_load_lds((const unsigned*)((const char*)(gbase) + (voff)[_i]), (PG8_LAS unsigned*)(lds + (bufoff) + ldsw + _i * 8192), 16, 0, 0); } while (0)
; #define PG8_LDA(dst, b, h) do { _Pragma("unroll") for (int m = 0; m < 4; ++m) _Pragma("unroll") for (int k = 0; k < 2; ++k) dst[m][k] = *(const PG8_LAS bf16x8*)(lds + PG8_SA(b, h) + aoff + m * 2048 + k * 1024); } while (0)
; #define PG8_LDB(dst, b, h) do { _Pragma("unroll") for (int n = 0; n < 2; ++n) _Pragma("unroll") for (int k = 0; k < 2; ++k) dst[n][k] = *(const PG8_LAS bf16x8*)(lds + PG8_SB(b, h) + boff + n * 2048 + k * 1024); } while (0)
; #define PG8_MMA(ai, bj, At, Bt) do { __builtin_amdgcn_s_setprio(1); _Pragma("unroll") for (int m = 0; m < 4; ++m) _Pragma("unroll") for (int n = 0; n < 2; ++n) _Pragma("unroll") for (int k = 0; k < 2; ++k) \
;     acc[ai][bj][m][n] = __builtin_amdgcn_mfma_f32_16x16x32_bf16(Bt[n][k], At[m][k], acc[ai][bj][m][n], 0, 0, 0); __builtin_amdgcn_s_setprio(0); } while (0)
; #define PG8_WAIT_V(n) asm volatile("s_waitcnt vmcnt(" #n ")" ::: "memory")
; #define PG8_WAIT_L(n) asm volatile("s_waitcnt lgkmcnt(" #n ")" ::: "memory")
; #define PG8_BAR __builtin_amdgcn_s_barrier()
; #define PG8_SCHED __builtin_amdgcn_sched_barrier(0)
; template <class Epi, class Sched>
; __device__ __forceinline__ void gemm_phase(PG8_LAS unsigned char* lds, const int lda, const int ldb, const Sched& S, const Epi& E) {
;     ...
;       PG8_STAGE(PG8_SB(0, 1), b2 + hstepB, voffB);
;       PG8_WAIT_V(6); PG8_BAR; PG8_MMA(1, 1, At, B1); PG8_BAR;
;       PG8_LDB(B0, 1, 0); PG8_SCHED; PG8_LDA(At, 1, 0); PG8_STAGE(PG8_SA(0, 1), a2 + hstepA, voffA);
;       PG8_WAIT_L(8); PG8_BAR; PG8_WAIT_L(0); PG8_MMA(0, 0, At, B0); PG8_BAR; PG8_SCHED;
;       PG8_LDB(B1, 1, 1); PG8_STAGE(PG8_SB(1, 0), b3, voffB);
;       PG8_BAR; PG8_WAIT_L(0); PG8_MMA(0, 1, At, B1); PG8_BAR;
;       PG8_LDA(At, 1, 1); PG8_STAGE(PG8_SA(1, 0), a3, voffA);
;       PG8_BAR; PG8_WAIT_L(0); PG8_MMA(1, 0, At, B0); PG8_BAR; PG8_SCHED;
	s_add_u32 s48, s20, 0x40000
	s_addc_u32 s49, s21, 0
	s_add_i32 s33, s47, s30
	v_lshl_add_u64 v[142:143], s[48:49], 0, v[134:135]
	s_mov_b32 m0, s33
	s_nop 0
	global_load_lds_dwordx4 v[142:143], off
	v_lshl_add_u64 v[142:143], s[48:49], 0, v[132:133]
	s_add_i32 m0, s33, 0x2000
	s_nop 0
	global_load_lds_dwordx4 v[142:143], off
	s_waitcnt vmcnt(6)
	s_barrier
	v_mfma_f32_16x16x32_bf16 v[58:61], v[216:219], v[158:161], v[58:61]
	v_mfma_f32_16x16x32_bf16 v[50:53], v[224:227], v[158:161], v[50:53]
	v_mfma_f32_16x16x32_bf16 v[42:45], v[216:219], v[166:169], v[42:45]
	v_mfma_f32_16x16x32_bf16 v[34:37], v[224:227], v[166:169], v[34:37]
	v_mfma_f32_16x16x32_bf16 v[26:29], v[216:219], v[200:203], v[26:29]
	v_mfma_f32_16x16x32_bf16 v[18:21], v[224:227], v[200:203], v[18:21]
	v_mfma_f32_16x16x32_bf16 v[10:13], v[216:219], v[208:211], v[10:13]
	v_mfma_f32_16x16x32_bf16 v[2:5], v[224:227], v[208:211], v[2:5]
	v_mfma_f32_16x16x32_bf16 v[58:61], v[220:223], v[162:165], v[58:61]
	v_mfma_f32_16x16x32_bf16 v[50:53], v[228:231], v[162:165], v[50:53]
	v_mfma_f32_16x16x32_bf16 v[42:45], v[220:223], v[170:173], v[42:45]
	v_mfma_f32_16x16x32_bf16 v[34:37], v[228:231], v[170:173], v[34:37]
	v_mfma_f32_16x16x32_bf16 v[26:29], v[220:223], v[204:207], v[26:29]
	v_mfma_f32_16x16x32_bf16 v[18:21], v[228:231], v[204:207], v[18:21]
	v_mfma_f32_16x16x32_bf16 v[10:13], v[220:223], v[212:215], v[10:13]
	v_mfma_f32_16x16x32_bf16 v[2:5], v[228:231], v[212:215], v[2:5]
	s_barrier
	s_add_i32 s33, 0, 0x18000
	v_add_u32_e32 v154, s33, v131
	ds_read_b128 v[142:145], v154
	ds_read_b128 v[146:149], v154 offset:1024
	ds_read_b128 v[150:153], v154 offset:2048
	ds_read_b128 v[154:157], v154 offset:3072
	s_add_u32 s22, s22, 0x40000
	s_addc_u32 s23, s23, 0
	s_mov_b32 m0, s36
	v_lshl_add_u64 v[216:217], s[22:23], 0, v[134:135]
	ds_read_b128 v[158:161], v141 offset:32768
	ds_read_b128 v[162:165], v141 offset:33792
	ds_read_b128 v[166:169], v141 offset:34816
	ds_read_b128 v[170:173], v141 offset:35840
	ds_read_b128 v[200:203], v141 offset:36864
	ds_read_b128 v[204:207], v141 offset:37888
	ds_read_b128 v[208:211], v141 offset:38912
	ds_read_b128 v[212:215], v141 offset:39936
	global_load_lds_dwordx4 v[216:217], off
	v_lshl_add_u64 v[216:217], s[22:23], 0, v[132:133]
	s_mov_b32 m0, s37
	s_nop 0
	global_load_lds_dwordx4 v[216:217], off
	s_waitcnt lgkmcnt(8)
	s_barrier
	s_waitcnt lgkmcnt(0)
	v_mfma_f32_16x16x32_bf16 v[126:129], v[142:145], v[158:161], v[126:129]
	v_mfma_f32_16x16x32_bf16 v[118:121], v[150:153], v[158:161], v[118:121]
	v_mfma_f32_16x16x32_bf16 v[110:113], v[142:145], v[166:169], v[110:113]
	v_mfma_f32_16x16x32_bf16 v[102:105], v[150:153], v[166:169], v[102:105]
	v_mfma_f32_16x16x32_bf16 v[94:97], v[142:145], v[200:203], v[94:97]
	v_mfma_f32_16x16x32_bf16 v[86:89], v[150:153], v[200:203], v[86:89]
	v_mfma_f32_16x16x32_bf16 v[78:81], v[142:145], v[208:211], v[78:81]
	v_mfma_f32_16x16x32_bf16 v[70:73], v[150:153], v[208:211], v[70:73]
	v_mfma_f32_16x16x32_bf16 v[126:129], v[146:149], v[162:165], v[126:129]
	v_mfma_f32_16x16x32_bf16 v[118:121], v[154:157], v[162:165], v[118:121]
	v_mfma_f32_16x16x32_bf16 v[110:113], v[146:149], v[170:173], v[110:113]
	v_mfma_f32_16x16x32_bf16 v[102:105], v[154:157], v[170:173], v[102:105]
	v_mfma_f32_16x16x32_bf16 v[94:97], v[146:149], v[204:207], v[94:97]
	v_mfma_f32_16x16x32_bf16 v[86:89], v[154:157], v[204:207], v[86:89]
	v_mfma_f32_16x16x32_bf16 v[78:81], v[146:149], v[212:215], v[78:81]
	v_mfma_f32_16x16x32_bf16 v[70:73], v[154:157], v[212:215], v[70:73]
	s_barrier
	s_add_i32 s22, 0, 0x1c000
	s_add_i32 s23, s33, s30
	v_add_u32_e32 v228, s22, v131
	v_lshl_add_u64 v[174:175], v[174:175], 0, s[86:87]
	s_mov_b32 m0, s23
	ds_read_b128 v[216:219], v228
	ds_read_b128 v[220:223], v228 offset:1024
	ds_read_b128 v[224:227], v228 offset:2048
	ds_read_b128 v[228:231], v228 offset:3072
	global_load_lds_dwordx4 v[174:175], off
	v_lshl_add_u64 v[174:175], v[182:183], 0, s[86:87]
	s_add_i32 m0, s23, 0x2000
	s_nop 0
	global_load_lds_dwordx4 v[174:175], off
	s_barrier
	s_waitcnt lgkmcnt(0)
	v_mfma_f32_16x16x32_bf16 v[122:125], v[216:219], v[158:161], v[122:125]
	v_mfma_f32_16x16x32_bf16 v[114:117], v[224:227], v[158:161], v[114:117]
	v_mfma_f32_16x16x32_bf16 v[106:109], v[216:219], v[166:169], v[106:109]
	v_mfma_f32_16x16x32_bf16 v[98:101], v[224:227], v[166:169], v[98:101]
	v_mfma_f32_16x16x32_bf16 v[90:93], v[216:219], v[200:203], v[90:93]
	v_mfma_f32_16x16x32_bf16 v[82:85], v[224:227], v[200:203], v[82:85]
	v_mfma_f32_16x16x32_bf16 v[74:77], v[216:219], v[208:211], v[74:77]
	v_mfma_f32_16x16x32_bf16 v[66:69], v[224:227], v[208:211], v[66:69]
	v_mfma_f32_16x16x32_bf16 v[122:125], v[220:223], v[162:165], v[122:125]
	v_mfma_f32_16x16x32_bf16 v[114:117], v[228:231], v[162:165], v[114:117]
	v_mfma_f32_16x16x32_bf16 v[106:109], v[220:223], v[170:173], v[106:109]
	v_mfma_f32_16x16x32_bf16 v[98:101], v[228:231], v[170:173], v[98:101]
	v_mfma_f32_16x16x32_bf16 v[90:93], v[220:223], v[204:207], v[90:93]
	v_mfma_f32_16x16x32_bf16 v[82:85], v[228:231], v[204:207], v[82:85]
	v_mfma_f32_16x16x32_bf16 v[74:77], v[220:223], v[212:215], v[74:77]
	v_mfma_f32_16x16x32_bf16 v[66:69], v[228:231], v[212:215], v[66:69]
	s_barrier
	s_mov_b32 m0, s38
	v_lshl_add_u64 v[174:175], v[184:185], 0, s[86:87]
	ds_read_b128 v[158:161], v141 offset:49152
	ds_read_b128 v[162:165], v141 offset:50176
	ds_read_b128 v[166:169], v141 offset:51200
	ds_read_b128 v[170:173], v141 offset:52224
	ds_read_b128 v[200:203], v141 offset:53248
	ds_read_b128 v[204:207], v141 offset:54272
	ds_read_b128 v[208:211], v141 offset:55296
	ds_read_b128 v[212:215], v141 offset:56320
	global_load_lds_dwordx4 v[174:175], off
	v_lshl_add_u64 v[174:175], v[232:233], 0, s[86:87]
	s_mov_b32 m0, s39
	s_nop 0
	global_load_lds_dwordx4 v[174:175], off
	s_barrier
; __device__ __forceinline__ float silu_f(float x) { return x * sigm(x); }
; #define PG8_STAGE(bufoff, gbase, voff) do { _Pragma("unroll") for (int _i = 0; _i < 2; ++_i) \
;     __builtin_amdgcn_global_load_lds((const unsigned*)((const char*)(gbase) + (voff)[_i]), (PG8_LAS unsigned*)(lds + (bufoff) + ldsw + _i * 8192), 16, 0, 0); } while (0)
; #define PG8_MMA(ai, bj, At, Bt) do { __builtin_amdgcn_s_setprio(1); _Pragma("unroll") for (int m = 0; m < 4; ++m) _Pragma("unroll") for (int n = 0; n < 2; ++n) _Pragma("unroll") for (int k = 0; k < 2; ++k) \
;     acc[ai][bj][m][n] = __builtin_amdgcn_mfma_f32_16x16x32_bf16(Bt[n][k], At[m][k], acc[ai][bj][m][n], 0, 0, 0); __builtin_amdgcn_s_setprio(0); } while (0)
; #define PG8_WAIT_V(n) asm volatile("s_waitcnt vmcnt(" #n ")" ::: "memory")
; #define PG8_WAIT_L(n) asm volatile("s_waitcnt lgkmcnt(" #n ")" ::: "memory")
; #define PG8_BAR __builtin_amdgcn_s_barrier()
; #define PG8_SCHED __builtin_amdgcn_sched_barrier(0)
; template <class Epi, class Sched>
; __device__ __forceinline__ void gemm_phase(PG8_LAS unsigned char* lds, const int lda, const int ldb, const Sched& S, const Epi& E) {
;     ...
;       PG8_BAR; PG8_WAIT_L(0); PG8_MMA(1, 0, At, B0); PG8_BAR; PG8_SCHED;
;       PG8_STAGE(PG8_SB(1, 1), b3 + hstepB, voffB);
;       PG8_WAIT_V(6); PG8_BAR; PG8_MMA(1, 1, At, B1); PG8_BAR;
;     }
;   __device__ __forceinline__ void operator()(const f32x4 (&acc)[2][2][4][2], const Unit& u, int wr, int wc, int fr, int fq) const {
;     ...
;         const int r = u.pm * 256 + ai * 128 + wr * 64 + m * 16 + fr;
; #pragma unroll
;         for (int n = 0; n < 2; ++n) {
;           const f32x4 g = acc[ai][0][m][n], up = acc[ai][1][m][n];
;           const int c = u.pn * 128 + wc * 32 + n * 16 + 4 * fq;
;           uint2 w;
;           w.x = pack2(silu_f(g[0]) * up[0], silu_f(g[1]) * up[1]);
;           w.y = pack2(silu_f(g[2]) * up[2], silu_f(g[3]) * up[3]);
;           *reinterpret_cast<uint2*>(HID + (size_t)r * DFF + c) = w;
	s_waitcnt lgkmcnt(0)
	v_mfma_f32_16x16x32_bf16 v[62:65], v[142:145], v[158:161], v[62:65]
	v_mfma_f32_16x16x32_bf16 v[54:57], v[150:153], v[158:161], v[54:57]
	v_mfma_f32_16x16x32_bf16 v[46:49], v[142:145], v[166:169], v[46:49]
	v_mfma_f32_16x16x32_bf16 v[38:41], v[150:153], v[166:169], v[38:41]
	v_mfma_f32_16x16x32_bf16 v[30:33], v[142:145], v[200:203], v[30:33]
	v_mfma_f32_16x16x32_bf16 v[22:25], v[150:153], v[200:203], v[22:25]
	v_mfma_f32_16x16x32_bf16 v[14:17], v[142:145], v[208:211], v[14:17]
	v_mfma_f32_16x16x32_bf16 v[6:9], v[150:153], v[208:211], v[6:9]
	v_mfma_f32_16x16x32_bf16 v[62:65], v[146:149], v[162:165], v[62:65]
	v_mfma_f32_16x16x32_bf16 v[54:57], v[154:157], v[162:165], v[54:57]
	v_mfma_f32_16x16x32_bf16 v[46:49], v[146:149], v[170:173], v[46:49]
	v_mfma_f32_16x16x32_bf16 v[38:41], v[154:157], v[170:173], v[38:41]
	v_mfma_f32_16x16x32_bf16 v[30:33], v[146:149], v[204:207], v[30:33]
	v_mfma_f32_16x16x32_bf16 v[22:25], v[154:157], v[204:207], v[22:25]
	v_mfma_f32_16x16x32_bf16 v[14:17], v[146:149], v[212:215], v[14:17]
	v_mfma_f32_16x16x32_bf16 v[6:9], v[154:157], v[212:215], v[6:9]
	s_barrier
	s_add_u32 s20, s20, 0x40080
	s_addc_u32 s21, s21, 0
	s_add_i32 s22, s22, s30
	v_lshl_add_u64 v[142:143], s[20:21], 0, v[134:135]
	s_mov_b32 m0, s22
	s_nop 0
	global_load_lds_dwordx4 v[142:143], off
	v_lshl_add_u64 v[142:143], s[20:21], 0, v[132:133]
	s_add_i32 m0, s22, 0x2000
	s_nop 0
	global_load_lds_dwordx4 v[142:143], off
	s_add_i32 s46, s46, 2
	s_add_u32 s18, s18, 0x100
	s_addc_u32 s19, s19, 0
	s_add_u32 s44, s44, 0x100
	s_addc_u32 s45, s45, 0
	s_cmp_gt_u32 s46, 13
	s_waitcnt vmcnt(6)
	s_barrier
	v_mfma_f32_16x16x32_bf16 v[58:61], v[216:219], v[158:161], v[58:61]
	v_mfma_f32_16x16x32_bf16 v[50:53], v[224:227], v[158:161], v[50:53]
	v_mfma_f32_16x16x32_bf16 v[42:45], v[216:219], v[166:169], v[42:45]
	v_mfma_f32_16x16x32_bf16 v[34:37], v[224:227], v[166:169], v[34:37]
	v_mfma_f32_16x16x32_bf16 v[26:29], v[216:219], v[200:203], v[26:29]
	v_mfma_f32_16x16x32_bf16 v[18:21], v[224:227], v[200:203], v[18:21]
	v_mfma_f32_16x16x32_bf16 v[10:13], v[216:219], v[208:211], v[10:13]
	v_mfma_f32_16x16x32_bf16 v[2:5], v[224:227], v[208:211], v[2:5]
	v_mfma_f32_16x16x32_bf16 v[58:61], v[220:223], v[162:165], v[58:61]
	v_mfma_f32_16x16x32_bf16 v[50:53], v[228:231], v[162:165], v[50:53]
	v_mfma_f32_16x16x32_bf16 v[42:45], v[220:223], v[170:173], v[42:45]
	v_mfma_f32_16x16x32_bf16 v[34:37], v[228:231], v[170:173], v[34:37]
	v_mfma_f32_16x16x32_bf16 v[26:29], v[220:223], v[204:207], v[26:29]
	v_mfma_f32_16x16x32_bf16 v[18:21], v[228:231], v[204:207], v[18:21]
	v_mfma_f32_16x16x32_bf16 v[10:13], v[220:223], v[212:215], v[10:13]
	v_mfma_f32_16x16x32_bf16 v[2:5], v[228:231], v[212:215], v[2:5]
	s_barrier
	s_cbranch_scc0 .LBB0_1604
	v_mul_f32_e32 v143, 0xbfb8aa3b, v126
	v_exp_f32_e32 v143, v143
	v_lshl_or_b32 v144, s41, 7, v140
	v_lshl_add_u32 v142, s16, 8, v1
	v_ashrrev_i32_e32 v145, 31, v144
	v_add_f32_e32 v143, 1.0, v143
	v_rcp_f32_e32 v146, v143
	v_mul_f32_e32 v143, 0xbfb8aa3b, v127
	v_exp_f32_e32 v143, v143
	s_and_b64 vcc, exec, s[6:7]
	s_mov_b32 s41, s0
	s_mov_b32 s16, s10
	v_add_f32_e32 v143, 1.0, v143
	v_rcp_f32_e32 v147, v143
	s_mov_b64 s[20:21], s[14:15]
	v_pk_mul_f32 v[126:127], v[126:127], v[146:147]
	s_nop 0
	v_pk_mul_f32 v[122:123], v[126:127], v[122:123]
	s_nop 0
	v_cvt_pk_bf16_f32 v126, v122, v123
	v_mul_f32_e32 v122, 0xbfb8aa3b, v128
	v_mul_f32_e32 v123, 0xbfb8aa3b, v129
	v_exp_f32_e32 v122, v122
	v_exp_f32_e32 v123, v123
	v_add_f32_e32 v122, 1.0, v122
	v_add_f32_e32 v123, 1.0, v123
	v_rcp_f32_e32 v122, v122
	v_rcp_f32_e32 v123, v123
	s_nop 0
	v_pk_mul_f32 v[122:123], v[128:129], v[122:123]
	s_nop 0
	v_pk_mul_f32 v[122:123], v[122:123], v[124:125]
	v_lshlrev_b64 v[124:125], 1, v[144:145]
	v_cvt_pk_bf16_f32 v127, v122, v123
	v_mov_b64_e32 v[122:123], s[84:85]
	v_mad_i64_i32 v[128:129], s[18:19], v142, s50, v[122:123]
	v_lshl_add_u64 v[128:129], v[128:129], 0, v[124:125]
	global_store_dwordx2 v[128:129], v[126:127], off
	v_mul_f32_e32 v126, 0xbfb8aa3b, v118
	v_mul_f32_e32 v127, 0xbfb8aa3b, v119
	v_exp_f32_e32 v126, v126
	v_exp_f32_e32 v127, v127
	v_add_f32_e32 v126, 1.0, v126
	v_add_f32_e32 v127, 1.0, v127
	v_rcp_f32_e32 v126, v126
	v_rcp_f32_e32 v127, v127
	s_nop 0
	v_pk_mul_f32 v[118:119], v[118:119], v[126:127]
	s_nop 0
	v_pk_mul_f32 v[114:115], v[118:119], v[114:115]
	s_nop 0
	v_cvt_pk_bf16_f32 v114, v114, v115
	v_mul_f32_e32 v115, 0xbfb8aa3b, v120
	v_exp_f32_e32 v115, v115
	s_nop 0
	v_add_f32_e32 v115, 1.0, v115
	v_rcp_f32_e32 v118, v115
	v_mul_f32_e32 v115, 0xbfb8aa3b, v121
	v_exp_f32_e32 v115, v115
	s_nop 0
	v_add_f32_e32 v115, 1.0, v115
	v_rcp_f32_e32 v119, v115
	s_nop 0
	v_pk_mul_f32 v[118:119], v[120:121], v[118:119]
	s_nop 0
	v_pk_mul_f32 v[116:117], v[118:119], v[116:117]
	s_nop 0
	v_cvt_pk_bf16_f32 v115, v116, v117
	global_store_dwordx2 v[128:129], v[114:115], off offset:32
	v_mul_f32_e32 v114, 0xbfb8aa3b, v110
	v_mul_f32_e32 v115, 0xbfb8aa3b, v111
	v_exp_f32_e32 v114, v114
	v_exp_f32_e32 v115, v115
	v_or_b32_e32 v116, 16, v142
	v_add_f32_e32 v114, 1.0, v114
	v_add_f32_e32 v115, 1.0, v115
	v_rcp_f32_e32 v114, v114
	v_rcp_f32_e32 v115, v115
	s_nop 0
	v_pk_mul_f32 v[110:111], v[110:111], v[114:115]
	s_nop 0
	v_pk_mul_f32 v[106:107], v[110:111], v[106:107]
	s_nop 0
	v_cvt_pk_bf16_f32 v106, v106, v107
	v_mul_f32_e32 v107, 0xbfb8aa3b, v112
	v_exp_f32_e32 v107, v107
	s_nop 0
	v_add_f32_e32 v107, 1.0, v107
	v_rcp_f32_e32 v110, v107
	v_mul_f32_e32 v107, 0xbfb8aa3b, v113
	v_exp_f32_e32 v107, v107
	s_nop 0
	v_add_f32_e32 v107, 1.0, v107
	v_rcp_f32_e32 v111, v107
	s_nop 0
	v_pk_mul_f32 v[110:111], v[112:113], v[110:111]
	s_nop 0
; __device__ __forceinline__ float silu_f(float x) { return x * sigm(x); }
;   __device__ __forceinline__ void operator()(const f32x4 (&acc)[2][2][4][2], const Unit& u, int wr, int wc, int fr, int fq) const {
;     ...
;         const int r = u.pm * 256 + ai * 128 + wr * 64 + m * 16 + fr;
; #pragma unroll
;         for (int n = 0; n < 2; ++n) {
;           const f32x4 g = acc[ai][0][m][n], up = acc[ai][1][m][n];
;           const int c = u.pn * 128 + wc * 32 + n * 16 + 4 * fq;
;           uint2 w;
;           w.x = pack2(silu_f(g[0]) * up[0], silu_f(g[1]) * up[1]);
;           w.y = pack2(silu_f(g[2]) * up[2], silu_f(g[3]) * up[3]);
;           *reinterpret_cast<uint2*>(HID + (size_t)r * DFF + c) = w;
	v_pk_mul_f32 v[108:109], v[110:111], v[108:109]
	s_nop 0
	v_cvt_pk_bf16_f32 v107, v108, v109
	v_mad_i64_i32 v[108:109], s[18:19], v116, s50, v[122:123]
	v_lshl_add_u64 v[108:109], v[108:109], 0, v[124:125]
	global_store_dwordx2 v[108:109], v[106:107], off
	v_mul_f32_e32 v106, 0xbfb8aa3b, v102
	v_mul_f32_e32 v107, 0xbfb8aa3b, v103
	v_exp_f32_e32 v106, v106
	v_exp_f32_e32 v107, v107
	v_add_f32_e32 v106, 1.0, v106
	v_add_f32_e32 v107, 1.0, v107
	v_rcp_f32_e32 v106, v106
	v_rcp_f32_e32 v107, v107
	s_nop 0
	v_pk_mul_f32 v[102:103], v[102:103], v[106:107]
	s_nop 0
	v_pk_mul_f32 v[98:99], v[102:103], v[98:99]
	s_nop 0
	v_cvt_pk_bf16_f32 v98, v98, v99
	v_mul_f32_e32 v99, 0xbfb8aa3b, v104
	v_exp_f32_e32 v99, v99
	s_nop 0
	v_add_f32_e32 v99, 1.0, v99
	v_rcp_f32_e32 v102, v99
	v_mul_f32_e32 v99, 0xbfb8aa3b, v105
	v_exp_f32_e32 v99, v99
	s_nop 0
	v_add_f32_e32 v99, 1.0, v99
	v_rcp_f32_e32 v103, v99
	s_nop 0
	v_pk_mul_f32 v[102:103], v[104:105], v[102:103]
	s_nop 0
	v_pk_mul_f32 v[100:101], v[102:103], v[100:101]
	s_nop 0
	v_cvt_pk_bf16_f32 v99, v100, v101
	global_store_dwordx2 v[108:109], v[98:99], off offset:32
	v_mul_f32_e32 v98, 0xbfb8aa3b, v94
	v_mul_f32_e32 v99, 0xbfb8aa3b, v95
	v_exp_f32_e32 v98, v98
	v_exp_f32_e32 v99, v99
	v_or_b32_e32 v100, 32, v142
	v_add_f32_e32 v98, 1.0, v98
	v_add_f32_e32 v99, 1.0, v99
	v_rcp_f32_e32 v98, v98
	v_rcp_f32_e32 v99, v99
	s_nop 0
	v_pk_mul_f32 v[94:95], v[94:95], v[98:99]
	s_nop 0
	v_pk_mul_f32 v[90:91], v[94:95], v[90:91]
	s_nop 0
	v_cvt_pk_bf16_f32 v90, v90, v91
	v_mul_f32_e32 v91, 0xbfb8aa3b, v96
	v_exp_f32_e32 v91, v91
	s_nop 0
	v_add_f32_e32 v91, 1.0, v91
	v_rcp_f32_e32 v94, v91
	v_mul_f32_e32 v91, 0xbfb8aa3b, v97
	v_exp_f32_e32 v91, v91
	s_nop 0
	v_add_f32_e32 v91, 1.0, v91
	v_rcp_f32_e32 v95, v91
	s_nop 0
	v_pk_mul_f32 v[94:95], v[96:97], v[94:95]
	s_nop 0
	v_pk_mul_f32 v[92:93], v[94:95], v[92:93]
	s_nop 0
	v_cvt_pk_bf16_f32 v91, v92, v93
	v_mad_i64_i32 v[92:93], s[18:19], v100, s50, v[122:123]
	v_lshl_add_u64 v[92:93], v[92:93], 0, v[124:125]
	global_store_dwordx2 v[92:93], v[90:91], off
	v_mul_f32_e32 v90, 0xbfb8aa3b, v86
	v_mul_f32_e32 v91, 0xbfb8aa3b, v87
	v_exp_f32_e32 v90, v90
	v_exp_f32_e32 v91, v91
	v_add_f32_e32 v90, 1.0, v90
	v_add_f32_e32 v91, 1.0, v91
	v_rcp_f32_e32 v90, v90
	v_rcp_f32_e32 v91, v91
	s_nop 0
	v_pk_mul_f32 v[86:87], v[86:87], v[90:91]
	s_nop 0
	v_pk_mul_f32 v[82:83], v[86:87], v[82:83]
	s_nop 0
	v_cvt_pk_bf16_f32 v82, v82, v83
	v_mul_f32_e32 v83, 0xbfb8aa3b, v88
	v_exp_f32_e32 v83, v83
	s_nop 0
	v_add_f32_e32 v83, 1.0, v83
	v_rcp_f32_e32 v86, v83
	v_mul_f32_e32 v83, 0xbfb8aa3b, v89
	v_exp_f32_e32 v83, v83
	s_nop 0
	v_add_f32_e32 v83, 1.0, v83
	v_rcp_f32_e32 v87, v83
	s_nop 0
	v_pk_mul_f32 v[86:87], v[88:89], v[86:87]
	s_nop 0
	v_pk_mul_f32 v[84:85], v[86:87], v[84:85]
	s_nop 0
	v_cvt_pk_bf16_f32 v83, v84, v85
	global_store_dwordx2 v[92:93], v[82:83], off offset:32
	v_mul_f32_e32 v82, 0xbfb8aa3b, v78
	v_mul_f32_e32 v83, 0xbfb8aa3b, v79
	v_exp_f32_e32 v82, v82
	v_exp_f32_e32 v83, v83
	v_or_b32_e32 v84, 48, v142
	v_add_f32_e32 v82, 1.0, v82
	v_add_f32_e32 v83, 1.0, v83
	v_rcp_f32_e32 v82, v82
	v_rcp_f32_e32 v83, v83
	s_nop 0
	v_pk_mul_f32 v[78:79], v[78:79], v[82:83]
	s_nop 0
	v_pk_mul_f32 v[74:75], v[78:79], v[74:75]
	s_nop 0
	v_cvt_pk_bf16_f32 v74, v74, v75
	v_mul_f32_e32 v75, 0xbfb8aa3b, v80
	v_exp_f32_e32 v75, v75
	s_nop 0
	v_add_f32_e32 v75, 1.0, v75
	v_rcp_f32_e32 v78, v75
	v_mul_f32_e32 v75, 0xbfb8aa3b, v81
	v_exp_f32_e32 v75, v75
	s_nop 0
	v_add_f32_e32 v75, 1.0, v75
	v_rcp_f32_e32 v79, v75
	s_nop 0
	v_pk_mul_f32 v[78:79], v[80:81], v[78:79]
	s_nop 0
	v_pk_mul_f32 v[76:77], v[78:79], v[76:77]
	s_nop 0
	v_cvt_pk_bf16_f32 v75, v76, v77
	v_mad_i64_i32 v[76:77], s[18:19], v84, s50, v[122:123]
	v_lshl_add_u64 v[76:77], v[76:77], 0, v[124:125]
	global_store_dwordx2 v[76:77], v[74:75], off
	v_mul_f32_e32 v74, 0xbfb8aa3b, v70
	v_mul_f32_e32 v75, 0xbfb8aa3b, v71
	v_exp_f32_e32 v74, v74
	v_exp_f32_e32 v75, v75
	v_add_f32_e32 v74, 1.0, v74
	v_add_f32_e32 v75, 1.0, v75
	v_rcp_f32_e32 v74, v74
	v_rcp_f32_e32 v75, v75
	s_nop 0
	v_pk_mul_f32 v[70:71], v[70:71], v[74:75]
	s_nop 0
	v_pk_mul_f32 v[66:67], v[70:71], v[66:67]
	s_nop 0
	v_cvt_pk_bf16_f32 v66, v66, v67
	v_mul_f32_e32 v67, 0xbfb8aa3b, v72
	v_exp_f32_e32 v67, v67
	s_nop 0
	v_add_f32_e32 v67, 1.0, v67
	v_rcp_f32_e32 v70, v67
	v_mul_f32_e32 v67, 0xbfb8aa3b, v73
	v_exp_f32_e32 v67, v67
	s_nop 0
	v_add_f32_e32 v67, 1.0, v67
	v_rcp_f32_e32 v71, v67
	s_nop 0
	v_pk_mul_f32 v[70:71], v[72:73], v[70:71]
	s_nop 0
	v_pk_mul_f32 v[68:69], v[70:71], v[68:69]
	s_nop 0
	v_cvt_pk_bf16_f32 v67, v68, v69
	global_store_dwordx2 v[76:77], v[66:67], off offset:32
	v_mul_f32_e32 v66, 0xbfb8aa3b, v62
	v_mul_f32_e32 v67, 0xbfb8aa3b, v63
	v_exp_f32_e32 v66, v66
	v_exp_f32_e32 v67, v67
	v_add_u32_e32 v68, 0x80, v142
	v_add_f32_e32 v66, 1.0, v66
	v_add_f32_e32 v67, 1.0, v67
	v_rcp_f32_e32 v66, v66
	v_rcp_f32_e32 v67, v67
	s_nop 0
	v_pk_mul_f32 v[62:63], v[62:63], v[66:67]
	s_nop 0
	v_pk_mul_f32 v[58:59], v[62:63], v[58:59]
	s_nop 0
	v_cvt_pk_bf16_f32 v58, v58, v59
	v_mul_f32_e32 v59, 0xbfb8aa3b, v64
	v_exp_f32_e32 v59, v59
	s_nop 0
	v_add_f32_e32 v59, 1.0, v59
	v_rcp_f32_e32 v62, v59
	v_mul_f32_e32 v59, 0xbfb8aa3b, v65
	v_exp_f32_e32 v59, v59
	s_nop 0
	v_add_f32_e32 v59, 1.0, v59
	v_rcp_f32_e32 v63, v59
	s_nop 0
	v_pk_mul_f32 v[62:63], v[64:65], v[62:63]
	s_nop 0
	v_pk_mul_f32 v[60:61], v[62:63], v[60:61]
	s_nop 0
	v_cvt_pk_bf16_f32 v59, v60, v61
	v_mad_i64_i32 v[60:61], s[18:19], v68, s50, v[122:123]
	v_lshl_add_u64 v[60:61], v[60:61], 0, v[124:125]
	global_store_dwordx2 v[60:61], v[58:59], off
	v_mul_f32_e32 v58, 0xbfb8aa3b, v54
; __device__ __forceinline__ float silu_f(float x) { return x * sigm(x); }
; #define PG8_WAIT_V(n) asm volatile("s_waitcnt vmcnt(" #n ")" ::: "memory")
; #define PG8_BAR __builtin_amdgcn_s_barrier()
;   __device__ __forceinline__ int kt(const Unit& u) const { return ((u.pn & 7) < 4) ? 4 : 16; }
; template <class Epi, class Sched>
; __device__ __forceinline__ void gemm_phase(PG8_LAS unsigned char* lds, const int lda, const int ldb, const Sched& S, const Epi& E) {
;     ...
;     E(acc, cur, wr, wc, fr, fq);
;     if (!has_next) break;
; #pragma unroll
;     for (int a = 0; a < 2; ++a)
; #pragma unroll
;       for (int b = 0; b < 2; ++b)
; #pragma unroll
;         for (int m = 0; m < 4; ++m)
; #pragma unroll
;           for (int n = 0; n < 2; ++n) acc[a][b][m][n] = (f32x4){0.f, 0.f, 0.f, 0.f};
;     cur = nxt; cA = nA; cB = nB; ++ui;
;     nt = S.kt(cur);
;   }
;   PG8_WAIT_V(0);
;   if (wr == 0) PG8_BAR;
;   PG8_BAR;
;   __device__ __forceinline__ void operator()(const f32x4 (&acc)[2][2][4][2], const Unit& u, int wr, int wc, int fr, int fq) const {
;     ...
;         const int r = u.pm * 256 + ai * 128 + wr * 64 + m * 16 + fr;
; #pragma unroll
;         for (int n = 0; n < 2; ++n) {
;           const f32x4 g = acc[ai][0][m][n], up = acc[ai][1][m][n];
;           const int c = u.pn * 128 + wc * 32 + n * 16 + 4 * fq;
;           uint2 w;
;           w.x = pack2(silu_f(g[0]) * up[0], silu_f(g[1]) * up[1]);
;           w.y = pack2(silu_f(g[2]) * up[2], silu_f(g[3]) * up[3]);
;           *reinterpret_cast<uint2*>(HID + (size_t)r * DFF + c) = w;
	v_mul_f32_e32 v59, 0xbfb8aa3b, v55
	v_exp_f32_e32 v58, v58
	v_exp_f32_e32 v59, v59
	v_add_f32_e32 v58, 1.0, v58
	v_add_f32_e32 v59, 1.0, v59
	v_rcp_f32_e32 v58, v58
	v_rcp_f32_e32 v59, v59
	s_nop 0
	v_pk_mul_f32 v[54:55], v[54:55], v[58:59]
	s_nop 0
	v_pk_mul_f32 v[50:51], v[54:55], v[50:51]
	s_nop 0
	v_cvt_pk_bf16_f32 v50, v50, v51
	v_mul_f32_e32 v51, 0xbfb8aa3b, v56
	v_exp_f32_e32 v51, v51
	s_nop 0
	v_add_f32_e32 v51, 1.0, v51
	v_rcp_f32_e32 v54, v51
	v_mul_f32_e32 v51, 0xbfb8aa3b, v57
	v_exp_f32_e32 v51, v51
	s_nop 0
	v_add_f32_e32 v51, 1.0, v51
	v_rcp_f32_e32 v55, v51
	s_nop 0
	v_pk_mul_f32 v[54:55], v[56:57], v[54:55]
	s_nop 0
	v_pk_mul_f32 v[52:53], v[54:55], v[52:53]
	s_nop 0
	v_cvt_pk_bf16_f32 v51, v52, v53
	global_store_dwordx2 v[60:61], v[50:51], off offset:32
	v_mul_f32_e32 v50, 0xbfb8aa3b, v46
	v_mul_f32_e32 v51, 0xbfb8aa3b, v47
	v_exp_f32_e32 v50, v50
	v_exp_f32_e32 v51, v51
	v_add_u32_e32 v52, 0x90, v142
	v_add_f32_e32 v50, 1.0, v50
	v_add_f32_e32 v51, 1.0, v51
	v_rcp_f32_e32 v50, v50
	v_rcp_f32_e32 v51, v51
	s_nop 0
	v_pk_mul_f32 v[46:47], v[46:47], v[50:51]
	s_nop 0
	v_pk_mul_f32 v[42:43], v[46:47], v[42:43]
	s_nop 0
	v_cvt_pk_bf16_f32 v42, v42, v43
	v_mul_f32_e32 v43, 0xbfb8aa3b, v48
	v_exp_f32_e32 v43, v43
	s_nop 0
	v_add_f32_e32 v43, 1.0, v43
	v_rcp_f32_e32 v46, v43
	v_mul_f32_e32 v43, 0xbfb8aa3b, v49
	v_exp_f32_e32 v43, v43
	s_nop 0
	v_add_f32_e32 v43, 1.0, v43
	v_rcp_f32_e32 v47, v43
	s_nop 0
	v_pk_mul_f32 v[46:47], v[48:49], v[46:47]
	s_nop 0
	v_pk_mul_f32 v[44:45], v[46:47], v[44:45]
	s_nop 0
	v_cvt_pk_bf16_f32 v43, v44, v45
	v_mad_i64_i32 v[44:45], s[18:19], v52, s50, v[122:123]
	v_lshl_add_u64 v[44:45], v[44:45], 0, v[124:125]
	global_store_dwordx2 v[44:45], v[42:43], off
	v_mul_f32_e32 v42, 0xbfb8aa3b, v38
	v_mul_f32_e32 v43, 0xbfb8aa3b, v39
	v_exp_f32_e32 v42, v42
	v_exp_f32_e32 v43, v43
	v_add_f32_e32 v42, 1.0, v42
	v_add_f32_e32 v43, 1.0, v43
	v_rcp_f32_e32 v42, v42
	v_rcp_f32_e32 v43, v43
	s_nop 0
	v_pk_mul_f32 v[38:39], v[38:39], v[42:43]
	s_nop 0
	v_pk_mul_f32 v[34:35], v[38:39], v[34:35]
	s_nop 0
	v_cvt_pk_bf16_f32 v34, v34, v35
	v_mul_f32_e32 v35, 0xbfb8aa3b, v40
	v_exp_f32_e32 v35, v35
	s_nop 0
	v_add_f32_e32 v35, 1.0, v35
	v_rcp_f32_e32 v38, v35
	v_mul_f32_e32 v35, 0xbfb8aa3b, v41
	v_exp_f32_e32 v35, v35
	s_nop 0
	v_add_f32_e32 v35, 1.0, v35
	v_rcp_f32_e32 v39, v35
	s_nop 0
	v_pk_mul_f32 v[38:39], v[40:41], v[38:39]
	s_nop 0
	v_pk_mul_f32 v[36:37], v[38:39], v[36:37]
	s_nop 0
	v_cvt_pk_bf16_f32 v35, v36, v37
	global_store_dwordx2 v[44:45], v[34:35], off offset:32
	v_mul_f32_e32 v34, 0xbfb8aa3b, v30
	v_mul_f32_e32 v35, 0xbfb8aa3b, v31
	v_exp_f32_e32 v34, v34
	v_exp_f32_e32 v35, v35
	v_add_u32_e32 v36, 0xa0, v142
	v_add_f32_e32 v34, 1.0, v34
	v_add_f32_e32 v35, 1.0, v35
	v_rcp_f32_e32 v34, v34
	v_rcp_f32_e32 v35, v35
	s_nop 0
	v_pk_mul_f32 v[30:31], v[30:31], v[34:35]
	s_nop 0
	v_pk_mul_f32 v[26:27], v[30:31], v[26:27]
	s_nop 0
	v_cvt_pk_bf16_f32 v26, v26, v27
	v_mul_f32_e32 v27, 0xbfb8aa3b, v32
	v_exp_f32_e32 v27, v27
	s_nop 0
	v_add_f32_e32 v27, 1.0, v27
	v_rcp_f32_e32 v30, v27
	v_mul_f32_e32 v27, 0xbfb8aa3b, v33
	v_exp_f32_e32 v27, v27
	s_nop 0
	v_add_f32_e32 v27, 1.0, v27
	v_rcp_f32_e32 v31, v27
	s_nop 0
	v_pk_mul_f32 v[30:31], v[32:33], v[30:31]
	s_nop 0
	v_pk_mul_f32 v[28:29], v[30:31], v[28:29]
	s_nop 0
	v_cvt_pk_bf16_f32 v27, v28, v29
	v_mad_i64_i32 v[28:29], s[18:19], v36, s50, v[122:123]
	v_lshl_add_u64 v[28:29], v[28:29], 0, v[124:125]
	global_store_dwordx2 v[28:29], v[26:27], off
	v_mul_f32_e32 v26, 0xbfb8aa3b, v22
	v_mul_f32_e32 v27, 0xbfb8aa3b, v23
	v_exp_f32_e32 v26, v26
	v_exp_f32_e32 v27, v27
	v_add_f32_e32 v26, 1.0, v26
	v_add_f32_e32 v27, 1.0, v27
	v_rcp_f32_e32 v26, v26
	v_rcp_f32_e32 v27, v27
	s_nop 0
	v_pk_mul_f32 v[22:23], v[22:23], v[26:27]
	s_nop 0
	v_pk_mul_f32 v[18:19], v[22:23], v[18:19]
	s_nop 0
	v_cvt_pk_bf16_f32 v18, v18, v19
	v_mul_f32_e32 v19, 0xbfb8aa3b, v24
	v_exp_f32_e32 v19, v19
	s_nop 0
	v_add_f32_e32 v19, 1.0, v19
	v_rcp_f32_e32 v22, v19
	v_mul_f32_e32 v19, 0xbfb8aa3b, v25
	v_exp_f32_e32 v19, v19
	s_nop 0
	v_add_f32_e32 v19, 1.0, v19
	v_rcp_f32_e32 v23, v19
	s_nop 0
	v_pk_mul_f32 v[22:23], v[24:25], v[22:23]
	s_nop 0
	v_pk_mul_f32 v[20:21], v[22:23], v[20:21]
	s_nop 0
	v_cvt_pk_bf16_f32 v19, v20, v21
	global_store_dwordx2 v[28:29], v[18:19], off offset:32
	v_mul_f32_e32 v18, 0xbfb8aa3b, v14
	v_mul_f32_e32 v19, 0xbfb8aa3b, v15
	v_exp_f32_e32 v18, v18
	v_exp_f32_e32 v19, v19
	v_add_u32_e32 v20, 0xb0, v142
	v_add_f32_e32 v18, 1.0, v18
	v_add_f32_e32 v19, 1.0, v19
	v_rcp_f32_e32 v18, v18
	v_rcp_f32_e32 v19, v19
	s_nop 0
	v_pk_mul_f32 v[14:15], v[14:15], v[18:19]
	s_nop 0
	v_pk_mul_f32 v[10:11], v[14:15], v[10:11]
	s_nop 0
	v_cvt_pk_bf16_f32 v10, v10, v11
	v_mul_f32_e32 v11, 0xbfb8aa3b, v16
	v_exp_f32_e32 v11, v11
	s_nop 0
	v_add_f32_e32 v11, 1.0, v11
	v_rcp_f32_e32 v14, v11
	v_mul_f32_e32 v11, 0xbfb8aa3b, v17
	v_exp_f32_e32 v11, v11
	s_nop 0
	v_add_f32_e32 v11, 1.0, v11
	v_rcp_f32_e32 v15, v11
	s_nop 0
	v_pk_mul_f32 v[14:15], v[16:17], v[14:15]
	s_nop 0
	v_pk_mul_f32 v[12:13], v[14:15], v[12:13]
	s_nop 0
	v_cvt_pk_bf16_f32 v11, v12, v13
	v_mad_i64_i32 v[12:13], s[18:19], v20, s50, v[122:123]
	v_lshl_add_u64 v[12:13], v[12:13], 0, v[124:125]
	global_store_dwordx2 v[12:13], v[10:11], off
	v_mul_f32_e32 v10, 0xbfb8aa3b, v6
	v_mul_f32_e32 v11, 0xbfb8aa3b, v7
	v_exp_f32_e32 v10, v10
	v_exp_f32_e32 v11, v11
	s_mov_b64 s[18:19], s[12:13]
	v_add_f32_e32 v10, 1.0, v10
	v_add_f32_e32 v11, 1.0, v11
	v_rcp_f32_e32 v10, v10
	v_rcp_f32_e32 v11, v11
	s_nop 0
	v_pk_mul_f32 v[6:7], v[6:7], v[10:11]
	s_nop 0
	v_pk_mul_f32 v[2:3], v[6:7], v[2:3]
	s_nop 0
	v_cvt_pk_bf16_f32 v2, v2, v3
	v_mul_f32_e32 v3, 0xbfb8aa3b, v8
	v_exp_f32_e32 v3, v3
	s_nop 0
	v_add_f32_e32 v3, 1.0, v3
	v_rcp_f32_e32 v6, v3
	v_mul_f32_e32 v3, 0xbfb8aa3b, v9
	v_exp_f32_e32 v3, v3
	s_nop 0
	v_add_f32_e32 v3, 1.0, v3
	v_rcp_f32_e32 v7, v3
	s_nop 0
	v_pk_mul_f32 v[6:7], v[8:9], v[6:7]
	s_nop 0
	v_pk_mul_f32 v[4:5], v[6:7], v[4:5]
	s_nop 0
	v_cvt_pk_bf16_f32 v3, v4, v5
	global_store_dwordx2 v[12:13], v[2:3], off offset:32
	s_cbranch_vccz .LBB0_1601
	s_waitcnt vmcnt(0)
	v_readlane_b32 s40, v253, 12
	s_cmpk_gt_u32 s9, 0xff
	v_readlane_b32 s41, v253, 13
	v_readlane_b32 s44, v253, 16
	v_readlane_b32 s45, v253, 17
	v_readlane_b32 s52, v253, 24
	v_readlane_b32 s53, v253, 25
	v_readlane_b32 s54, v253, 26
	v_readlane_b32 s55, v253, 27
	v_readlane_b32 s38, v255, 23
	v_readlane_b32 s42, v253, 14
	v_readlane_b32 s43, v253, 15
	v_readlane_b32 s46, v253, 18
	v_readlane_b32 s47, v253, 19
	v_readlane_b32 s48, v253, 20
	v_readlane_b32 s49, v253, 21
	v_readlane_b32 s50, v253, 22
	v_readlane_b32 s51, v253, 23
	v_readlane_b32 s39, v255, 24
	s_cbranch_scc1 .LBB0_1608
	s_barrier

; #define PG8_STAGE(bufoff, gbase, voff) do { _Pragma("unroll") for (int _i = 0; _i < 2; ++_i) \
;     __builtin_amdgcn_global_load_lds((const unsigned*)((const char*)(gbase) + (voff)[_i]), (PG8_LAS unsigned*)(lds + (bufoff) + ldsw + _i * 8192), 16, 0, 0); } while (0)
; #define PG8_LDA(dst, b, h) do { _Pragma("unroll") for (int m = 0; m < 4; ++m) _Pragma("unroll") for (int k = 0; k < 2; ++k) dst[m][k] = *(const PG8_LAS bf16x8*)(lds + PG8_SA(b, h) + aoff + m * 2048 + k * 1024); } while (0)
; #define PG8_LDB(dst, b, h) do { _Pragma("unroll") for (int n = 0; n < 2; ++n) _Pragma("unroll") for (int k = 0; k < 2; ++k) dst[n][k] = *(const PG8_LAS bf16x8*)(lds + PG8_SB(b, h) + boff + n * 2048 + k * 1024); } while (0)
; #define PG8_MMA(ai, bj, At, Bt) do { __builtin_amdgcn_s_setprio(1); _Pragma("unroll") for (int m = 0; m < 4; ++m) _Pragma("unroll") for (int n = 0; n < 2; ++n) _Pragma("unroll") for (int k = 0; k < 2; ++k) \
;     acc[ai][bj][m][n] = __builtin_amdgcn_mfma_f32_16x16x32_bf16(Bt[n][k], At[m][k], acc[ai][bj][m][n], 0, 0, 0); __builtin_amdgcn_s_setprio(0); } while (0)
; #define PG8_WAIT_L(n) asm volatile("s_waitcnt lgkmcnt(" #n ")" ::: "memory")
; #define PG8_BAR __builtin_amdgcn_s_barrier()
; #define PG8_SCHED __builtin_amdgcn_sched_barrier(0)
; template <class Epi, class Sched>
; __device__ __forceinline__ void gemm_phase(PG8_LAS unsigned char* lds, const int lda, const int ldb, const Sched& S, const Epi& E) {
;     ...
;     for (int t = 0; t < nt; t += 2) {
;       const bool last = (t == nt - 2);
;       const char* a1 = cA + (size_t)(t + 1) * kstep;
;       const char* a2 = last ? nA : cA + (size_t)(t + 2) * kstep; const char* b2 = last ? nB : cB + (size_t)(t + 2) * kstep;
;       const char* a3 = a2 + kstep; const char* b3 = b2 + kstep;
;       PG8_LDB(B0, 0, 0); PG8_SCHED; PG8_LDA(At, 0, 0); PG8_STAGE(PG8_SA(1, 1), a1 + hstepA, voffA);
;       PG8_WAIT_L(8); PG8_BAR; PG8_WAIT_L(0); PG8_MMA(0, 0, At, B0); PG8_BAR; PG8_SCHED;
;       PG8_LDB(B1, 0, 1); PG8_STAGE(PG8_SB(0, 0), b2, voffB);
;       PG8_BAR; PG8_WAIT_L(0); PG8_MMA(0, 1, At, B1); PG8_BAR;
;       PG8_LDA(At, 0, 1); PG8_STAGE(PG8_SA(0, 0), a2, voffA);
;       PG8_BAR; PG8_WAIT_L(0); PG8_MMA(1, 0, At, B0); PG8_BAR; PG8_SCHED;
.LBB0_1673:
	s_add_u32 s12, s10, 0x100
	s_addc_u32 s13, s11, 0
	s_add_i32 s33, 0, 0x10000
	v_add_u32_e32 v154, s33, v131
	ds_read_b128 v[140:143], v154
	ds_read_b128 v[146:149], v154 offset:1024
	ds_read_b128 v[150:153], v154 offset:2048
	ds_read_b128 v[154:157], v154 offset:3072
	s_cmp_eq_u32 s41, 40
	s_cselect_b32 s17, s7, s13
	s_cselect_b32 s16, s6, s12
	s_cselect_b32 s15, s1, s40
	s_cselect_b32 s14, s0, s39
	v_lshl_add_u64 v[174:175], s[10:11], 0, v[136:137]
	s_add_i32 m0, s23, 0xc000
	ds_read_b128 v[158:161], v145
	ds_read_b128 v[162:165], v145 offset:1024
	ds_read_b128 v[166:169], v145 offset:2048
	ds_read_b128 v[170:173], v145 offset:3072
	ds_read_b128 v[200:203], v145 offset:4096
	ds_read_b128 v[204:207], v145 offset:5120
	ds_read_b128 v[208:211], v145 offset:6144
	ds_read_b128 v[212:215], v145 offset:7168
	global_load_lds_dwordx4 v[174:175], off
	v_lshl_add_u64 v[174:175], s[10:11], 0, v[138:139]
	s_add_i32 m0, s23, 0xe000
	s_nop 0
	global_load_lds_dwordx4 v[174:175], off
	s_waitcnt lgkmcnt(8)
	s_barrier
	s_waitcnt lgkmcnt(0)
	v_mfma_f32_16x16x32_bf16 v[126:129], v[140:143], v[158:161], v[126:129]
	v_mfma_f32_16x16x32_bf16 v[122:125], v[150:153], v[158:161], v[122:125]
	v_mfma_f32_16x16x32_bf16 v[110:113], v[140:143], v[166:169], v[110:113]
	v_mfma_f32_16x16x32_bf16 v[106:109], v[150:153], v[166:169], v[106:109]
	v_mfma_f32_16x16x32_bf16 v[94:97], v[140:143], v[200:203], v[94:97]
	v_mfma_f32_16x16x32_bf16 v[90:93], v[150:153], v[200:203], v[90:93]
	v_mfma_f32_16x16x32_bf16 v[78:81], v[140:143], v[208:211], v[78:81]
	v_mfma_f32_16x16x32_bf16 v[74:77], v[150:153], v[208:211], v[74:77]
	v_mfma_f32_16x16x32_bf16 v[126:129], v[146:149], v[162:165], v[126:129]
	v_mfma_f32_16x16x32_bf16 v[122:125], v[154:157], v[162:165], v[122:125]
	v_mfma_f32_16x16x32_bf16 v[110:113], v[146:149], v[170:173], v[110:113]
	v_mfma_f32_16x16x32_bf16 v[106:109], v[154:157], v[170:173], v[106:109]
	v_mfma_f32_16x16x32_bf16 v[94:97], v[146:149], v[204:207], v[94:97]
	v_mfma_f32_16x16x32_bf16 v[90:93], v[154:157], v[204:207], v[90:93]
	v_mfma_f32_16x16x32_bf16 v[78:81], v[146:149], v[212:215], v[78:81]
	v_mfma_f32_16x16x32_bf16 v[74:77], v[154:157], v[212:215], v[74:77]
	s_barrier
	s_add_i32 s42, 0, 0x14000
	v_add_u32_e32 v174, s42, v131
	s_add_i32 s10, s33, s20
	ds_read_b128 v[216:219], v174
	ds_read_b128 v[220:223], v174 offset:1024
	ds_read_b128 v[224:227], v174 offset:2048
	ds_read_b128 v[228:231], v174 offset:3072
	v_lshl_add_u64 v[174:175], s[14:15], 0, v[134:135]
	s_mov_b32 m0, s10
	v_lshl_add_u64 v[182:183], s[14:15], 0, v[132:133]
	global_load_lds_dwordx4 v[174:175], off
	s_add_i32 m0, s10, 0x2000
	s_nop 0
	global_load_lds_dwordx4 v[182:183], off
	s_barrier
	s_waitcnt lgkmcnt(0)
	v_mfma_f32_16x16x32_bf16 v[118:121], v[216:219], v[158:161], v[118:121]
	v_mfma_f32_16x16x32_bf16 v[114:117], v[224:227], v[158:161], v[114:117]
	v_mfma_f32_16x16x32_bf16 v[102:105], v[216:219], v[166:169], v[102:105]
	v_mfma_f32_16x16x32_bf16 v[98:101], v[224:227], v[166:169], v[98:101]
	v_mfma_f32_16x16x32_bf16 v[86:89], v[216:219], v[200:203], v[86:89]
	v_mfma_f32_16x16x32_bf16 v[82:85], v[224:227], v[200:203], v[82:85]
	v_mfma_f32_16x16x32_bf16 v[70:73], v[216:219], v[208:211], v[70:73]
	v_mfma_f32_16x16x32_bf16 v[66:69], v[224:227], v[208:211], v[66:69]
	v_mfma_f32_16x16x32_bf16 v[118:121], v[220:223], v[162:165], v[118:121]
	v_mfma_f32_16x16x32_bf16 v[114:117], v[228:231], v[162:165], v[114:117]
	v_mfma_f32_16x16x32_bf16 v[102:105], v[220:223], v[170:173], v[102:105]
	v_mfma_f32_16x16x32_bf16 v[98:101], v[228:231], v[170:173], v[98:101]
	v_mfma_f32_16x16x32_bf16 v[86:89], v[220:223], v[204:207], v[86:89]
	v_mfma_f32_16x16x32_bf16 v[82:85], v[228:231], v[204:207], v[82:85]
	v_mfma_f32_16x16x32_bf16 v[70:73], v[220:223], v[212:215], v[70:73]
	v_mfma_f32_16x16x32_bf16 v[66:69], v[228:231], v[212:215], v[66:69]
	s_barrier
	s_mov_b32 m0, s23
	v_lshl_add_u64 v[184:185], s[16:17], 0, v[134:135]
	ds_read_b128 v[158:161], v145 offset:16384
	ds_read_b128 v[162:165], v145 offset:17408
	ds_read_b128 v[166:169], v145 offset:18432
	ds_read_b128 v[170:173], v145 offset:19456
	ds_read_b128 v[200:203], v145 offset:20480
	ds_read_b128 v[204:207], v145 offset:21504
	ds_read_b128 v[208:211], v145 offset:22528
	ds_read_b128 v[212:215], v145 offset:23552
	global_load_lds_dwordx4 v[184:185], off
	v_lshl_add_u64 v[232:233], s[16:17], 0, v[132:133]
	s_mov_b32 m0, s24
	s_nop 0
	global_load_lds_dwordx4 v[232:233], off
	s_barrier
	s_waitcnt lgkmcnt(0)
	v_mfma_f32_16x16x32_bf16 v[62:65], v[140:143], v[158:161], v[62:65]
	v_mfma_f32_16x16x32_bf16 v[58:61], v[150:153], v[158:161], v[58:61]
	v_mfma_f32_16x16x32_bf16 v[46:49], v[140:143], v[166:169], v[46:49]
	v_mfma_f32_16x16x32_bf16 v[42:45], v[150:153], v[166:169], v[42:45]
	v_mfma_f32_16x16x32_bf16 v[30:33], v[140:143], v[200:203], v[30:33]
	v_mfma_f32_16x16x32_bf16 v[26:29], v[150:153], v[200:203], v[26:29]
	v_mfma_f32_16x16x32_bf16 v[14:17], v[140:143], v[208:211], v[14:17]
	v_mfma_f32_16x16x32_bf16 v[10:13], v[150:153], v[208:211], v[10:13]
	v_mfma_f32_16x16x32_bf16 v[62:65], v[146:149], v[162:165], v[62:65]
	v_mfma_f32_16x16x32_bf16 v[58:61], v[154:157], v[162:165], v[58:61]
	v_mfma_f32_16x16x32_bf16 v[46:49], v[146:149], v[170:173], v[46:49]
	v_mfma_f32_16x16x32_bf16 v[42:45], v[154:157], v[170:173], v[42:45]
	v_mfma_f32_16x16x32_bf16 v[30:33], v[146:149], v[204:207], v[30:33]
	v_mfma_f32_16x16x32_bf16 v[26:29], v[154:157], v[204:207], v[26:29]
	v_mfma_f32_16x16x32_bf16 v[14:17], v[146:149], v[212:215], v[14:17]
	v_mfma_f32_16x16x32_bf16 v[10:13], v[154:157], v[212:215], v[10:13]
	s_barrier
; #define PG8_STAGE(bufoff, gbase, voff) do { _Pragma("unroll") for (int _i = 0; _i < 2; ++_i) \
;     __builtin_amdgcn_global_load_lds((const unsigned*)((const char*)(gbase) + (voff)[_i]), (PG8_LAS unsigned*)(lds + (bufoff) + ldsw + _i * 8192), 16, 0, 0); } while (0)
; #define PG8_LDA(dst, b, h) do { _Pragma("unroll") for (int m = 0; m < 4; ++m) _Pragma("unroll") for (int k = 0; k < 2; ++k) dst[m][k] = *(const PG8_LAS bf16x8*)(lds + PG8_SA(b, h) + aoff + m * 2048 + k * 1024); } while (0)
; #define PG8_LDB(dst, b, h) do { _Pragma("unroll") for (int n = 0; n < 2; ++n) _Pragma("unroll") for (int k = 0; k < 2; ++k) dst[n][k] = *(const PG8_LAS bf16x8*)(lds + PG8_SB(b, h) + boff + n * 2048 + k * 1024); } while (0)
; #define PG8_MMA(ai, bj, At, Bt) do { __builtin_amdgcn_s_setprio(1); _Pragma("unroll") for (int m = 0; m < 4; ++m) _Pragma("unroll") for (int n = 0; n < 2; ++n) _Pragma("unroll") for (int k = 0; k < 2; ++k) \
;     acc[ai][bj][m][n] = __builtin_amdgcn_mfma_f32_16x16x32_bf16(Bt[n][k], At[m][k], acc[ai][bj][m][n], 0, 0, 0); __builtin_amdgcn_s_setprio(0); } while (0)
; #define PG8_WAIT_V(n) asm volatile("s_waitcnt vmcnt(" #n ")" ::: "memory")
; #define PG8_WAIT_L(n) asm volatile("s_waitcnt lgkmcnt(" #n ")" ::: "memory")
; #define PG8_BAR __builtin_amdgcn_s_barrier()
; #define PG8_SCHED __builtin_amdgcn_sched_barrier(0)
; template <class Epi, class Sched>
; __device__ __forceinline__ void gemm_phase(PG8_LAS unsigned char* lds, const int lda, const int ldb, const Sched& S, const Epi& E) {
;     ...
;       PG8_STAGE(PG8_SB(0, 1), b2 + hstepB, voffB);
;       PG8_WAIT_V(6); PG8_BAR; PG8_MMA(1, 1, At, B1); PG8_BAR;
;       PG8_LDB(B0, 1, 0); PG8_SCHED; PG8_LDA(At, 1, 0); PG8_STAGE(PG8_SA(0, 1), a2 + hstepA, voffA);
;       PG8_WAIT_L(8); PG8_BAR; PG8_WAIT_L(0); PG8_MMA(0, 0, At, B0); PG8_BAR; PG8_SCHED;
;       PG8_LDB(B1, 1, 1); PG8_STAGE(PG8_SB(1, 0), b3, voffB);
;       PG8_BAR; PG8_WAIT_L(0); PG8_MMA(0, 1, At, B1); PG8_BAR;
;       PG8_LDA(At, 1, 1); PG8_STAGE(PG8_SA(1, 0), a3, voffA);
	s_add_u32 s10, s14, 0xb0000
	s_addc_u32 s11, s15, 0
	s_add_i32 s33, s42, s20
	v_lshl_add_u64 v[140:141], s[10:11], 0, v[134:135]
	s_mov_b32 m0, s33
	s_nop 0
	global_load_lds_dwordx4 v[140:141], off
	v_lshl_add_u64 v[140:141], s[10:11], 0, v[132:133]
	s_add_i32 m0, s33, 0x2000
	s_nop 0
	global_load_lds_dwordx4 v[140:141], off
	s_waitcnt vmcnt(6)
	s_barrier
	v_mfma_f32_16x16x32_bf16 v[54:57], v[216:219], v[158:161], v[54:57]
	v_mfma_f32_16x16x32_bf16 v[50:53], v[224:227], v[158:161], v[50:53]
	v_mfma_f32_16x16x32_bf16 v[38:41], v[216:219], v[166:169], v[38:41]
	v_mfma_f32_16x16x32_bf16 v[34:37], v[224:227], v[166:169], v[34:37]
	v_mfma_f32_16x16x32_bf16 v[22:25], v[216:219], v[200:203], v[22:25]
	v_mfma_f32_16x16x32_bf16 v[18:21], v[224:227], v[200:203], v[18:21]
	v_mfma_f32_16x16x32_bf16 v[6:9], v[216:219], v[208:211], v[6:9]
	v_mfma_f32_16x16x32_bf16 v[2:5], v[224:227], v[208:211], v[2:5]
	v_mfma_f32_16x16x32_bf16 v[54:57], v[220:223], v[162:165], v[54:57]
	v_mfma_f32_16x16x32_bf16 v[50:53], v[228:231], v[162:165], v[50:53]
	v_mfma_f32_16x16x32_bf16 v[38:41], v[220:223], v[170:173], v[38:41]
	v_mfma_f32_16x16x32_bf16 v[34:37], v[228:231], v[170:173], v[34:37]
	v_mfma_f32_16x16x32_bf16 v[22:25], v[220:223], v[204:207], v[22:25]
	v_mfma_f32_16x16x32_bf16 v[18:21], v[228:231], v[204:207], v[18:21]
	v_mfma_f32_16x16x32_bf16 v[6:9], v[220:223], v[212:215], v[6:9]
	v_mfma_f32_16x16x32_bf16 v[2:5], v[228:231], v[212:215], v[2:5]
	s_barrier
	s_add_i32 s33, 0, 0x18000
	v_add_u32_e32 v154, s33, v131
	ds_read_b128 v[140:143], v154
	ds_read_b128 v[146:149], v154 offset:1024
	ds_read_b128 v[150:153], v154 offset:2048
	ds_read_b128 v[154:157], v154 offset:3072
	s_add_u32 s10, s16, 0xb0000
	s_addc_u32 s11, s17, 0
	s_mov_b32 m0, s25
	v_lshl_add_u64 v[216:217], s[10:11], 0, v[134:135]
	ds_read_b128 v[158:161], v145 offset:32768
	ds_read_b128 v[162:165], v145 offset:33792
	ds_read_b128 v[166:169], v145 offset:34816
	ds_read_b128 v[170:173], v145 offset:35840
	ds_read_b128 v[200:203], v145 offset:36864
	ds_read_b128 v[204:207], v145 offset:37888
	ds_read_b128 v[208:211], v145 offset:38912
	ds_read_b128 v[212:215], v145 offset:39936
	global_load_lds_dwordx4 v[216:217], off
	v_lshl_add_u64 v[216:217], s[10:11], 0, v[132:133]
	s_mov_b32 m0, s26
	s_nop 0
	global_load_lds_dwordx4 v[216:217], off
	s_waitcnt lgkmcnt(8)
	s_barrier
	s_waitcnt lgkmcnt(0)
	v_mfma_f32_16x16x32_bf16 v[126:129], v[140:143], v[158:161], v[126:129]
	v_mfma_f32_16x16x32_bf16 v[122:125], v[150:153], v[158:161], v[122:125]
	v_mfma_f32_16x16x32_bf16 v[110:113], v[140:143], v[166:169], v[110:113]
	v_mfma_f32_16x16x32_bf16 v[106:109], v[150:153], v[166:169], v[106:109]
	v_mfma_f32_16x16x32_bf16 v[94:97], v[140:143], v[200:203], v[94:97]
	v_mfma_f32_16x16x32_bf16 v[90:93], v[150:153], v[200:203], v[90:93]
	v_mfma_f32_16x16x32_bf16 v[78:81], v[140:143], v[208:211], v[78:81]
	v_mfma_f32_16x16x32_bf16 v[74:77], v[150:153], v[208:211], v[74:77]
	v_mfma_f32_16x16x32_bf16 v[126:129], v[146:149], v[162:165], v[126:129]
	v_mfma_f32_16x16x32_bf16 v[122:125], v[154:157], v[162:165], v[122:125]
	v_mfma_f32_16x16x32_bf16 v[110:113], v[146:149], v[170:173], v[110:113]
	v_mfma_f32_16x16x32_bf16 v[106:109], v[154:157], v[170:173], v[106:109]
	v_mfma_f32_16x16x32_bf16 v[94:97], v[146:149], v[204:207], v[94:97]
	v_mfma_f32_16x16x32_bf16 v[90:93], v[154:157], v[204:207], v[90:93]
	v_mfma_f32_16x16x32_bf16 v[78:81], v[146:149], v[212:215], v[78:81]
	v_mfma_f32_16x16x32_bf16 v[74:77], v[154:157], v[212:215], v[74:77]
	s_barrier
	s_add_i32 s16, 0, 0x1c000
	s_add_i32 s10, s33, s20
	v_add_u32_e32 v228, s16, v131
	v_lshl_add_u64 v[174:175], v[174:175], 0, s[86:87]
	s_mov_b32 m0, s10
	ds_read_b128 v[216:219], v228
	ds_read_b128 v[220:223], v228 offset:1024
	ds_read_b128 v[224:227], v228 offset:2048
	ds_read_b128 v[228:231], v228 offset:3072
	global_load_lds_dwordx4 v[174:175], off
	v_lshl_add_u64 v[174:175], v[182:183], 0, s[86:87]
	s_add_i32 m0, s10, 0x2000
	s_nop 0
	global_load_lds_dwordx4 v[174:175], off
	s_barrier
; #define PG8_STAGE(bufoff, gbase, voff) do { _Pragma("unroll") for (int _i = 0; _i < 2; ++_i) \
;     __builtin_amdgcn_global_load_lds((const unsigned*)((const char*)(gbase) + (voff)[_i]), (PG8_LAS unsigned*)(lds + (bufoff) + ldsw + _i * 8192), 16, 0, 0); } while (0)
; #define PG8_MMA(ai, bj, At, Bt) do { __builtin_amdgcn_s_setprio(1); _Pragma("unroll") for (int m = 0; m < 4; ++m) _Pragma("unroll") for (int n = 0; n < 2; ++n) _Pragma("unroll") for (int k = 0; k < 2; ++k) \
;     acc[ai][bj][m][n] = __builtin_amdgcn_mfma_f32_16x16x32_bf16(Bt[n][k], At[m][k], acc[ai][bj][m][n], 0, 0, 0); __builtin_amdgcn_s_setprio(0); } while (0)
; #define PG8_WAIT_V(n) asm volatile("s_waitcnt vmcnt(" #n ")" ::: "memory")
; #define PG8_WAIT_L(n) asm volatile("s_waitcnt lgkmcnt(" #n ")" ::: "memory")
; #define PG8_BAR __builtin_amdgcn_s_barrier()
; #define PG8_SCHED __builtin_amdgcn_sched_barrier(0)
; template <class Epi, class Sched>
; __device__ __forceinline__ void gemm_phase(PG8_LAS unsigned char* lds, const int lda, const int ldb, const Sched& S, const Epi& E) {
;     ...
;       PG8_BAR; PG8_WAIT_L(0); PG8_MMA(1, 0, At, B0); PG8_BAR; PG8_SCHED;
;       PG8_STAGE(PG8_SB(1, 1), b3 + hstepB, voffB);
;       PG8_WAIT_V(6); PG8_BAR; PG8_MMA(1, 1, At, B1); PG8_BAR;
;     }
;   __device__ __forceinline__ void operator()(const f32x4 (&acc)[2][2][4][2], const Unit& u, int wr, int wc, int fr, int fq) const {
;     const int mr = (u.pm * 256 < ML) ? ((u.pm * 256) >> 11) : 32;
;     const float* gp = mod + (size_t)mr * 6144 + gate_off;
	s_waitcnt lgkmcnt(0)
	v_mfma_f32_16x16x32_bf16 v[118:121], v[216:219], v[158:161], v[118:121]
	v_mfma_f32_16x16x32_bf16 v[114:117], v[224:227], v[158:161], v[114:117]
	v_mfma_f32_16x16x32_bf16 v[102:105], v[216:219], v[166:169], v[102:105]
	v_mfma_f32_16x16x32_bf16 v[98:101], v[224:227], v[166:169], v[98:101]
	v_mfma_f32_16x16x32_bf16 v[86:89], v[216:219], v[200:203], v[86:89]
	v_mfma_f32_16x16x32_bf16 v[82:85], v[224:227], v[200:203], v[82:85]
	v_mfma_f32_16x16x32_bf16 v[70:73], v[216:219], v[208:211], v[70:73]
	v_mfma_f32_16x16x32_bf16 v[66:69], v[224:227], v[208:211], v[66:69]
	v_mfma_f32_16x16x32_bf16 v[118:121], v[220:223], v[162:165], v[118:121]
	v_mfma_f32_16x16x32_bf16 v[114:117], v[228:231], v[162:165], v[114:117]
	v_mfma_f32_16x16x32_bf16 v[102:105], v[220:223], v[170:173], v[102:105]
	v_mfma_f32_16x16x32_bf16 v[98:101], v[228:231], v[170:173], v[98:101]
	v_mfma_f32_16x16x32_bf16 v[86:89], v[220:223], v[204:207], v[86:89]
	v_mfma_f32_16x16x32_bf16 v[82:85], v[228:231], v[204:207], v[82:85]
	v_mfma_f32_16x16x32_bf16 v[70:73], v[220:223], v[212:215], v[70:73]
	v_mfma_f32_16x16x32_bf16 v[66:69], v[228:231], v[212:215], v[66:69]
	s_barrier
	s_mov_b32 m0, s28
	v_lshl_add_u64 v[174:175], v[184:185], 0, s[86:87]
	ds_read_b128 v[158:161], v145 offset:49152
	ds_read_b128 v[162:165], v145 offset:50176
	ds_read_b128 v[166:169], v145 offset:51200
	ds_read_b128 v[170:173], v145 offset:52224
	ds_read_b128 v[200:203], v145 offset:53248
	ds_read_b128 v[204:207], v145 offset:54272
	ds_read_b128 v[208:211], v145 offset:55296
	ds_read_b128 v[212:215], v145 offset:56320
	global_load_lds_dwordx4 v[174:175], off
	v_lshl_add_u64 v[174:175], v[232:233], 0, s[86:87]
	s_mov_b32 m0, s29
	s_nop 0
	global_load_lds_dwordx4 v[174:175], off
	s_barrier
	s_waitcnt lgkmcnt(0)
	v_mfma_f32_16x16x32_bf16 v[62:65], v[140:143], v[158:161], v[62:65]
	v_mfma_f32_16x16x32_bf16 v[58:61], v[150:153], v[158:161], v[58:61]
	v_mfma_f32_16x16x32_bf16 v[46:49], v[140:143], v[166:169], v[46:49]
	v_mfma_f32_16x16x32_bf16 v[42:45], v[150:153], v[166:169], v[42:45]
	v_mfma_f32_16x16x32_bf16 v[30:33], v[140:143], v[200:203], v[30:33]
	v_mfma_f32_16x16x32_bf16 v[26:29], v[150:153], v[200:203], v[26:29]
	v_mfma_f32_16x16x32_bf16 v[14:17], v[140:143], v[208:211], v[14:17]
	v_mfma_f32_16x16x32_bf16 v[10:13], v[150:153], v[208:211], v[10:13]
	v_mfma_f32_16x16x32_bf16 v[62:65], v[146:149], v[162:165], v[62:65]
	v_mfma_f32_16x16x32_bf16 v[58:61], v[154:157], v[162:165], v[58:61]
	v_mfma_f32_16x16x32_bf16 v[46:49], v[146:149], v[170:173], v[46:49]
	v_mfma_f32_16x16x32_bf16 v[42:45], v[154:157], v[170:173], v[42:45]
	v_mfma_f32_16x16x32_bf16 v[30:33], v[146:149], v[204:207], v[30:33]
	v_mfma_f32_16x16x32_bf16 v[26:29], v[154:157], v[204:207], v[26:29]
	v_mfma_f32_16x16x32_bf16 v[14:17], v[146:149], v[212:215], v[14:17]
	v_mfma_f32_16x16x32_bf16 v[10:13], v[154:157], v[212:215], v[10:13]
	s_barrier
	s_add_u32 s10, s14, 0xb0080
	s_addc_u32 s11, s15, 0
	s_add_i32 s14, s16, s20
	v_lshl_add_u64 v[140:141], s[10:11], 0, v[134:135]
	s_mov_b32 m0, s14
	s_nop 0
	global_load_lds_dwordx4 v[140:141], off
	v_lshl_add_u64 v[140:141], s[10:11], 0, v[132:133]
	s_add_i32 m0, s14, 0x2000
	s_nop 0
	global_load_lds_dwordx4 v[140:141], off
	s_add_i32 s41, s41, 2
	s_add_u32 s39, s39, 0x100
	s_addc_u32 s40, s40, 0
	s_cmp_gt_u32 s41, 41
	s_mov_b64 s[10:11], s[12:13]
	s_waitcnt vmcnt(6)
	s_barrier
	v_mfma_f32_16x16x32_bf16 v[54:57], v[216:219], v[158:161], v[54:57]
	v_mfma_f32_16x16x32_bf16 v[50:53], v[224:227], v[158:161], v[50:53]
	v_mfma_f32_16x16x32_bf16 v[38:41], v[216:219], v[166:169], v[38:41]
	v_mfma_f32_16x16x32_bf16 v[34:37], v[224:227], v[166:169], v[34:37]
	v_mfma_f32_16x16x32_bf16 v[22:25], v[216:219], v[200:203], v[22:25]
	v_mfma_f32_16x16x32_bf16 v[18:21], v[224:227], v[200:203], v[18:21]
	v_mfma_f32_16x16x32_bf16 v[6:9], v[216:219], v[208:211], v[6:9]
	v_mfma_f32_16x16x32_bf16 v[2:5], v[224:227], v[208:211], v[2:5]
	v_mfma_f32_16x16x32_bf16 v[54:57], v[220:223], v[162:165], v[54:57]
	v_mfma_f32_16x16x32_bf16 v[50:53], v[228:231], v[162:165], v[50:53]
	v_mfma_f32_16x16x32_bf16 v[38:41], v[220:223], v[170:173], v[38:41]
	v_mfma_f32_16x16x32_bf16 v[34:37], v[228:231], v[170:173], v[34:37]
	v_mfma_f32_16x16x32_bf16 v[22:25], v[220:223], v[204:207], v[22:25]
	v_mfma_f32_16x16x32_bf16 v[18:21], v[228:231], v[204:207], v[18:21]
	v_mfma_f32_16x16x32_bf16 v[6:9], v[220:223], v[212:215], v[6:9]
	v_mfma_f32_16x16x32_bf16 v[2:5], v[228:231], v[212:215], v[2:5]
	s_barrier
	s_cbranch_scc0 .LBB0_1673
	s_cmpk_gt_i32 s37, 0xff
	s_mov_b64 s[10:11], 0x30000
	s_cbranch_scc1 .LBB0_1665
	s_ashr_i32 s10, s37, 3
	s_mul_hi_i32 s11, s10, 0x1800
	s_mulk_i32 s10, 0x1800
	s_branch .LBB0_1665
